# GEMM loops: the s_barrier that ends each MMA block moved ahead of the block's last MFMA (the partner half starts while the last MFMA is still in the pipe)
# speedup vs baseline: 1.0102x; 1.0049x over previous
; #define PG8_STAGE(bufoff, gbase, voff) do { _Pragma("unroll") for (int _i = 0; _i < 2; ++_i) \
;         __builtin_amdgcn_global_load_lds((const unsigned*)((const char*)(gbase) + (voff)[_i]), (PG8_LAS unsigned*)(lds + (bufoff) + ldsw + _i * 8192), 16, 0, 0); } while (0)
; #define PG8_LDA(dst, b, h) do { _Pragma("unroll") for (int m = 0; m < 4; ++m) _Pragma("unroll") for (int k = 0; k < 2; ++k) dst[m][k] = *(const PG8_LAS bf16x8*)(lds + PG8_SA(b, h) + aoff + m * 2048 + k * 1024); } while (0)
; #define PG8_LDB(dst, b, h) do { _Pragma("unroll") for (int n = 0; n < 2; ++n) _Pragma("unroll") for (int k = 0; k < 2; ++k) dst[n][k] = *(const PG8_LAS bf16x8*)(lds + PG8_SB(b, h) + boff + n * 2048 + k * 1024); } while (0)
; #define PG8_MMA(ai, bj, At, Bt) do { __builtin_amdgcn_s_setprio(1); _Pragma("unroll") for (int m = 0; m < 4; ++m) _Pragma("unroll") for (int n = 0; n < 2; ++n) _Pragma("unroll") for (int k = 0; k < 2; ++k) \
;         acc[ai][bj][m][n] = __builtin_amdgcn_mfma_f32_16x16x32_bf16(Bt[n][k], At[m][k], acc[ai][bj][m][n], 0, 0, 0); __builtin_amdgcn_s_setprio(0); } while (0)
; #define PG8_WAIT_V(n) asm volatile("s_waitcnt vmcnt(" #n ")" ::: "memory")
; #define PG8_WAIT_L(n) asm volatile("s_waitcnt lgkmcnt(" #n ")" ::: "memory")
; #define PG8_BAR __builtin_amdgcn_s_barrier()
; #define PG8_SCHED __builtin_amdgcn_sched_barrier(0)
; template <class Epi, class Sched, bool ALIGN_EPI = false, bool SP2 = false>
; __device__ __forceinline__ void gemm_phase(PG8_LAS unsigned char* lds, const Gemm g, const Sched& S, const Epi& E) {
;     ...
;             PG8_LDB(B0, 0, 0); PG8_LDB(B1, 0, 1); PG8_SCHED; PG8_LDA(At, 0, 0); PG8_STAGE(PG8_SA(1, 1), a1 + hstep, voffA);
;             PG8_WAIT_V(8); PG8_WAIT_L(0); PG8_BAR; PG8_MMA(0, 0, At, B0); PG8_MMA(0, 1, At, B1); PG8_BAR; PG8_SCHED;
;             PG8_LDA(At, 0, 1); PG8_STAGE(PG8_SB(0, 0), b2, voffB); PG8_STAGE(PG8_SB(0, 1), b2 + hstep, voffB); PG8_STAGE(PG8_SA(0, 0), a2, voffA);
.LBB0_143:
	ds_read_b128 v[144:147], v163
	ds_read_b128 v[168:171], v163 offset:1024
	ds_read_b128 v[172:175], v163 offset:2048
	ds_read_b128 v[176:179], v163 offset:3072
	ds_read_b128 v[180:183], v164
	ds_read_b128 v[184:187], v164 offset:1024
	ds_read_b128 v[188:191], v164 offset:2048
	ds_read_b128 v[192:195], v164 offset:3072
	s_add_u32 s40, s38, 0xfffc0080
	s_addc_u32 s41, s39, -1
	s_cmp_eq_u32 s85, 12
	s_cselect_b32 s43, s7, s41
	s_cselect_b32 s42, s29, s40
	s_cselect_b32 s41, s27, s84
	s_cselect_b32 s40, s82, s83
	v_lshl_add_u64 v[148:149], s[38:39], 0, v[136:137]
	s_add_i32 m0, s37, 0xc000
	ds_read_b128 v[196:199], v165
	ds_read_b128 v[200:203], v165 offset:1024
	ds_read_b128 v[204:207], v165 offset:2048
	ds_read_b128 v[210:213], v165 offset:3072
	ds_read_b128 v[214:217], v165 offset:4096
	ds_read_b128 v[218:221], v165 offset:5120
	ds_read_b128 v[222:225], v165 offset:6144
	ds_read_b128 v[226:229], v165 offset:7168
	global_load_lds_dwordx4 v[148:149], off
	v_lshl_add_u64 v[148:149], s[38:39], 0, v[138:139]
	s_add_i32 m0, s37, 0xe000
	s_nop 0
	global_load_lds_dwordx4 v[148:149], off
	s_waitcnt vmcnt(8)
	s_waitcnt lgkmcnt(0)
	s_barrier
	s_setprio 1
	s_waitcnt lgkmcnt(0)
	v_mfma_f32_16x16x32_bf16 v[124:127], v[144:147], v[196:199], v[124:127]
	v_mfma_f32_16x16x32_bf16 v[116:119], v[172:175], v[196:199], v[116:119]
	v_mfma_f32_16x16x32_bf16 v[108:111], v[144:147], v[204:207], v[108:111]
	v_mfma_f32_16x16x32_bf16 v[100:103], v[172:175], v[204:207], v[100:103]
	v_mfma_f32_16x16x32_bf16 v[92:95], v[144:147], v[214:217], v[92:95]
	v_mfma_f32_16x16x32_bf16 v[84:87], v[172:175], v[214:217], v[84:87]
	v_mfma_f32_16x16x32_bf16 v[76:79], v[144:147], v[222:225], v[76:79]
	v_mfma_f32_16x16x32_bf16 v[68:71], v[172:175], v[222:225], v[68:71]
	v_mfma_f32_16x16x32_bf16 v[124:127], v[168:171], v[200:203], v[124:127]
	v_mfma_f32_16x16x32_bf16 v[116:119], v[176:179], v[200:203], v[116:119]
	v_mfma_f32_16x16x32_bf16 v[108:111], v[168:171], v[210:213], v[108:111]
	v_mfma_f32_16x16x32_bf16 v[100:103], v[176:179], v[210:213], v[100:103]
	v_mfma_f32_16x16x32_bf16 v[92:95], v[168:171], v[218:221], v[92:95]
	v_mfma_f32_16x16x32_bf16 v[84:87], v[176:179], v[218:221], v[84:87]
	v_mfma_f32_16x16x32_bf16 v[76:79], v[168:171], v[226:229], v[76:79]
	v_mfma_f32_16x16x32_bf16 v[68:71], v[176:179], v[226:229], v[68:71]
	s_setprio 0
	s_setprio 1
	v_mfma_f32_16x16x32_bf16 v[120:123], v[180:183], v[196:199], v[120:123]
	v_mfma_f32_16x16x32_bf16 v[112:115], v[188:191], v[196:199], v[112:115]
	v_mfma_f32_16x16x32_bf16 v[104:107], v[180:183], v[204:207], v[104:107]
	v_mfma_f32_16x16x32_bf16 v[96:99], v[188:191], v[204:207], v[96:99]
	v_mfma_f32_16x16x32_bf16 v[88:91], v[180:183], v[214:217], v[88:91]
	v_mfma_f32_16x16x32_bf16 v[80:83], v[188:191], v[214:217], v[80:83]
	v_mfma_f32_16x16x32_bf16 v[72:75], v[180:183], v[222:225], v[72:75]
	v_mfma_f32_16x16x32_bf16 v[64:67], v[188:191], v[222:225], v[64:67]
	v_mfma_f32_16x16x32_bf16 v[120:123], v[184:187], v[200:203], v[120:123]
	v_mfma_f32_16x16x32_bf16 v[112:115], v[192:195], v[200:203], v[112:115]
	v_mfma_f32_16x16x32_bf16 v[104:107], v[184:187], v[210:213], v[104:107]
	v_mfma_f32_16x16x32_bf16 v[96:99], v[192:195], v[210:213], v[96:99]
	v_mfma_f32_16x16x32_bf16 v[88:91], v[184:187], v[218:221], v[88:91]
	v_mfma_f32_16x16x32_bf16 v[80:83], v[192:195], v[218:221], v[80:83]
	v_mfma_f32_16x16x32_bf16 v[72:75], v[184:187], v[226:229], v[72:75]
	s_barrier
	v_mfma_f32_16x16x32_bf16 v[64:67], v[192:195], v[226:229], v[64:67]
	s_setprio 0
	s_add_i32 s52, s77, s64
	v_lshl_add_u64 v[148:149], s[40:41], 0, v[130:131]
	s_mov_b32 m0, s52
	ds_read_b128 v[196:199], v165 offset:16384
	ds_read_b128 v[200:203], v165 offset:17408
	ds_read_b128 v[204:207], v165 offset:18432
	ds_read_b128 v[210:213], v165 offset:19456
	ds_read_b128 v[214:217], v165 offset:20480
	ds_read_b128 v[218:221], v165 offset:21504
	ds_read_b128 v[222:225], v165 offset:22528
	ds_read_b128 v[226:229], v165 offset:23552
	global_load_lds_dwordx4 v[148:149], off
	s_add_i32 m0, s52, 0x2000
	s_add_u32 s86, s40, 0x40000
	v_lshl_add_u64 v[230:231], s[40:41], 0, v[134:135]
	s_addc_u32 s87, s41, 0
	s_add_i32 s52, s79, s64
	global_load_lds_dwordx4 v[230:231], off
	v_lshl_add_u64 v[232:233], s[86:87], 0, v[130:131]
	s_mov_b32 m0, s52
	v_lshl_add_u64 v[234:235], s[42:43], 0, v[132:133]
	global_load_lds_dwordx4 v[232:233], off
	v_lshl_add_u64 v[232:233], s[86:87], 0, v[134:135]
	s_add_i32 m0, s52, 0x2000
	s_nop 0
	global_load_lds_dwordx4 v[232:233], off
	v_lshl_add_u64 v[232:233], s[42:43], 0, v[128:129]
	s_mov_b32 m0, s37
	s_nop 0
	global_load_lds_dwordx4 v[232:233], off
	s_mov_b32 m0, s65
	s_nop 0
	global_load_lds_dwordx4 v[234:235], off
	s_waitcnt vmcnt(8)
	s_waitcnt lgkmcnt(0)
	s_barrier
; #define PG8_STAGE(bufoff, gbase, voff) do { _Pragma("unroll") for (int _i = 0; _i < 2; ++_i) \
;         __builtin_amdgcn_global_load_lds((const unsigned*)((const char*)(gbase) + (voff)[_i]), (PG8_LAS unsigned*)(lds + (bufoff) + ldsw + _i * 8192), 16, 0, 0); } while (0)
; #define PG8_LDA(dst, b, h) do { _Pragma("unroll") for (int m = 0; m < 4; ++m) _Pragma("unroll") for (int k = 0; k < 2; ++k) dst[m][k] = *(const PG8_LAS bf16x8*)(lds + PG8_SA(b, h) + aoff + m * 2048 + k * 1024); } while (0)
; #define PG8_LDB(dst, b, h) do { _Pragma("unroll") for (int n = 0; n < 2; ++n) _Pragma("unroll") for (int k = 0; k < 2; ++k) dst[n][k] = *(const PG8_LAS bf16x8*)(lds + PG8_SB(b, h) + boff + n * 2048 + k * 1024); } while (0)
; #define PG8_MMA(ai, bj, At, Bt) do { __builtin_amdgcn_s_setprio(1); _Pragma("unroll") for (int m = 0; m < 4; ++m) _Pragma("unroll") for (int n = 0; n < 2; ++n) _Pragma("unroll") for (int k = 0; k < 2; ++k) \
;         acc[ai][bj][m][n] = __builtin_amdgcn_mfma_f32_16x16x32_bf16(Bt[n][k], At[m][k], acc[ai][bj][m][n], 0, 0, 0); __builtin_amdgcn_s_setprio(0); } while (0)
; #define PG8_WAIT_V(n) asm volatile("s_waitcnt vmcnt(" #n ")" ::: "memory")
; #define PG8_WAIT_L(n) asm volatile("s_waitcnt lgkmcnt(" #n ")" ::: "memory")
; #define PG8_BAR __builtin_amdgcn_s_barrier()
; #define PG8_SCHED __builtin_amdgcn_sched_barrier(0)
; template <class Epi, class Sched, bool ALIGN_EPI = false, bool SP2 = false>
; __device__ __forceinline__ void gemm_phase(PG8_LAS unsigned char* lds, const Gemm g, const Sched& S, const Epi& E) {
;     ...
;             PG8_WAIT_V(8); PG8_WAIT_L(0); PG8_BAR; PG8_MMA(1, 0, At, B0); PG8_MMA(1, 1, At, B1); PG8_BAR; PG8_SCHED;
;             PG8_LDB(B0, 1, 0); PG8_LDB(B1, 1, 1); PG8_SCHED; PG8_LDA(At, 1, 0); PG8_STAGE(PG8_SA(0, 1), a2 + hstep, voffA);
;             PG8_WAIT_V(8); PG8_WAIT_L(0); PG8_BAR; PG8_MMA(0, 0, At, B0); PG8_MMA(0, 1, At, B1); PG8_BAR; PG8_SCHED;
	s_setprio 1
	s_waitcnt lgkmcnt(0)
	v_mfma_f32_16x16x32_bf16 v[60:63], v[144:147], v[196:199], v[60:63]
	v_mfma_f32_16x16x32_bf16 v[52:55], v[172:175], v[196:199], v[52:55]
	v_mfma_f32_16x16x32_bf16 v[44:47], v[144:147], v[204:207], v[44:47]
	v_mfma_f32_16x16x32_bf16 v[36:39], v[172:175], v[204:207], v[36:39]
	v_mfma_f32_16x16x32_bf16 v[28:31], v[144:147], v[214:217], v[28:31]
	v_mfma_f32_16x16x32_bf16 v[20:23], v[172:175], v[214:217], v[20:23]
	v_mfma_f32_16x16x32_bf16 v[12:15], v[144:147], v[222:225], v[12:15]
	v_mfma_f32_16x16x32_bf16 v[4:7], v[172:175], v[222:225], v[4:7]
	v_mfma_f32_16x16x32_bf16 v[60:63], v[168:171], v[200:203], v[60:63]
	v_mfma_f32_16x16x32_bf16 v[52:55], v[176:179], v[200:203], v[52:55]
	v_mfma_f32_16x16x32_bf16 v[44:47], v[168:171], v[210:213], v[44:47]
	v_mfma_f32_16x16x32_bf16 v[36:39], v[176:179], v[210:213], v[36:39]
	v_mfma_f32_16x16x32_bf16 v[28:31], v[168:171], v[218:221], v[28:31]
	v_mfma_f32_16x16x32_bf16 v[20:23], v[176:179], v[218:221], v[20:23]
	v_mfma_f32_16x16x32_bf16 v[12:15], v[168:171], v[226:229], v[12:15]
	v_mfma_f32_16x16x32_bf16 v[4:7], v[176:179], v[226:229], v[4:7]
	s_setprio 0
	s_setprio 1
	v_mfma_f32_16x16x32_bf16 v[56:59], v[180:183], v[196:199], v[56:59]
	v_mfma_f32_16x16x32_bf16 v[48:51], v[188:191], v[196:199], v[48:51]
	v_mfma_f32_16x16x32_bf16 v[40:43], v[180:183], v[204:207], v[40:43]
	v_mfma_f32_16x16x32_bf16 v[32:35], v[188:191], v[204:207], v[32:35]
	v_mfma_f32_16x16x32_bf16 v[24:27], v[180:183], v[214:217], v[24:27]
	v_mfma_f32_16x16x32_bf16 v[16:19], v[188:191], v[214:217], v[16:19]
	v_mfma_f32_16x16x32_bf16 v[8:11], v[180:183], v[222:225], v[8:11]
	v_mfma_f32_16x16x32_bf16 v[0:3], v[188:191], v[222:225], v[0:3]
	v_mfma_f32_16x16x32_bf16 v[56:59], v[184:187], v[200:203], v[56:59]
	v_mfma_f32_16x16x32_bf16 v[48:51], v[192:195], v[200:203], v[48:51]
	v_mfma_f32_16x16x32_bf16 v[40:43], v[184:187], v[210:213], v[40:43]
	v_mfma_f32_16x16x32_bf16 v[32:35], v[192:195], v[210:213], v[32:35]
	v_mfma_f32_16x16x32_bf16 v[24:27], v[184:187], v[218:221], v[24:27]
	v_mfma_f32_16x16x32_bf16 v[16:19], v[192:195], v[218:221], v[16:19]
	v_mfma_f32_16x16x32_bf16 v[8:11], v[184:187], v[226:229], v[8:11]
	s_barrier
	v_mfma_f32_16x16x32_bf16 v[0:3], v[192:195], v[226:229], v[0:3]
	s_setprio 0
	s_add_i32 s52, 0, 0x18000
	v_add_u32_e32 v150, s52, v161
	s_add_i32 s53, 0, 0x1c000
	ds_read_b128 v[144:147], v150
	ds_read_b128 v[168:171], v150 offset:1024
	ds_read_b128 v[172:175], v150 offset:2048
	ds_read_b128 v[176:179], v150 offset:3072
	v_add_u32_e32 v150, s53, v161
	ds_read_b128 v[180:183], v150
	ds_read_b128 v[184:187], v150 offset:1024
	ds_read_b128 v[188:191], v150 offset:2048
	ds_read_b128 v[192:195], v150 offset:3072
	s_add_u32 s42, s42, 0x40000
	s_addc_u32 s43, s43, 0
	s_mov_b32 m0, s66
	v_lshl_add_u64 v[236:237], s[42:43], 0, v[128:129]
	ds_read_b128 v[196:199], v165 offset:32768
	ds_read_b128 v[200:203], v165 offset:33792
	ds_read_b128 v[204:207], v165 offset:34816
	ds_read_b128 v[210:213], v165 offset:35840
	ds_read_b128 v[214:217], v165 offset:36864
	ds_read_b128 v[218:221], v165 offset:37888
	ds_read_b128 v[222:225], v165 offset:38912
	ds_read_b128 v[226:229], v165 offset:39936
	global_load_lds_dwordx4 v[236:237], off
	v_lshl_add_u64 v[236:237], s[42:43], 0, v[132:133]
	s_mov_b32 m0, s67
	s_nop 0
	global_load_lds_dwordx4 v[236:237], off
	s_waitcnt vmcnt(8)
	s_waitcnt lgkmcnt(0)
	s_barrier
	s_setprio 1
	s_waitcnt lgkmcnt(0)
	v_mfma_f32_16x16x32_bf16 v[124:127], v[144:147], v[196:199], v[124:127]
	v_mfma_f32_16x16x32_bf16 v[116:119], v[172:175], v[196:199], v[116:119]
	v_mfma_f32_16x16x32_bf16 v[108:111], v[144:147], v[204:207], v[108:111]
	v_mfma_f32_16x16x32_bf16 v[100:103], v[172:175], v[204:207], v[100:103]
	v_mfma_f32_16x16x32_bf16 v[92:95], v[144:147], v[214:217], v[92:95]
	v_mfma_f32_16x16x32_bf16 v[84:87], v[172:175], v[214:217], v[84:87]
	v_mfma_f32_16x16x32_bf16 v[76:79], v[144:147], v[222:225], v[76:79]
	v_mfma_f32_16x16x32_bf16 v[68:71], v[172:175], v[222:225], v[68:71]
	v_mfma_f32_16x16x32_bf16 v[124:127], v[168:171], v[200:203], v[124:127]
	v_mfma_f32_16x16x32_bf16 v[116:119], v[176:179], v[200:203], v[116:119]
	v_mfma_f32_16x16x32_bf16 v[108:111], v[168:171], v[210:213], v[108:111]
	v_mfma_f32_16x16x32_bf16 v[100:103], v[176:179], v[210:213], v[100:103]
	v_mfma_f32_16x16x32_bf16 v[92:95], v[168:171], v[218:221], v[92:95]
	v_mfma_f32_16x16x32_bf16 v[84:87], v[176:179], v[218:221], v[84:87]
	v_mfma_f32_16x16x32_bf16 v[76:79], v[168:171], v[226:229], v[76:79]
	v_mfma_f32_16x16x32_bf16 v[68:71], v[176:179], v[226:229], v[68:71]
	s_setprio 0
	s_setprio 1
	v_mfma_f32_16x16x32_bf16 v[120:123], v[180:183], v[196:199], v[120:123]
	v_mfma_f32_16x16x32_bf16 v[112:115], v[188:191], v[196:199], v[112:115]
	v_mfma_f32_16x16x32_bf16 v[104:107], v[180:183], v[204:207], v[104:107]
	v_mfma_f32_16x16x32_bf16 v[96:99], v[188:191], v[204:207], v[96:99]
	v_mfma_f32_16x16x32_bf16 v[88:91], v[180:183], v[214:217], v[88:91]
	v_mfma_f32_16x16x32_bf16 v[80:83], v[188:191], v[214:217], v[80:83]
	v_mfma_f32_16x16x32_bf16 v[72:75], v[180:183], v[222:225], v[72:75]
	v_mfma_f32_16x16x32_bf16 v[64:67], v[188:191], v[222:225], v[64:67]
	v_mfma_f32_16x16x32_bf16 v[120:123], v[184:187], v[200:203], v[120:123]
	v_mfma_f32_16x16x32_bf16 v[112:115], v[192:195], v[200:203], v[112:115]
	v_mfma_f32_16x16x32_bf16 v[104:107], v[184:187], v[210:213], v[104:107]
	v_mfma_f32_16x16x32_bf16 v[96:99], v[192:195], v[210:213], v[96:99]
	v_mfma_f32_16x16x32_bf16 v[88:91], v[184:187], v[218:221], v[88:91]
	v_mfma_f32_16x16x32_bf16 v[80:83], v[192:195], v[218:221], v[80:83]
	v_mfma_f32_16x16x32_bf16 v[72:75], v[184:187], v[226:229], v[72:75]
	s_barrier
; #define PG8_STAGE(bufoff, gbase, voff) do { _Pragma("unroll") for (int _i = 0; _i < 2; ++_i) \
;         __builtin_amdgcn_global_load_lds((const unsigned*)((const char*)(gbase) + (voff)[_i]), (PG8_LAS unsigned*)(lds + (bufoff) + ldsw + _i * 8192), 16, 0, 0); } while (0)
; #define PG8_LDA(dst, b, h) do { _Pragma("unroll") for (int m = 0; m < 4; ++m) _Pragma("unroll") for (int k = 0; k < 2; ++k) dst[m][k] = *(const PG8_LAS bf16x8*)(lds + PG8_SA(b, h) + aoff + m * 2048 + k * 1024); } while (0)
; #define PG8_MMA(ai, bj, At, Bt) do { __builtin_amdgcn_s_setprio(1); _Pragma("unroll") for (int m = 0; m < 4; ++m) _Pragma("unroll") for (int n = 0; n < 2; ++n) _Pragma("unroll") for (int k = 0; k < 2; ++k) \
;         acc[ai][bj][m][n] = __builtin_amdgcn_mfma_f32_16x16x32_bf16(Bt[n][k], At[m][k], acc[ai][bj][m][n], 0, 0, 0); __builtin_amdgcn_s_setprio(0); } while (0)
; #define PG8_WAIT_V(n) asm volatile("s_waitcnt vmcnt(" #n ")" ::: "memory")
; #define PG8_WAIT_L(n) asm volatile("s_waitcnt lgkmcnt(" #n ")" ::: "memory")
; #define PG8_BAR __builtin_amdgcn_s_barrier()
; #define PG8_SCHED __builtin_amdgcn_sched_barrier(0)
; __device__ __forceinline__ float row_rs(const float* ssq, int row) { return ssq ? rsqrtf(ssq[row] * (1.f / 1024.f) + RMS_EPS) : 1.f; }
; template <class Epi, class Sched, bool ALIGN_EPI = false, bool SP2 = false>
; __device__ __forceinline__ void gemm_phase(PG8_LAS unsigned char* lds, const Gemm g, const Sched& S, const Epi& E) {
;     ...
;             PG8_WAIT_V(8); PG8_WAIT_L(0); PG8_BAR; PG8_MMA(0, 0, At, B0); PG8_MMA(0, 1, At, B1); PG8_BAR; PG8_SCHED;
;             PG8_LDA(At, 1, 1); PG8_STAGE(PG8_SB(1, 0), b3, voffB); PG8_STAGE(PG8_SB(1, 1), b3 + hstep, voffB); PG8_STAGE(PG8_SA(1, 0), a3, voffA);
;             PG8_WAIT_V(8); PG8_WAIT_L(0); PG8_BAR; PG8_MMA(1, 0, At, B0); PG8_MMA(1, 1, At, B1); PG8_BAR; PG8_SCHED;
;     __device__ __forceinline__ void operator()(const f32x4 (&acc)[2][2][4][2], const Unit& u, int wr, int wc, int fr, int fq) const {
;     ...
;             for (int m = 0; m < 4; ++m) { const int row = row0 + ai * HALF + m * 16; const float rs = row_rs(ssq, row);
	v_mfma_f32_16x16x32_bf16 v[64:67], v[192:195], v[226:229], v[64:67]
	s_setprio 0
	s_add_i32 s42, s52, s64
	v_lshl_add_u64 v[148:149], v[148:149], 0, s[16:17]
	s_mov_b32 m0, s42
	ds_read_b128 v[196:199], v165 offset:49152
	ds_read_b128 v[200:203], v165 offset:50176
	ds_read_b128 v[204:207], v165 offset:51200
	ds_read_b128 v[210:213], v165 offset:52224
	ds_read_b128 v[214:217], v165 offset:53248
	ds_read_b128 v[218:221], v165 offset:54272
	ds_read_b128 v[222:225], v165 offset:55296
	ds_read_b128 v[226:229], v165 offset:56320
	global_load_lds_dwordx4 v[148:149], off
	s_add_i32 m0, s42, 0x2000
	s_add_u32 s40, s40, 0x40080
	v_lshl_add_u64 v[148:149], v[230:231], 0, s[16:17]
	s_addc_u32 s41, s41, 0
	s_add_i32 s42, s53, s64
	global_load_lds_dwordx4 v[148:149], off
	v_lshl_add_u64 v[148:149], s[40:41], 0, v[130:131]
	s_mov_b32 m0, s42
	s_nop 0
	global_load_lds_dwordx4 v[148:149], off
	v_lshl_add_u64 v[148:149], s[40:41], 0, v[134:135]
	s_add_i32 m0, s42, 0x2000
	s_nop 0
	global_load_lds_dwordx4 v[148:149], off
	v_lshl_add_u64 v[148:149], v[232:233], 0, s[16:17]
	s_mov_b32 m0, s74
	s_nop 0
	global_load_lds_dwordx4 v[148:149], off
	v_lshl_add_u64 v[148:149], v[234:235], 0, s[16:17]
	s_mov_b32 m0, s75
	s_nop 0
	global_load_lds_dwordx4 v[148:149], off
	s_waitcnt vmcnt(8)
	s_waitcnt lgkmcnt(0)
	s_barrier
	s_setprio 1
	s_waitcnt lgkmcnt(0)
	v_mfma_f32_16x16x32_bf16 v[60:63], v[144:147], v[196:199], v[60:63]
	v_mfma_f32_16x16x32_bf16 v[52:55], v[172:175], v[196:199], v[52:55]
	v_mfma_f32_16x16x32_bf16 v[44:47], v[144:147], v[204:207], v[44:47]
	v_mfma_f32_16x16x32_bf16 v[36:39], v[172:175], v[204:207], v[36:39]
	v_mfma_f32_16x16x32_bf16 v[28:31], v[144:147], v[214:217], v[28:31]
	v_mfma_f32_16x16x32_bf16 v[20:23], v[172:175], v[214:217], v[20:23]
	v_mfma_f32_16x16x32_bf16 v[12:15], v[144:147], v[222:225], v[12:15]
	v_mfma_f32_16x16x32_bf16 v[4:7], v[172:175], v[222:225], v[4:7]
	v_mfma_f32_16x16x32_bf16 v[60:63], v[168:171], v[200:203], v[60:63]
	v_mfma_f32_16x16x32_bf16 v[52:55], v[176:179], v[200:203], v[52:55]
	v_mfma_f32_16x16x32_bf16 v[44:47], v[168:171], v[210:213], v[44:47]
	v_mfma_f32_16x16x32_bf16 v[36:39], v[176:179], v[210:213], v[36:39]
	v_mfma_f32_16x16x32_bf16 v[28:31], v[168:171], v[218:221], v[28:31]
	v_mfma_f32_16x16x32_bf16 v[20:23], v[176:179], v[218:221], v[20:23]
	v_mfma_f32_16x16x32_bf16 v[12:15], v[168:171], v[226:229], v[12:15]
	v_mfma_f32_16x16x32_bf16 v[4:7], v[176:179], v[226:229], v[4:7]
	s_setprio 0
	s_setprio 1
	v_mfma_f32_16x16x32_bf16 v[56:59], v[180:183], v[196:199], v[56:59]
	v_mfma_f32_16x16x32_bf16 v[48:51], v[188:191], v[196:199], v[48:51]
	v_mfma_f32_16x16x32_bf16 v[40:43], v[180:183], v[204:207], v[40:43]
	v_mfma_f32_16x16x32_bf16 v[32:35], v[188:191], v[204:207], v[32:35]
	v_mfma_f32_16x16x32_bf16 v[24:27], v[180:183], v[214:217], v[24:27]
	v_mfma_f32_16x16x32_bf16 v[16:19], v[188:191], v[214:217], v[16:19]
	v_mfma_f32_16x16x32_bf16 v[8:11], v[180:183], v[222:225], v[8:11]
	v_mfma_f32_16x16x32_bf16 v[0:3], v[188:191], v[222:225], v[0:3]
	v_mfma_f32_16x16x32_bf16 v[56:59], v[184:187], v[200:203], v[56:59]
	v_mfma_f32_16x16x32_bf16 v[48:51], v[192:195], v[200:203], v[48:51]
	v_mfma_f32_16x16x32_bf16 v[40:43], v[184:187], v[210:213], v[40:43]
	v_mfma_f32_16x16x32_bf16 v[32:35], v[192:195], v[210:213], v[32:35]
	v_mfma_f32_16x16x32_bf16 v[24:27], v[184:187], v[218:221], v[24:27]
	v_mfma_f32_16x16x32_bf16 v[16:19], v[192:195], v[218:221], v[16:19]
	v_mfma_f32_16x16x32_bf16 v[8:11], v[184:187], v[226:229], v[8:11]
	s_barrier
	v_mfma_f32_16x16x32_bf16 v[0:3], v[192:195], v[226:229], v[0:3]
	s_setprio 0
	s_add_i32 s85, s85, 2
	s_add_u32 s38, s38, 0x100
	s_addc_u32 s39, s39, 0
	s_add_u32 s83, s83, 0x100
	s_addc_u32 s84, s84, 0
	s_cmp_gt_u32 s85, 13
	s_cbranch_scc0 .LBB0_143
	v_lshl_add_u32 v146, s6, 8, v160
	v_ashrrev_i32_e32 v147, 31, v146
	s_andn2_b64 vcc, exec, s[12:13]
	v_lshl_add_u64 v[148:149], v[146:147], 2, s[48:49]
	s_cbranch_vccnz .Lp1_rs_issued
	global_load_dword v172, v[148:149], off
	global_load_dword v173, v[148:149], off offset:64
	global_load_dword v174, v[148:149], off offset:128
	global_load_dword v175, v[148:149], off offset:192
	global_load_dword v176, v[148:149], off offset:512
	global_load_dword v177, v[148:149], off offset:576
	global_load_dword v178, v[148:149], off offset:640
	global_load_dword v179, v[148:149], off offset:704

; #define PG8_STAGE(bufoff, gbase, voff) do { _Pragma("unroll") for (int _i = 0; _i < 2; ++_i) \
;         __builtin_amdgcn_global_load_lds((const unsigned*)((const char*)(gbase) + (voff)[_i]), (PG8_LAS unsigned*)(lds + (bufoff) + ldsw + _i * 8192), 16, 0, 0); } while (0)
; #define PG8_LDA(dst, b, h) do { _Pragma("unroll") for (int m = 0; m < 4; ++m) _Pragma("unroll") for (int k = 0; k < 2; ++k) dst[m][k] = *(const PG8_LAS bf16x8*)(lds + PG8_SA(b, h) + aoff + m * 2048 + k * 1024); } while (0)
; #define PG8_LDB(dst, b, h) do { _Pragma("unroll") for (int n = 0; n < 2; ++n) _Pragma("unroll") for (int k = 0; k < 2; ++k) dst[n][k] = *(const PG8_LAS bf16x8*)(lds + PG8_SB(b, h) + boff + n * 2048 + k * 1024); } while (0)
; #define PG8_MMA(ai, bj, At, Bt) do { __builtin_amdgcn_s_setprio(1); _Pragma("unroll") for (int m = 0; m < 4; ++m) _Pragma("unroll") for (int n = 0; n < 2; ++n) _Pragma("unroll") for (int k = 0; k < 2; ++k) \
;         acc[ai][bj][m][n] = __builtin_amdgcn_mfma_f32_16x16x32_bf16(Bt[n][k], At[m][k], acc[ai][bj][m][n], 0, 0, 0); __builtin_amdgcn_s_setprio(0); } while (0)
; #define PG8_WAIT_V(n) asm volatile("s_waitcnt vmcnt(" #n ")" ::: "memory")
; #define PG8_WAIT_L(n) asm volatile("s_waitcnt lgkmcnt(" #n ")" ::: "memory")
; #define PG8_BAR __builtin_amdgcn_s_barrier()
; #define PG8_SCHED __builtin_amdgcn_sched_barrier(0)
; template <class Epi, class Sched, bool ALIGN_EPI = false, bool SP2 = false>
; __device__ __forceinline__ void gemm_phase(PG8_LAS unsigned char* lds, const Gemm g, const Sched& S, const Epi& E) {
;     ...
;             PG8_LDB(B0, 0, 0); PG8_LDB(B1, 0, 1); PG8_SCHED; PG8_LDA(At, 0, 0); PG8_STAGE(PG8_SA(1, 1), a1 + hstep, voffA);
;             PG8_WAIT_V(8); PG8_WAIT_L(0); PG8_BAR; PG8_MMA(0, 0, At, B0); PG8_MMA(0, 1, At, B1); PG8_BAR; PG8_SCHED;
;             PG8_LDA(At, 0, 1); PG8_STAGE(PG8_SB(0, 0), b2, voffB); PG8_STAGE(PG8_SB(0, 1), b2 + hstep, voffB); PG8_STAGE(PG8_SA(0, 0), a2, voffA);
.LBB0_183:
	ds_read_b128 v[146:149], v143
	ds_read_b128 v[160:163], v143 offset:1024
	ds_read_b128 v[164:167], v143 offset:2048
	ds_read_b128 v[168:171], v143 offset:3072
	ds_read_b128 v[172:175], v144
	ds_read_b128 v[176:179], v144 offset:1024
	ds_read_b128 v[180:183], v144 offset:2048
	ds_read_b128 v[184:187], v144 offset:3072
	s_add_u32 s52, s42, 0xfffc0080
	s_addc_u32 s53, s43, -1
	s_cmp_eq_u32 vcc_lo, 12
	s_cselect_b32 s65, s37, s53
	s_cselect_b32 s64, s94, s52
	s_cselect_b32 s63, s35, s97
	s_cselect_b32 s62, s95, s96
	v_lshl_add_u64 v[222:223], s[42:43], 0, v[136:137]
	s_add_i32 m0, s31, 0xc000
	ds_read_b128 v[188:191], v145
	ds_read_b128 v[192:195], v145 offset:1024
	ds_read_b128 v[196:199], v145 offset:2048
	ds_read_b128 v[200:203], v145 offset:3072
	ds_read_b128 v[204:207], v145 offset:4096
	ds_read_b128 v[210:213], v145 offset:5120
	ds_read_b128 v[214:217], v145 offset:6144
	ds_read_b128 v[218:221], v145 offset:7168
	global_load_lds_dwordx4 v[222:223], off
	v_lshl_add_u64 v[222:223], s[42:43], 0, v[138:139]
	s_add_i32 m0, s31, 0xe000
	s_nop 0
	global_load_lds_dwordx4 v[222:223], off
	s_waitcnt vmcnt(8)
	s_waitcnt lgkmcnt(0)
	s_barrier
	s_setprio 1
	s_waitcnt lgkmcnt(0)
	v_mfma_f32_16x16x32_bf16 v[124:127], v[146:149], v[188:191], v[124:127]
	v_mfma_f32_16x16x32_bf16 v[120:123], v[164:167], v[188:191], v[120:123]
	v_mfma_f32_16x16x32_bf16 v[116:119], v[146:149], v[196:199], v[116:119]
	v_mfma_f32_16x16x32_bf16 v[112:115], v[164:167], v[196:199], v[112:115]
	v_mfma_f32_16x16x32_bf16 v[100:103], v[146:149], v[204:207], v[100:103]
	v_mfma_f32_16x16x32_bf16 v[96:99], v[164:167], v[204:207], v[96:99]
	v_mfma_f32_16x16x32_bf16 v[84:87], v[146:149], v[214:217], v[84:87]
	v_mfma_f32_16x16x32_bf16 v[80:83], v[164:167], v[214:217], v[80:83]
	v_mfma_f32_16x16x32_bf16 v[124:127], v[160:163], v[192:195], v[124:127]
	v_mfma_f32_16x16x32_bf16 v[120:123], v[168:171], v[192:195], v[120:123]
	v_mfma_f32_16x16x32_bf16 v[116:119], v[160:163], v[200:203], v[116:119]
	v_mfma_f32_16x16x32_bf16 v[112:115], v[168:171], v[200:203], v[112:115]
	v_mfma_f32_16x16x32_bf16 v[100:103], v[160:163], v[210:213], v[100:103]
	v_mfma_f32_16x16x32_bf16 v[96:99], v[168:171], v[210:213], v[96:99]
	v_mfma_f32_16x16x32_bf16 v[84:87], v[160:163], v[218:221], v[84:87]
	v_mfma_f32_16x16x32_bf16 v[80:83], v[168:171], v[218:221], v[80:83]
	s_setprio 0
	s_setprio 1
	v_mfma_f32_16x16x32_bf16 v[108:111], v[172:175], v[188:191], v[108:111]
	v_mfma_f32_16x16x32_bf16 v[104:107], v[180:183], v[188:191], v[104:107]
	v_mfma_f32_16x16x32_bf16 v[92:95], v[172:175], v[196:199], v[92:95]
	v_mfma_f32_16x16x32_bf16 v[88:91], v[180:183], v[196:199], v[88:91]
	v_mfma_f32_16x16x32_bf16 v[76:79], v[172:175], v[204:207], v[76:79]
	v_mfma_f32_16x16x32_bf16 v[72:75], v[180:183], v[204:207], v[72:75]
	v_mfma_f32_16x16x32_bf16 v[68:71], v[172:175], v[214:217], v[68:71]
	v_mfma_f32_16x16x32_bf16 v[64:67], v[180:183], v[214:217], v[64:67]
	v_mfma_f32_16x16x32_bf16 v[108:111], v[176:179], v[192:195], v[108:111]
	v_mfma_f32_16x16x32_bf16 v[104:107], v[184:187], v[192:195], v[104:107]
	v_mfma_f32_16x16x32_bf16 v[92:95], v[176:179], v[200:203], v[92:95]
	v_mfma_f32_16x16x32_bf16 v[88:91], v[184:187], v[200:203], v[88:91]
	v_mfma_f32_16x16x32_bf16 v[76:79], v[176:179], v[210:213], v[76:79]
	v_mfma_f32_16x16x32_bf16 v[72:75], v[184:187], v[210:213], v[72:75]
	v_mfma_f32_16x16x32_bf16 v[68:71], v[176:179], v[218:221], v[68:71]
	s_barrier
	v_mfma_f32_16x16x32_bf16 v[64:67], v[184:187], v[218:221], v[64:67]
	s_setprio 0
	s_add_i32 s52, s87, s77
	v_lshl_add_u64 v[222:223], s[62:63], 0, v[130:131]
	s_mov_b32 m0, s52
	ds_read_b128 v[188:191], v145 offset:16384
	ds_read_b128 v[192:195], v145 offset:17408
	ds_read_b128 v[196:199], v145 offset:18432
	ds_read_b128 v[200:203], v145 offset:19456
	ds_read_b128 v[204:207], v145 offset:20480
	ds_read_b128 v[210:213], v145 offset:21504
	ds_read_b128 v[214:217], v145 offset:22528
	ds_read_b128 v[218:221], v145 offset:23552
	global_load_lds_dwordx4 v[222:223], off
	s_add_i32 m0, s52, 0x2000
	s_add_u32 s52, s62, 0x40000
	v_lshl_add_u64 v[224:225], s[62:63], 0, v[134:135]
	s_addc_u32 s53, s63, 0
	s_add_i32 vcc_hi, s88, s77
	global_load_lds_dwordx4 v[224:225], off
	v_lshl_add_u64 v[226:227], s[52:53], 0, v[130:131]
	s_mov_b32 m0, vcc_hi
	v_lshl_add_u64 v[228:229], s[64:65], 0, v[132:133]
	global_load_lds_dwordx4 v[226:227], off
	v_lshl_add_u64 v[226:227], s[52:53], 0, v[134:135]
	s_add_i32 m0, vcc_hi, 0x2000
	s_nop 0
	global_load_lds_dwordx4 v[226:227], off
	v_lshl_add_u64 v[226:227], s[64:65], 0, v[128:129]
	s_mov_b32 m0, s31
	s_nop 0
	global_load_lds_dwordx4 v[226:227], off
	s_mov_b32 m0, s81
	s_nop 0
	global_load_lds_dwordx4 v[228:229], off
	s_waitcnt vmcnt(8)
	s_waitcnt lgkmcnt(0)
	s_barrier
; #define PG8_STAGE(bufoff, gbase, voff) do { _Pragma("unroll") for (int _i = 0; _i < 2; ++_i) \
;         __builtin_amdgcn_global_load_lds((const unsigned*)((const char*)(gbase) + (voff)[_i]), (PG8_LAS unsigned*)(lds + (bufoff) + ldsw + _i * 8192), 16, 0, 0); } while (0)
; #define PG8_LDA(dst, b, h) do { _Pragma("unroll") for (int m = 0; m < 4; ++m) _Pragma("unroll") for (int k = 0; k < 2; ++k) dst[m][k] = *(const PG8_LAS bf16x8*)(lds + PG8_SA(b, h) + aoff + m * 2048 + k * 1024); } while (0)
; #define PG8_LDB(dst, b, h) do { _Pragma("unroll") for (int n = 0; n < 2; ++n) _Pragma("unroll") for (int k = 0; k < 2; ++k) dst[n][k] = *(const PG8_LAS bf16x8*)(lds + PG8_SB(b, h) + boff + n * 2048 + k * 1024); } while (0)
; #define PG8_MMA(ai, bj, At, Bt) do { __builtin_amdgcn_s_setprio(1); _Pragma("unroll") for (int m = 0; m < 4; ++m) _Pragma("unroll") for (int n = 0; n < 2; ++n) _Pragma("unroll") for (int k = 0; k < 2; ++k) \
;         acc[ai][bj][m][n] = __builtin_amdgcn_mfma_f32_16x16x32_bf16(Bt[n][k], At[m][k], acc[ai][bj][m][n], 0, 0, 0); __builtin_amdgcn_s_setprio(0); } while (0)
; #define PG8_WAIT_V(n) asm volatile("s_waitcnt vmcnt(" #n ")" ::: "memory")
; #define PG8_WAIT_L(n) asm volatile("s_waitcnt lgkmcnt(" #n ")" ::: "memory")
; #define PG8_BAR __builtin_amdgcn_s_barrier()
; #define PG8_SCHED __builtin_amdgcn_sched_barrier(0)
; template <class Epi, class Sched, bool ALIGN_EPI = false, bool SP2 = false>
; __device__ __forceinline__ void gemm_phase(PG8_LAS unsigned char* lds, const Gemm g, const Sched& S, const Epi& E) {
;     ...
;             PG8_WAIT_V(8); PG8_WAIT_L(0); PG8_BAR; PG8_MMA(1, 0, At, B0); PG8_MMA(1, 1, At, B1); PG8_BAR; PG8_SCHED;
;             PG8_LDB(B0, 1, 0); PG8_LDB(B1, 1, 1); PG8_SCHED; PG8_LDA(At, 1, 0); PG8_STAGE(PG8_SA(0, 1), a2 + hstep, voffA);
;             PG8_WAIT_V(8); PG8_WAIT_L(0); PG8_BAR; PG8_MMA(0, 0, At, B0); PG8_MMA(0, 1, At, B1); PG8_BAR; PG8_SCHED;
	s_setprio 1
	s_waitcnt lgkmcnt(0)
	v_mfma_f32_16x16x32_bf16 v[60:63], v[146:149], v[188:191], v[60:63]
	v_mfma_f32_16x16x32_bf16 v[56:59], v[164:167], v[188:191], v[56:59]
	v_mfma_f32_16x16x32_bf16 v[52:55], v[146:149], v[196:199], v[52:55]
	v_mfma_f32_16x16x32_bf16 v[48:51], v[164:167], v[196:199], v[48:51]
	v_mfma_f32_16x16x32_bf16 v[36:39], v[146:149], v[204:207], v[36:39]
	v_mfma_f32_16x16x32_bf16 v[32:35], v[164:167], v[204:207], v[32:35]
	v_mfma_f32_16x16x32_bf16 v[20:23], v[146:149], v[214:217], v[20:23]
	v_mfma_f32_16x16x32_bf16 v[16:19], v[164:167], v[214:217], v[16:19]
	v_mfma_f32_16x16x32_bf16 v[60:63], v[160:163], v[192:195], v[60:63]
	v_mfma_f32_16x16x32_bf16 v[56:59], v[168:171], v[192:195], v[56:59]
	v_mfma_f32_16x16x32_bf16 v[52:55], v[160:163], v[200:203], v[52:55]
	v_mfma_f32_16x16x32_bf16 v[48:51], v[168:171], v[200:203], v[48:51]
	v_mfma_f32_16x16x32_bf16 v[36:39], v[160:163], v[210:213], v[36:39]
	v_mfma_f32_16x16x32_bf16 v[32:35], v[168:171], v[210:213], v[32:35]
	v_mfma_f32_16x16x32_bf16 v[20:23], v[160:163], v[218:221], v[20:23]
	v_mfma_f32_16x16x32_bf16 v[16:19], v[168:171], v[218:221], v[16:19]
	s_setprio 0
	s_setprio 1
	v_mfma_f32_16x16x32_bf16 v[44:47], v[172:175], v[188:191], v[44:47]
	v_mfma_f32_16x16x32_bf16 v[40:43], v[180:183], v[188:191], v[40:43]
	v_mfma_f32_16x16x32_bf16 v[28:31], v[172:175], v[196:199], v[28:31]
	v_mfma_f32_16x16x32_bf16 v[24:27], v[180:183], v[196:199], v[24:27]
	v_mfma_f32_16x16x32_bf16 v[12:15], v[172:175], v[204:207], v[12:15]
	v_mfma_f32_16x16x32_bf16 v[8:11], v[180:183], v[204:207], v[8:11]
	v_mfma_f32_16x16x32_bf16 v[4:7], v[172:175], v[214:217], v[4:7]
	v_mfma_f32_16x16x32_bf16 v[0:3], v[180:183], v[214:217], v[0:3]
	v_mfma_f32_16x16x32_bf16 v[44:47], v[176:179], v[192:195], v[44:47]
	v_mfma_f32_16x16x32_bf16 v[40:43], v[184:187], v[192:195], v[40:43]
	v_mfma_f32_16x16x32_bf16 v[28:31], v[176:179], v[200:203], v[28:31]
	v_mfma_f32_16x16x32_bf16 v[24:27], v[184:187], v[200:203], v[24:27]
	v_mfma_f32_16x16x32_bf16 v[12:15], v[176:179], v[210:213], v[12:15]
	v_mfma_f32_16x16x32_bf16 v[8:11], v[184:187], v[210:213], v[8:11]
	v_mfma_f32_16x16x32_bf16 v[4:7], v[176:179], v[218:221], v[4:7]
	s_barrier
	v_mfma_f32_16x16x32_bf16 v[0:3], v[184:187], v[218:221], v[0:3]
	s_setprio 0
	s_add_i32 vcc_hi, 0, 0x18000
	v_add_u32_e32 v150, vcc_hi, v141
	s_add_i32 s78, 0, 0x1c000
	ds_read_b128 v[146:149], v150
	ds_read_b128 v[160:163], v150 offset:1024
	ds_read_b128 v[164:167], v150 offset:2048
	ds_read_b128 v[168:171], v150 offset:3072
	v_add_u32_e32 v150, s78, v141
	ds_read_b128 v[172:175], v150
	ds_read_b128 v[176:179], v150 offset:1024
	ds_read_b128 v[180:183], v150 offset:2048
	ds_read_b128 v[184:187], v150 offset:3072
	s_add_u32 s52, s64, 0x40000
	s_addc_u32 s53, s65, 0
	s_mov_b32 m0, s82
	v_lshl_add_u64 v[230:231], s[52:53], 0, v[128:129]
	ds_read_b128 v[188:191], v145 offset:32768
	ds_read_b128 v[192:195], v145 offset:33792
	ds_read_b128 v[196:199], v145 offset:34816
	ds_read_b128 v[200:203], v145 offset:35840
	ds_read_b128 v[204:207], v145 offset:36864
	ds_read_b128 v[210:213], v145 offset:37888
	ds_read_b128 v[214:217], v145 offset:38912
	ds_read_b128 v[218:221], v145 offset:39936
	global_load_lds_dwordx4 v[230:231], off
	v_lshl_add_u64 v[230:231], s[52:53], 0, v[132:133]
	s_mov_b32 m0, s83
	s_nop 0
	global_load_lds_dwordx4 v[230:231], off
	s_waitcnt vmcnt(8)
	s_waitcnt lgkmcnt(0)
	s_barrier
	s_setprio 1
	s_waitcnt lgkmcnt(0)
	v_mfma_f32_16x16x32_bf16 v[124:127], v[146:149], v[188:191], v[124:127]
	v_mfma_f32_16x16x32_bf16 v[120:123], v[164:167], v[188:191], v[120:123]
	v_mfma_f32_16x16x32_bf16 v[116:119], v[146:149], v[196:199], v[116:119]
	v_mfma_f32_16x16x32_bf16 v[112:115], v[164:167], v[196:199], v[112:115]
	v_mfma_f32_16x16x32_bf16 v[100:103], v[146:149], v[204:207], v[100:103]
	v_mfma_f32_16x16x32_bf16 v[96:99], v[164:167], v[204:207], v[96:99]
	v_mfma_f32_16x16x32_bf16 v[84:87], v[146:149], v[214:217], v[84:87]
	v_mfma_f32_16x16x32_bf16 v[80:83], v[164:167], v[214:217], v[80:83]
	v_mfma_f32_16x16x32_bf16 v[124:127], v[160:163], v[192:195], v[124:127]
	v_mfma_f32_16x16x32_bf16 v[120:123], v[168:171], v[192:195], v[120:123]
	v_mfma_f32_16x16x32_bf16 v[116:119], v[160:163], v[200:203], v[116:119]
	v_mfma_f32_16x16x32_bf16 v[112:115], v[168:171], v[200:203], v[112:115]
	v_mfma_f32_16x16x32_bf16 v[100:103], v[160:163], v[210:213], v[100:103]
	v_mfma_f32_16x16x32_bf16 v[96:99], v[168:171], v[210:213], v[96:99]
	v_mfma_f32_16x16x32_bf16 v[84:87], v[160:163], v[218:221], v[84:87]
	v_mfma_f32_16x16x32_bf16 v[80:83], v[168:171], v[218:221], v[80:83]
	s_setprio 0
	s_setprio 1
	v_mfma_f32_16x16x32_bf16 v[108:111], v[172:175], v[188:191], v[108:111]
	v_mfma_f32_16x16x32_bf16 v[104:107], v[180:183], v[188:191], v[104:107]
	v_mfma_f32_16x16x32_bf16 v[92:95], v[172:175], v[196:199], v[92:95]
	v_mfma_f32_16x16x32_bf16 v[88:91], v[180:183], v[196:199], v[88:91]
	v_mfma_f32_16x16x32_bf16 v[76:79], v[172:175], v[204:207], v[76:79]
	v_mfma_f32_16x16x32_bf16 v[72:75], v[180:183], v[204:207], v[72:75]
	v_mfma_f32_16x16x32_bf16 v[68:71], v[172:175], v[214:217], v[68:71]
	v_mfma_f32_16x16x32_bf16 v[64:67], v[180:183], v[214:217], v[64:67]
	v_mfma_f32_16x16x32_bf16 v[108:111], v[176:179], v[192:195], v[108:111]
	v_mfma_f32_16x16x32_bf16 v[104:107], v[184:187], v[192:195], v[104:107]
	v_mfma_f32_16x16x32_bf16 v[92:95], v[176:179], v[200:203], v[92:95]
	v_mfma_f32_16x16x32_bf16 v[88:91], v[184:187], v[200:203], v[88:91]
	v_mfma_f32_16x16x32_bf16 v[76:79], v[176:179], v[210:213], v[76:79]
	v_mfma_f32_16x16x32_bf16 v[72:75], v[184:187], v[210:213], v[72:75]
	v_mfma_f32_16x16x32_bf16 v[68:71], v[176:179], v[218:221], v[68:71]
	s_barrier
; #define PG8_STAGE(bufoff, gbase, voff) do { _Pragma("unroll") for (int _i = 0; _i < 2; ++_i) \
;         __builtin_amdgcn_global_load_lds((const unsigned*)((const char*)(gbase) + (voff)[_i]), (PG8_LAS unsigned*)(lds + (bufoff) + ldsw + _i * 8192), 16, 0, 0); } while (0)
; #define PG8_LDA(dst, b, h) do { _Pragma("unroll") for (int m = 0; m < 4; ++m) _Pragma("unroll") for (int k = 0; k < 2; ++k) dst[m][k] = *(const PG8_LAS bf16x8*)(lds + PG8_SA(b, h) + aoff + m * 2048 + k * 1024); } while (0)
; #define PG8_MMA(ai, bj, At, Bt) do { __builtin_amdgcn_s_setprio(1); _Pragma("unroll") for (int m = 0; m < 4; ++m) _Pragma("unroll") for (int n = 0; n < 2; ++n) _Pragma("unroll") for (int k = 0; k < 2; ++k) \
;         acc[ai][bj][m][n] = __builtin_amdgcn_mfma_f32_16x16x32_bf16(Bt[n][k], At[m][k], acc[ai][bj][m][n], 0, 0, 0); __builtin_amdgcn_s_setprio(0); } while (0)
; #define PG8_WAIT_V(n) asm volatile("s_waitcnt vmcnt(" #n ")" ::: "memory")
; #define PG8_WAIT_L(n) asm volatile("s_waitcnt lgkmcnt(" #n ")" ::: "memory")
; #define PG8_BAR __builtin_amdgcn_s_barrier()
; #define PG8_SCHED __builtin_amdgcn_sched_barrier(0)
; template <class Epi, class Sched, bool ALIGN_EPI = false, bool SP2 = false>
; __device__ __forceinline__ void gemm_phase(PG8_LAS unsigned char* lds, const Gemm g, const Sched& S, const Epi& E) {
;     ...
;             PG8_WAIT_V(8); PG8_WAIT_L(0); PG8_BAR; PG8_MMA(0, 0, At, B0); PG8_MMA(0, 1, At, B1); PG8_BAR; PG8_SCHED;
;             PG8_LDA(At, 1, 1); PG8_STAGE(PG8_SB(1, 0), b3, voffB); PG8_STAGE(PG8_SB(1, 1), b3 + hstep, voffB); PG8_STAGE(PG8_SA(1, 0), a3, voffA);
;             PG8_WAIT_V(8); PG8_WAIT_L(0); PG8_BAR; PG8_MMA(1, 0, At, B0); PG8_MMA(1, 1, At, B1); PG8_BAR; PG8_SCHED;
;     ...
;         if constexpr (ALIGN_EPI) { if (wr == 0) PG8_BAR; }
	v_mfma_f32_16x16x32_bf16 v[64:67], v[184:187], v[218:221], v[64:67]
	s_setprio 0
	s_add_i32 s52, vcc_hi, s77
	v_lshl_add_u64 v[222:223], v[222:223], 0, s[10:11]
	s_mov_b32 m0, s52
	ds_read_b128 v[188:191], v145 offset:49152
	ds_read_b128 v[192:195], v145 offset:50176
	ds_read_b128 v[196:199], v145 offset:51200
	ds_read_b128 v[200:203], v145 offset:52224
	ds_read_b128 v[204:207], v145 offset:53248
	ds_read_b128 v[210:213], v145 offset:54272
	ds_read_b128 v[214:217], v145 offset:55296
	ds_read_b128 v[218:221], v145 offset:56320
	global_load_lds_dwordx4 v[222:223], off
	s_add_i32 m0, s52, 0x2000
	s_add_u32 s52, s62, 0x40080
	v_lshl_add_u64 v[222:223], v[224:225], 0, s[10:11]
	s_addc_u32 s53, s63, 0
	s_add_i32 s62, s78, s77
	global_load_lds_dwordx4 v[222:223], off
	v_lshl_add_u64 v[222:223], s[52:53], 0, v[130:131]
	s_mov_b32 m0, s62
	s_nop 0
	global_load_lds_dwordx4 v[222:223], off
	v_lshl_add_u64 v[222:223], s[52:53], 0, v[134:135]
	s_add_i32 m0, s62, 0x2000
	s_nop 0
	global_load_lds_dwordx4 v[222:223], off
	v_lshl_add_u64 v[222:223], v[226:227], 0, s[10:11]
	s_mov_b32 m0, s85
	s_nop 0
	global_load_lds_dwordx4 v[222:223], off
	v_lshl_add_u64 v[222:223], v[228:229], 0, s[10:11]
	s_mov_b32 m0, s86
	s_nop 0
	global_load_lds_dwordx4 v[222:223], off
	s_waitcnt vmcnt(8)
	s_waitcnt lgkmcnt(0)
	s_barrier
	s_setprio 1
	s_waitcnt lgkmcnt(0)
	v_mfma_f32_16x16x32_bf16 v[60:63], v[146:149], v[188:191], v[60:63]
	v_mfma_f32_16x16x32_bf16 v[56:59], v[164:167], v[188:191], v[56:59]
	v_mfma_f32_16x16x32_bf16 v[52:55], v[146:149], v[196:199], v[52:55]
	v_mfma_f32_16x16x32_bf16 v[48:51], v[164:167], v[196:199], v[48:51]
	v_mfma_f32_16x16x32_bf16 v[36:39], v[146:149], v[204:207], v[36:39]
	v_mfma_f32_16x16x32_bf16 v[32:35], v[164:167], v[204:207], v[32:35]
	v_mfma_f32_16x16x32_bf16 v[20:23], v[146:149], v[214:217], v[20:23]
	v_mfma_f32_16x16x32_bf16 v[16:19], v[164:167], v[214:217], v[16:19]
	v_mfma_f32_16x16x32_bf16 v[60:63], v[160:163], v[192:195], v[60:63]
	v_mfma_f32_16x16x32_bf16 v[56:59], v[168:171], v[192:195], v[56:59]
	v_mfma_f32_16x16x32_bf16 v[52:55], v[160:163], v[200:203], v[52:55]
	v_mfma_f32_16x16x32_bf16 v[48:51], v[168:171], v[200:203], v[48:51]
	v_mfma_f32_16x16x32_bf16 v[36:39], v[160:163], v[210:213], v[36:39]
	v_mfma_f32_16x16x32_bf16 v[32:35], v[168:171], v[210:213], v[32:35]
	v_mfma_f32_16x16x32_bf16 v[20:23], v[160:163], v[218:221], v[20:23]
	v_mfma_f32_16x16x32_bf16 v[16:19], v[168:171], v[218:221], v[16:19]
	s_setprio 0
	s_setprio 1
	v_mfma_f32_16x16x32_bf16 v[44:47], v[172:175], v[188:191], v[44:47]
	v_mfma_f32_16x16x32_bf16 v[40:43], v[180:183], v[188:191], v[40:43]
	v_mfma_f32_16x16x32_bf16 v[28:31], v[172:175], v[196:199], v[28:31]
	v_mfma_f32_16x16x32_bf16 v[24:27], v[180:183], v[196:199], v[24:27]
	v_mfma_f32_16x16x32_bf16 v[12:15], v[172:175], v[204:207], v[12:15]
	v_mfma_f32_16x16x32_bf16 v[8:11], v[180:183], v[204:207], v[8:11]
	v_mfma_f32_16x16x32_bf16 v[4:7], v[172:175], v[214:217], v[4:7]
	v_mfma_f32_16x16x32_bf16 v[0:3], v[180:183], v[214:217], v[0:3]
	v_mfma_f32_16x16x32_bf16 v[44:47], v[176:179], v[192:195], v[44:47]
	v_mfma_f32_16x16x32_bf16 v[40:43], v[184:187], v[192:195], v[40:43]
	v_mfma_f32_16x16x32_bf16 v[28:31], v[176:179], v[200:203], v[28:31]
	v_mfma_f32_16x16x32_bf16 v[24:27], v[184:187], v[200:203], v[24:27]
	v_mfma_f32_16x16x32_bf16 v[12:15], v[176:179], v[210:213], v[12:15]
	v_mfma_f32_16x16x32_bf16 v[8:11], v[184:187], v[210:213], v[8:11]
	v_mfma_f32_16x16x32_bf16 v[4:7], v[176:179], v[218:221], v[4:7]
	s_barrier
	v_mfma_f32_16x16x32_bf16 v[0:3], v[184:187], v[218:221], v[0:3]
	s_setprio 0
	s_add_i32 vcc_lo, vcc_lo, 2
	s_add_u32 s42, s42, 0x100
	s_addc_u32 s43, s43, 0
	s_add_u32 s96, s96, 0x100
	s_addc_u32 s97, s97, 0
	s_cmp_gt_u32 vcc_lo, 13
	s_cbranch_scc0 .LBB0_183
	s_and_b64 vcc, exec, s[12:13]
	s_cbranch_vccz .LBB0_186
	s_barrier

; #define PG8_STAGE(bufoff, gbase, voff) do { _Pragma("unroll") for (int _i = 0; _i < 2; ++_i) \
;         __builtin_amdgcn_global_load_lds((const unsigned*)((const char*)(gbase) + (voff)[_i]), (PG8_LAS unsigned*)(lds + (bufoff) + ldsw + _i * 8192), 16, 0, 0); } while (0)
; #define PG8_LDA(dst, b, h) do { _Pragma("unroll") for (int m = 0; m < 4; ++m) _Pragma("unroll") for (int k = 0; k < 2; ++k) dst[m][k] = *(const PG8_LAS bf16x8*)(lds + PG8_SA(b, h) + aoff + m * 2048 + k * 1024); } while (0)
; #define PG8_LDB(dst, b, h) do { _Pragma("unroll") for (int n = 0; n < 2; ++n) _Pragma("unroll") for (int k = 0; k < 2; ++k) dst[n][k] = *(const PG8_LAS bf16x8*)(lds + PG8_SB(b, h) + boff + n * 2048 + k * 1024); } while (0)
; #define PG8_MMA(ai, bj, At, Bt) do { __builtin_amdgcn_s_setprio(1); _Pragma("unroll") for (int m = 0; m < 4; ++m) _Pragma("unroll") for (int n = 0; n < 2; ++n) _Pragma("unroll") for (int k = 0; k < 2; ++k) \
;         acc[ai][bj][m][n] = __builtin_amdgcn_mfma_f32_16x16x32_bf16(Bt[n][k], At[m][k], acc[ai][bj][m][n], 0, 0, 0); __builtin_amdgcn_s_setprio(0); } while (0)
; #define PG8_WAIT_V(n) asm volatile("s_waitcnt vmcnt(" #n ")" ::: "memory")
; #define PG8_WAIT_L(n) asm volatile("s_waitcnt lgkmcnt(" #n ")" ::: "memory")
; #define PG8_BAR __builtin_amdgcn_s_barrier()
; #define PG8_SCHED __builtin_amdgcn_sched_barrier(0)
; template <class Epi, class Sched, bool ALIGN_EPI = false, bool SP2 = false>
; __device__ __forceinline__ void gemm_phase(PG8_LAS unsigned char* lds, const Gemm g, const Sched& S, const Epi& E) {
;     ...
;             PG8_LDB(B0, 0, 0); PG8_LDB(B1, 0, 1); PG8_SCHED; PG8_LDA(At, 0, 0); PG8_STAGE(PG8_SA(1, 1), a1 + hstep, voffA);
;             PG8_WAIT_V(8); PG8_WAIT_L(0); PG8_BAR; PG8_MMA(0, 0, At, B0); PG8_MMA(0, 1, At, B1); PG8_BAR; PG8_SCHED;
;             PG8_LDA(At, 0, 1); PG8_STAGE(PG8_SB(0, 0), b2, voffB); PG8_STAGE(PG8_SB(0, 1), b2 + hstep, voffB); PG8_STAGE(PG8_SA(0, 0), a2, voffA);
.LBB0_207:
	ds_read_b128 v[146:149], v143
	ds_read_b128 v[150:153], v143 offset:1024
	ds_read_b128 v[154:157], v143 offset:2048
	ds_read_b128 v[158:161], v143 offset:3072
	ds_read_b128 v[162:165], v144
	ds_read_b128 v[166:169], v144 offset:1024
	ds_read_b128 v[170:173], v144 offset:2048
	ds_read_b128 v[174:177], v144 offset:3072
	s_add_u32 s52, s62, 0xfffc0080
	s_addc_u32 s53, s63, -1
	s_cmp_eq_u32 s97, 12
	s_cselect_b32 s67, s39, s53
	s_cselect_b32 s66, s93, s52
	s_cselect_b32 s65, s37, s96
	s_cselect_b32 s64, s94, s95
	v_lshl_add_u64 v[206:207], s[62:63], 0, v[136:137]
	s_add_i32 m0, s35, 0xc000
	ds_read_b128 v[178:181], v145
	ds_read_b128 v[182:185], v145 offset:1024
	ds_read_b128 v[186:189], v145 offset:2048
	ds_read_b128 v[190:193], v145 offset:3072
	ds_read_b128 v[194:197], v145 offset:4096
	ds_read_b128 v[198:201], v145 offset:5120
	ds_read_b128 v[202:205], v145 offset:6144
	ds_read_b128 v[210:213], v145 offset:7168
	global_load_lds_dwordx4 v[206:207], off
	v_lshl_add_u64 v[206:207], s[62:63], 0, v[138:139]
	s_add_i32 m0, s35, 0xe000
	s_nop 0
	global_load_lds_dwordx4 v[206:207], off
	s_waitcnt vmcnt(8)
	s_waitcnt lgkmcnt(0)
	s_barrier
	s_setprio 1
	s_waitcnt lgkmcnt(0)
	v_mfma_f32_16x16x32_bf16 v[124:127], v[146:149], v[178:181], v[124:127]
	v_mfma_f32_16x16x32_bf16 v[120:123], v[154:157], v[178:181], v[120:123]
	v_mfma_f32_16x16x32_bf16 v[116:119], v[146:149], v[186:189], v[116:119]
	v_mfma_f32_16x16x32_bf16 v[112:115], v[154:157], v[186:189], v[112:115]
	v_mfma_f32_16x16x32_bf16 v[100:103], v[146:149], v[194:197], v[100:103]
	v_mfma_f32_16x16x32_bf16 v[96:99], v[154:157], v[194:197], v[96:99]
	v_mfma_f32_16x16x32_bf16 v[84:87], v[146:149], v[202:205], v[84:87]
	v_mfma_f32_16x16x32_bf16 v[80:83], v[154:157], v[202:205], v[80:83]
	v_mfma_f32_16x16x32_bf16 v[124:127], v[150:153], v[182:185], v[124:127]
	v_mfma_f32_16x16x32_bf16 v[120:123], v[158:161], v[182:185], v[120:123]
	v_mfma_f32_16x16x32_bf16 v[116:119], v[150:153], v[190:193], v[116:119]
	v_mfma_f32_16x16x32_bf16 v[112:115], v[158:161], v[190:193], v[112:115]
	v_mfma_f32_16x16x32_bf16 v[100:103], v[150:153], v[198:201], v[100:103]
	v_mfma_f32_16x16x32_bf16 v[96:99], v[158:161], v[198:201], v[96:99]
	v_mfma_f32_16x16x32_bf16 v[84:87], v[150:153], v[210:213], v[84:87]
	v_mfma_f32_16x16x32_bf16 v[80:83], v[158:161], v[210:213], v[80:83]
	s_setprio 0
	s_setprio 1
	v_mfma_f32_16x16x32_bf16 v[108:111], v[162:165], v[178:181], v[108:111]
	v_mfma_f32_16x16x32_bf16 v[104:107], v[170:173], v[178:181], v[104:107]
	v_mfma_f32_16x16x32_bf16 v[92:95], v[162:165], v[186:189], v[92:95]
	v_mfma_f32_16x16x32_bf16 v[88:91], v[170:173], v[186:189], v[88:91]
	v_mfma_f32_16x16x32_bf16 v[76:79], v[162:165], v[194:197], v[76:79]
	v_mfma_f32_16x16x32_bf16 v[72:75], v[170:173], v[194:197], v[72:75]
	v_mfma_f32_16x16x32_bf16 v[68:71], v[162:165], v[202:205], v[68:71]
	v_mfma_f32_16x16x32_bf16 v[64:67], v[170:173], v[202:205], v[64:67]
	v_mfma_f32_16x16x32_bf16 v[108:111], v[166:169], v[182:185], v[108:111]
	v_mfma_f32_16x16x32_bf16 v[104:107], v[174:177], v[182:185], v[104:107]
	v_mfma_f32_16x16x32_bf16 v[92:95], v[166:169], v[190:193], v[92:95]
	v_mfma_f32_16x16x32_bf16 v[88:91], v[174:177], v[190:193], v[88:91]
	v_mfma_f32_16x16x32_bf16 v[76:79], v[166:169], v[198:201], v[76:79]
	v_mfma_f32_16x16x32_bf16 v[72:75], v[174:177], v[198:201], v[72:75]
	v_mfma_f32_16x16x32_bf16 v[68:71], v[166:169], v[210:213], v[68:71]
	s_barrier
	v_mfma_f32_16x16x32_bf16 v[64:67], v[174:177], v[210:213], v[64:67]
	s_setprio 0
	s_add_i32 s52, s86, s76
	v_lshl_add_u64 v[206:207], s[64:65], 0, v[130:131]
	s_mov_b32 m0, s52
	ds_read_b128 v[178:181], v145 offset:16384
	ds_read_b128 v[182:185], v145 offset:17408
	ds_read_b128 v[186:189], v145 offset:18432
	ds_read_b128 v[190:193], v145 offset:19456
	ds_read_b128 v[194:197], v145 offset:20480
	ds_read_b128 v[198:201], v145 offset:21504
	ds_read_b128 v[202:205], v145 offset:22528
	ds_read_b128 v[210:213], v145 offset:23552
	global_load_lds_dwordx4 v[206:207], off
	s_add_i32 m0, s52, 0x2000
	s_add_u32 s52, s64, 0x40000
	v_lshl_add_u64 v[214:215], s[64:65], 0, v[134:135]
	s_addc_u32 s53, s65, 0
	s_add_i32 s78, s87, s76
	global_load_lds_dwordx4 v[214:215], off
	v_lshl_add_u64 v[216:217], s[52:53], 0, v[130:131]
	s_mov_b32 m0, s78
	v_lshl_add_u64 v[218:219], s[66:67], 0, v[132:133]
	global_load_lds_dwordx4 v[216:217], off
	v_lshl_add_u64 v[216:217], s[52:53], 0, v[134:135]
	s_add_i32 m0, s78, 0x2000
	s_nop 0
	global_load_lds_dwordx4 v[216:217], off
	v_lshl_add_u64 v[216:217], s[66:67], 0, v[128:129]
	s_mov_b32 m0, s35
	s_nop 0
	global_load_lds_dwordx4 v[216:217], off
	s_mov_b32 m0, s80
	s_nop 0
	global_load_lds_dwordx4 v[218:219], off
	s_waitcnt vmcnt(8)
	s_waitcnt lgkmcnt(0)
	s_barrier
; #define PG8_STAGE(bufoff, gbase, voff) do { _Pragma("unroll") for (int _i = 0; _i < 2; ++_i) \
;         __builtin_amdgcn_global_load_lds((const unsigned*)((const char*)(gbase) + (voff)[_i]), (PG8_LAS unsigned*)(lds + (bufoff) + ldsw + _i * 8192), 16, 0, 0); } while (0)
; #define PG8_LDA(dst, b, h) do { _Pragma("unroll") for (int m = 0; m < 4; ++m) _Pragma("unroll") for (int k = 0; k < 2; ++k) dst[m][k] = *(const PG8_LAS bf16x8*)(lds + PG8_SA(b, h) + aoff + m * 2048 + k * 1024); } while (0)
; #define PG8_LDB(dst, b, h) do { _Pragma("unroll") for (int n = 0; n < 2; ++n) _Pragma("unroll") for (int k = 0; k < 2; ++k) dst[n][k] = *(const PG8_LAS bf16x8*)(lds + PG8_SB(b, h) + boff + n * 2048 + k * 1024); } while (0)
; #define PG8_MMA(ai, bj, At, Bt) do { __builtin_amdgcn_s_setprio(1); _Pragma("unroll") for (int m = 0; m < 4; ++m) _Pragma("unroll") for (int n = 0; n < 2; ++n) _Pragma("unroll") for (int k = 0; k < 2; ++k) \
;         acc[ai][bj][m][n] = __builtin_amdgcn_mfma_f32_16x16x32_bf16(Bt[n][k], At[m][k], acc[ai][bj][m][n], 0, 0, 0); __builtin_amdgcn_s_setprio(0); } while (0)
; #define PG8_WAIT_V(n) asm volatile("s_waitcnt vmcnt(" #n ")" ::: "memory")
; #define PG8_WAIT_L(n) asm volatile("s_waitcnt lgkmcnt(" #n ")" ::: "memory")
; #define PG8_BAR __builtin_amdgcn_s_barrier()
; #define PG8_SCHED __builtin_amdgcn_sched_barrier(0)
; template <class Epi, class Sched, bool ALIGN_EPI = false, bool SP2 = false>
; __device__ __forceinline__ void gemm_phase(PG8_LAS unsigned char* lds, const Gemm g, const Sched& S, const Epi& E) {
;     ...
;             PG8_WAIT_V(8); PG8_WAIT_L(0); PG8_BAR; PG8_MMA(1, 0, At, B0); PG8_MMA(1, 1, At, B1); PG8_BAR; PG8_SCHED;
;             PG8_LDB(B0, 1, 0); PG8_LDB(B1, 1, 1); PG8_SCHED; PG8_LDA(At, 1, 0); PG8_STAGE(PG8_SA(0, 1), a2 + hstep, voffA);
;             PG8_WAIT_V(8); PG8_WAIT_L(0); PG8_BAR; PG8_MMA(0, 0, At, B0); PG8_MMA(0, 1, At, B1); PG8_BAR; PG8_SCHED;
	s_setprio 1
	s_waitcnt lgkmcnt(0)
	v_mfma_f32_16x16x32_bf16 v[60:63], v[146:149], v[178:181], v[60:63]
	v_mfma_f32_16x16x32_bf16 v[56:59], v[154:157], v[178:181], v[56:59]
	v_mfma_f32_16x16x32_bf16 v[52:55], v[146:149], v[186:189], v[52:55]
	v_mfma_f32_16x16x32_bf16 v[48:51], v[154:157], v[186:189], v[48:51]
	v_mfma_f32_16x16x32_bf16 v[36:39], v[146:149], v[194:197], v[36:39]
	v_mfma_f32_16x16x32_bf16 v[32:35], v[154:157], v[194:197], v[32:35]
	v_mfma_f32_16x16x32_bf16 v[20:23], v[146:149], v[202:205], v[20:23]
	v_mfma_f32_16x16x32_bf16 v[16:19], v[154:157], v[202:205], v[16:19]
	v_mfma_f32_16x16x32_bf16 v[60:63], v[150:153], v[182:185], v[60:63]
	v_mfma_f32_16x16x32_bf16 v[56:59], v[158:161], v[182:185], v[56:59]
	v_mfma_f32_16x16x32_bf16 v[52:55], v[150:153], v[190:193], v[52:55]
	v_mfma_f32_16x16x32_bf16 v[48:51], v[158:161], v[190:193], v[48:51]
	v_mfma_f32_16x16x32_bf16 v[36:39], v[150:153], v[198:201], v[36:39]
	v_mfma_f32_16x16x32_bf16 v[32:35], v[158:161], v[198:201], v[32:35]
	v_mfma_f32_16x16x32_bf16 v[20:23], v[150:153], v[210:213], v[20:23]
	v_mfma_f32_16x16x32_bf16 v[16:19], v[158:161], v[210:213], v[16:19]
	s_setprio 0
	s_setprio 1
	v_mfma_f32_16x16x32_bf16 v[44:47], v[162:165], v[178:181], v[44:47]
	v_mfma_f32_16x16x32_bf16 v[40:43], v[170:173], v[178:181], v[40:43]
	v_mfma_f32_16x16x32_bf16 v[28:31], v[162:165], v[186:189], v[28:31]
	v_mfma_f32_16x16x32_bf16 v[24:27], v[170:173], v[186:189], v[24:27]
	v_mfma_f32_16x16x32_bf16 v[12:15], v[162:165], v[194:197], v[12:15]
	v_mfma_f32_16x16x32_bf16 v[8:11], v[170:173], v[194:197], v[8:11]
	v_mfma_f32_16x16x32_bf16 v[4:7], v[162:165], v[202:205], v[4:7]
	v_mfma_f32_16x16x32_bf16 v[0:3], v[170:173], v[202:205], v[0:3]
	v_mfma_f32_16x16x32_bf16 v[44:47], v[166:169], v[182:185], v[44:47]
	v_mfma_f32_16x16x32_bf16 v[40:43], v[174:177], v[182:185], v[40:43]
	v_mfma_f32_16x16x32_bf16 v[28:31], v[166:169], v[190:193], v[28:31]
	v_mfma_f32_16x16x32_bf16 v[24:27], v[174:177], v[190:193], v[24:27]
	v_mfma_f32_16x16x32_bf16 v[12:15], v[166:169], v[198:201], v[12:15]
	v_mfma_f32_16x16x32_bf16 v[8:11], v[174:177], v[198:201], v[8:11]
	v_mfma_f32_16x16x32_bf16 v[4:7], v[166:169], v[210:213], v[4:7]
	s_barrier
	v_mfma_f32_16x16x32_bf16 v[0:3], v[174:177], v[210:213], v[0:3]
	s_setprio 0
	s_add_i32 s78, 0, 0x18000
	s_add_i32 vcc_lo, 0, 0x1c000
	v_add_u32_e32 v158, s78, v141
	v_add_u32_e32 v174, vcc_lo, v141
	ds_read_b128 v[146:149], v158
	ds_read_b128 v[150:153], v158 offset:1024
	ds_read_b128 v[154:157], v158 offset:2048
	ds_read_b128 v[158:161], v158 offset:3072
	ds_read_b128 v[162:165], v174
	ds_read_b128 v[166:169], v174 offset:1024
	ds_read_b128 v[170:173], v174 offset:2048
	ds_read_b128 v[174:177], v174 offset:3072
	s_add_u32 s52, s66, 0x40000
	s_addc_u32 s53, s67, 0
	s_mov_b32 m0, s81
	v_lshl_add_u64 v[220:221], s[52:53], 0, v[128:129]
	ds_read_b128 v[178:181], v145 offset:32768
	ds_read_b128 v[182:185], v145 offset:33792
	ds_read_b128 v[186:189], v145 offset:34816
	ds_read_b128 v[190:193], v145 offset:35840
	ds_read_b128 v[194:197], v145 offset:36864
	ds_read_b128 v[198:201], v145 offset:37888
	ds_read_b128 v[202:205], v145 offset:38912
	ds_read_b128 v[210:213], v145 offset:39936
	global_load_lds_dwordx4 v[220:221], off
	v_lshl_add_u64 v[220:221], s[52:53], 0, v[132:133]
	s_mov_b32 m0, s82
	s_nop 0
	global_load_lds_dwordx4 v[220:221], off
	s_waitcnt vmcnt(8)
	s_waitcnt lgkmcnt(0)
	s_barrier
	s_setprio 1
	s_waitcnt lgkmcnt(0)
	v_mfma_f32_16x16x32_bf16 v[124:127], v[146:149], v[178:181], v[124:127]
	v_mfma_f32_16x16x32_bf16 v[120:123], v[154:157], v[178:181], v[120:123]
	v_mfma_f32_16x16x32_bf16 v[116:119], v[146:149], v[186:189], v[116:119]
	v_mfma_f32_16x16x32_bf16 v[112:115], v[154:157], v[186:189], v[112:115]
	v_mfma_f32_16x16x32_bf16 v[100:103], v[146:149], v[194:197], v[100:103]
	v_mfma_f32_16x16x32_bf16 v[96:99], v[154:157], v[194:197], v[96:99]
	v_mfma_f32_16x16x32_bf16 v[84:87], v[146:149], v[202:205], v[84:87]
	v_mfma_f32_16x16x32_bf16 v[80:83], v[154:157], v[202:205], v[80:83]
	v_mfma_f32_16x16x32_bf16 v[124:127], v[150:153], v[182:185], v[124:127]
	v_mfma_f32_16x16x32_bf16 v[120:123], v[158:161], v[182:185], v[120:123]
	v_mfma_f32_16x16x32_bf16 v[116:119], v[150:153], v[190:193], v[116:119]
	v_mfma_f32_16x16x32_bf16 v[112:115], v[158:161], v[190:193], v[112:115]
	v_mfma_f32_16x16x32_bf16 v[100:103], v[150:153], v[198:201], v[100:103]
	v_mfma_f32_16x16x32_bf16 v[96:99], v[158:161], v[198:201], v[96:99]
	v_mfma_f32_16x16x32_bf16 v[84:87], v[150:153], v[210:213], v[84:87]
	v_mfma_f32_16x16x32_bf16 v[80:83], v[158:161], v[210:213], v[80:83]
	s_setprio 0
	s_setprio 1
	v_mfma_f32_16x16x32_bf16 v[108:111], v[162:165], v[178:181], v[108:111]
	v_mfma_f32_16x16x32_bf16 v[104:107], v[170:173], v[178:181], v[104:107]
	v_mfma_f32_16x16x32_bf16 v[92:95], v[162:165], v[186:189], v[92:95]
	v_mfma_f32_16x16x32_bf16 v[88:91], v[170:173], v[186:189], v[88:91]
	v_mfma_f32_16x16x32_bf16 v[76:79], v[162:165], v[194:197], v[76:79]
	v_mfma_f32_16x16x32_bf16 v[72:75], v[170:173], v[194:197], v[72:75]
	v_mfma_f32_16x16x32_bf16 v[68:71], v[162:165], v[202:205], v[68:71]
	v_mfma_f32_16x16x32_bf16 v[64:67], v[170:173], v[202:205], v[64:67]
	v_mfma_f32_16x16x32_bf16 v[108:111], v[166:169], v[182:185], v[108:111]
	v_mfma_f32_16x16x32_bf16 v[104:107], v[174:177], v[182:185], v[104:107]
	v_mfma_f32_16x16x32_bf16 v[92:95], v[166:169], v[190:193], v[92:95]
	v_mfma_f32_16x16x32_bf16 v[88:91], v[174:177], v[190:193], v[88:91]
	v_mfma_f32_16x16x32_bf16 v[76:79], v[166:169], v[198:201], v[76:79]
	v_mfma_f32_16x16x32_bf16 v[72:75], v[174:177], v[198:201], v[72:75]
	v_mfma_f32_16x16x32_bf16 v[68:71], v[166:169], v[210:213], v[68:71]
	s_barrier
; #define PG8_STAGE(bufoff, gbase, voff) do { _Pragma("unroll") for (int _i = 0; _i < 2; ++_i) \
;         __builtin_amdgcn_global_load_lds((const unsigned*)((const char*)(gbase) + (voff)[_i]), (PG8_LAS unsigned*)(lds + (bufoff) + ldsw + _i * 8192), 16, 0, 0); } while (0)
; #define PG8_LDA(dst, b, h) do { _Pragma("unroll") for (int m = 0; m < 4; ++m) _Pragma("unroll") for (int k = 0; k < 2; ++k) dst[m][k] = *(const PG8_LAS bf16x8*)(lds + PG8_SA(b, h) + aoff + m * 2048 + k * 1024); } while (0)
; #define PG8_MMA(ai, bj, At, Bt) do { __builtin_amdgcn_s_setprio(1); _Pragma("unroll") for (int m = 0; m < 4; ++m) _Pragma("unroll") for (int n = 0; n < 2; ++n) _Pragma("unroll") for (int k = 0; k < 2; ++k) \
;         acc[ai][bj][m][n] = __builtin_amdgcn_mfma_f32_16x16x32_bf16(Bt[n][k], At[m][k], acc[ai][bj][m][n], 0, 0, 0); __builtin_amdgcn_s_setprio(0); } while (0)
; #define PG8_WAIT_V(n) asm volatile("s_waitcnt vmcnt(" #n ")" ::: "memory")
; #define PG8_WAIT_L(n) asm volatile("s_waitcnt lgkmcnt(" #n ")" ::: "memory")
; #define PG8_BAR __builtin_amdgcn_s_barrier()
; #define PG8_SCHED __builtin_amdgcn_sched_barrier(0)
; template <class Epi, class Sched, bool ALIGN_EPI = false, bool SP2 = false>
; __device__ __forceinline__ void gemm_phase(PG8_LAS unsigned char* lds, const Gemm g, const Sched& S, const Epi& E) {
;     ...
;             PG8_WAIT_V(8); PG8_WAIT_L(0); PG8_BAR; PG8_MMA(0, 0, At, B0); PG8_MMA(0, 1, At, B1); PG8_BAR; PG8_SCHED;
;             PG8_LDA(At, 1, 1); PG8_STAGE(PG8_SB(1, 0), b3, voffB); PG8_STAGE(PG8_SB(1, 1), b3 + hstep, voffB); PG8_STAGE(PG8_SA(1, 0), a3, voffA);
;             PG8_WAIT_V(8); PG8_WAIT_L(0); PG8_BAR; PG8_MMA(1, 0, At, B0); PG8_MMA(1, 1, At, B1); PG8_BAR; PG8_SCHED;
;     ...
;         if constexpr (ALIGN_EPI) { if (wr == 0) PG8_BAR; }
	v_mfma_f32_16x16x32_bf16 v[64:67], v[174:177], v[210:213], v[64:67]
	s_setprio 0
	s_add_i32 s52, s78, s76
	v_lshl_add_u64 v[206:207], v[206:207], 0, s[12:13]
	s_mov_b32 m0, s52
	ds_read_b128 v[178:181], v145 offset:49152
	ds_read_b128 v[182:185], v145 offset:50176
	ds_read_b128 v[186:189], v145 offset:51200
	ds_read_b128 v[190:193], v145 offset:52224
	ds_read_b128 v[194:197], v145 offset:53248
	ds_read_b128 v[198:201], v145 offset:54272
	ds_read_b128 v[202:205], v145 offset:55296
	ds_read_b128 v[210:213], v145 offset:56320
	global_load_lds_dwordx4 v[206:207], off
	s_add_i32 m0, s52, 0x2000
	s_add_u32 s52, s64, 0x40080
	v_lshl_add_u64 v[206:207], v[214:215], 0, s[12:13]
	s_addc_u32 s53, s65, 0
	s_add_i32 s64, vcc_lo, s76
	global_load_lds_dwordx4 v[206:207], off
	v_lshl_add_u64 v[206:207], s[52:53], 0, v[130:131]
	s_mov_b32 m0, s64
	s_nop 0
	global_load_lds_dwordx4 v[206:207], off
	v_lshl_add_u64 v[206:207], s[52:53], 0, v[134:135]
	s_add_i32 m0, s64, 0x2000
	s_nop 0
	global_load_lds_dwordx4 v[206:207], off
	v_lshl_add_u64 v[206:207], v[216:217], 0, s[12:13]
	s_mov_b32 m0, s84
	s_nop 0
	global_load_lds_dwordx4 v[206:207], off
	v_lshl_add_u64 v[206:207], v[218:219], 0, s[12:13]
	s_mov_b32 m0, s85
	s_nop 0
	global_load_lds_dwordx4 v[206:207], off
	s_waitcnt vmcnt(8)
	s_waitcnt lgkmcnt(0)
	s_barrier
	s_setprio 1
	s_waitcnt lgkmcnt(0)
	v_mfma_f32_16x16x32_bf16 v[60:63], v[146:149], v[178:181], v[60:63]
	v_mfma_f32_16x16x32_bf16 v[56:59], v[154:157], v[178:181], v[56:59]
	v_mfma_f32_16x16x32_bf16 v[52:55], v[146:149], v[186:189], v[52:55]
	v_mfma_f32_16x16x32_bf16 v[48:51], v[154:157], v[186:189], v[48:51]
	v_mfma_f32_16x16x32_bf16 v[36:39], v[146:149], v[194:197], v[36:39]
	v_mfma_f32_16x16x32_bf16 v[32:35], v[154:157], v[194:197], v[32:35]
	v_mfma_f32_16x16x32_bf16 v[20:23], v[146:149], v[202:205], v[20:23]
	v_mfma_f32_16x16x32_bf16 v[16:19], v[154:157], v[202:205], v[16:19]
	v_mfma_f32_16x16x32_bf16 v[60:63], v[150:153], v[182:185], v[60:63]
	v_mfma_f32_16x16x32_bf16 v[56:59], v[158:161], v[182:185], v[56:59]
	v_mfma_f32_16x16x32_bf16 v[52:55], v[150:153], v[190:193], v[52:55]
	v_mfma_f32_16x16x32_bf16 v[48:51], v[158:161], v[190:193], v[48:51]
	v_mfma_f32_16x16x32_bf16 v[36:39], v[150:153], v[198:201], v[36:39]
	v_mfma_f32_16x16x32_bf16 v[32:35], v[158:161], v[198:201], v[32:35]
	v_mfma_f32_16x16x32_bf16 v[20:23], v[150:153], v[210:213], v[20:23]
	v_mfma_f32_16x16x32_bf16 v[16:19], v[158:161], v[210:213], v[16:19]
	s_setprio 0
	s_setprio 1
	v_mfma_f32_16x16x32_bf16 v[44:47], v[162:165], v[178:181], v[44:47]
	v_mfma_f32_16x16x32_bf16 v[40:43], v[170:173], v[178:181], v[40:43]
	v_mfma_f32_16x16x32_bf16 v[28:31], v[162:165], v[186:189], v[28:31]
	v_mfma_f32_16x16x32_bf16 v[24:27], v[170:173], v[186:189], v[24:27]
	v_mfma_f32_16x16x32_bf16 v[12:15], v[162:165], v[194:197], v[12:15]
	v_mfma_f32_16x16x32_bf16 v[8:11], v[170:173], v[194:197], v[8:11]
	v_mfma_f32_16x16x32_bf16 v[4:7], v[162:165], v[202:205], v[4:7]
	v_mfma_f32_16x16x32_bf16 v[0:3], v[170:173], v[202:205], v[0:3]
	v_mfma_f32_16x16x32_bf16 v[44:47], v[166:169], v[182:185], v[44:47]
	v_mfma_f32_16x16x32_bf16 v[40:43], v[174:177], v[182:185], v[40:43]
	v_mfma_f32_16x16x32_bf16 v[28:31], v[166:169], v[190:193], v[28:31]
	v_mfma_f32_16x16x32_bf16 v[24:27], v[174:177], v[190:193], v[24:27]
	v_mfma_f32_16x16x32_bf16 v[12:15], v[166:169], v[198:201], v[12:15]
	v_mfma_f32_16x16x32_bf16 v[8:11], v[174:177], v[198:201], v[8:11]
	v_mfma_f32_16x16x32_bf16 v[4:7], v[166:169], v[210:213], v[4:7]
	s_barrier
	v_mfma_f32_16x16x32_bf16 v[0:3], v[174:177], v[210:213], v[0:3]
	s_setprio 0
	s_add_i32 s97, s97, 2
	s_add_u32 s62, s62, 0x100
	s_addc_u32 s63, s63, 0
	s_add_u32 s95, s95, 0x100
	s_addc_u32 s96, s96, 0
	s_cmp_gt_u32 s97, 13
	s_cbranch_scc0 .LBB0_207
	s_and_b64 vcc, exec, s[16:17]
	s_cbranch_vccz .LBB0_210
	s_barrier

; #define PG8_STAGE(bufoff, gbase, voff) do { _Pragma("unroll") for (int _i = 0; _i < 2; ++_i) \
;         __builtin_amdgcn_global_load_lds((const unsigned*)((const char*)(gbase) + (voff)[_i]), (PG8_LAS unsigned*)(lds + (bufoff) + ldsw + _i * 8192), 16, 0, 0); } while (0)
; #define PG8_LDA(dst, b, h) do { _Pragma("unroll") for (int m = 0; m < 4; ++m) _Pragma("unroll") for (int k = 0; k < 2; ++k) dst[m][k] = *(const PG8_LAS bf16x8*)(lds + PG8_SA(b, h) + aoff + m * 2048 + k * 1024); } while (0)
; #define PG8_LDB(dst, b, h) do { _Pragma("unroll") for (int n = 0; n < 2; ++n) _Pragma("unroll") for (int k = 0; k < 2; ++k) dst[n][k] = *(const PG8_LAS bf16x8*)(lds + PG8_SB(b, h) + boff + n * 2048 + k * 1024); } while (0)
; #define PG8_MMA(ai, bj, At, Bt) do { __builtin_amdgcn_s_setprio(1); _Pragma("unroll") for (int m = 0; m < 4; ++m) _Pragma("unroll") for (int n = 0; n < 2; ++n) _Pragma("unroll") for (int k = 0; k < 2; ++k) \
;         acc[ai][bj][m][n] = __builtin_amdgcn_mfma_f32_16x16x32_bf16(Bt[n][k], At[m][k], acc[ai][bj][m][n], 0, 0, 0); __builtin_amdgcn_s_setprio(0); } while (0)
; #define PG8_WAIT_V(n) asm volatile("s_waitcnt vmcnt(" #n ")" ::: "memory")
; #define PG8_WAIT_L(n) asm volatile("s_waitcnt lgkmcnt(" #n ")" ::: "memory")
; #define PG8_BAR __builtin_amdgcn_s_barrier()
; #define PG8_SCHED __builtin_amdgcn_sched_barrier(0)
; template <class Epi, class Sched, bool ALIGN_EPI = false, bool SP2 = false>
; __device__ __forceinline__ void gemm_phase(PG8_LAS unsigned char* lds, const Gemm g, const Sched& S, const Epi& E) {
;     ...
;             PG8_LDB(B0, 0, 0); PG8_LDB(B1, 0, 1); PG8_SCHED; PG8_LDA(At, 0, 0); PG8_STAGE(PG8_SA(1, 1), a1 + hstep, voffA);
;             PG8_WAIT_V(8); PG8_WAIT_L(0); PG8_BAR; PG8_MMA(0, 0, At, B0); PG8_MMA(0, 1, At, B1); PG8_BAR; PG8_SCHED;
;             PG8_LDA(At, 0, 1); PG8_STAGE(PG8_SB(0, 0), b2, voffB); PG8_STAGE(PG8_SB(0, 1), b2 + hstep, voffB); PG8_STAGE(PG8_SA(0, 0), a2, voffA);
.LBB0_366:
	v_add_u32_e32 v153, s43, v151
	ds_read_b128 v[154:157], v153
	ds_read_b128 v[158:161], v153 offset:1024
	ds_read_b128 v[162:165], v153 offset:2048
	ds_read_b128 v[166:169], v153 offset:3072
	v_add_u32_e32 v153, s59, v151
	s_add_u32 s20, s12, s18
	ds_read_b128 v[170:173], v153
	ds_read_b128 v[174:177], v153 offset:1024
	ds_read_b128 v[178:181], v153 offset:2048
	ds_read_b128 v[182:185], v153 offset:3072
	s_addc_u32 s21, s13, s19
	s_add_u32 s20, s20, 0x100
	s_addc_u32 s21, s21, 0
	s_add_u32 s52, s64, s18
	s_addc_u32 s53, s65, s19
	s_cmpk_eq_i32 s18, 0x1500
	s_cselect_b32 s23, s17, s21
	s_cselect_b32 s22, s16, s20
	s_cselect_b32 s21, s9, s53
	s_cselect_b32 s20, s8, s52
	v_lshl_add_u64 v[206:207], v[144:145], 0, s[18:19]
	s_add_i32 m0, s34, 0xc000
	ds_read_b128 v[186:189], v152
	ds_read_b128 v[190:193], v152 offset:1024
	ds_read_b128 v[194:197], v152 offset:2048
	ds_read_b128 v[198:201], v152 offset:3072
	ds_read_b128 v[202:205], v152 offset:4096
	ds_read_b128 v[210:213], v152 offset:5120
	ds_read_b128 v[214:217], v152 offset:6144
	ds_read_b128 v[218:221], v152 offset:7168
	global_load_lds_dwordx4 v[206:207], off
	v_lshl_add_u64 v[206:207], v[146:147], 0, s[18:19]
	s_add_i32 m0, s34, 0xe000
	s_nop 0
	global_load_lds_dwordx4 v[206:207], off
	s_waitcnt vmcnt(8)
	s_waitcnt lgkmcnt(0)
	s_barrier
	s_setprio 1
	s_waitcnt lgkmcnt(0)
	v_mfma_f32_16x16x32_bf16 v[124:127], v[154:157], v[186:189], v[124:127]
	v_mfma_f32_16x16x32_bf16 v[120:123], v[162:165], v[186:189], v[120:123]
	v_mfma_f32_16x16x32_bf16 v[108:111], v[154:157], v[194:197], v[108:111]
	v_mfma_f32_16x16x32_bf16 v[104:107], v[162:165], v[194:197], v[104:107]
	v_mfma_f32_16x16x32_bf16 v[92:95], v[154:157], v[202:205], v[92:95]
	v_mfma_f32_16x16x32_bf16 v[88:91], v[162:165], v[202:205], v[88:91]
	v_mfma_f32_16x16x32_bf16 v[76:79], v[154:157], v[214:217], v[76:79]
	v_mfma_f32_16x16x32_bf16 v[72:75], v[162:165], v[214:217], v[72:75]
	v_mfma_f32_16x16x32_bf16 v[124:127], v[158:161], v[190:193], v[124:127]
	v_mfma_f32_16x16x32_bf16 v[120:123], v[166:169], v[190:193], v[120:123]
	v_mfma_f32_16x16x32_bf16 v[108:111], v[158:161], v[198:201], v[108:111]
	v_mfma_f32_16x16x32_bf16 v[104:107], v[166:169], v[198:201], v[104:107]
	v_mfma_f32_16x16x32_bf16 v[92:95], v[158:161], v[210:213], v[92:95]
	v_mfma_f32_16x16x32_bf16 v[88:91], v[166:169], v[210:213], v[88:91]
	v_mfma_f32_16x16x32_bf16 v[76:79], v[158:161], v[218:221], v[76:79]
	v_mfma_f32_16x16x32_bf16 v[72:75], v[166:169], v[218:221], v[72:75]
	s_setprio 0
	s_setprio 1
	v_mfma_f32_16x16x32_bf16 v[116:119], v[170:173], v[186:189], v[116:119]
	v_mfma_f32_16x16x32_bf16 v[112:115], v[178:181], v[186:189], v[112:115]
	v_mfma_f32_16x16x32_bf16 v[100:103], v[170:173], v[194:197], v[100:103]
	v_mfma_f32_16x16x32_bf16 v[96:99], v[178:181], v[194:197], v[96:99]
	v_mfma_f32_16x16x32_bf16 v[84:87], v[170:173], v[202:205], v[84:87]
	v_mfma_f32_16x16x32_bf16 v[80:83], v[178:181], v[202:205], v[80:83]
	v_mfma_f32_16x16x32_bf16 v[68:71], v[170:173], v[214:217], v[68:71]
	v_mfma_f32_16x16x32_bf16 v[64:67], v[178:181], v[214:217], v[64:67]
	v_mfma_f32_16x16x32_bf16 v[116:119], v[174:177], v[190:193], v[116:119]
	v_mfma_f32_16x16x32_bf16 v[112:115], v[182:185], v[190:193], v[112:115]
	v_mfma_f32_16x16x32_bf16 v[100:103], v[174:177], v[198:201], v[100:103]
	v_mfma_f32_16x16x32_bf16 v[96:99], v[182:185], v[198:201], v[96:99]
	v_mfma_f32_16x16x32_bf16 v[84:87], v[174:177], v[210:213], v[84:87]
	v_mfma_f32_16x16x32_bf16 v[80:83], v[182:185], v[210:213], v[80:83]
	v_mfma_f32_16x16x32_bf16 v[68:71], v[174:177], v[218:221], v[68:71]
	s_barrier
	v_mfma_f32_16x16x32_bf16 v[64:67], v[182:185], v[218:221], v[64:67]
	s_setprio 0
	s_add_i32 s52, s43, s29
	v_lshl_add_u64 v[206:207], s[20:21], 0, v[130:131]
	s_mov_b32 m0, s52
	ds_read_b128 v[186:189], v152 offset:16384
	ds_read_b128 v[190:193], v152 offset:17408
	ds_read_b128 v[194:197], v152 offset:18432
	ds_read_b128 v[198:201], v152 offset:19456
	ds_read_b128 v[202:205], v152 offset:20480
	ds_read_b128 v[210:213], v152 offset:21504
	ds_read_b128 v[214:217], v152 offset:22528
	ds_read_b128 v[218:221], v152 offset:23552
	global_load_lds_dwordx4 v[206:207], off
	s_add_i32 m0, s52, 0x2000
	s_add_u32 s52, s20, 0xb0000
	v_lshl_add_u64 v[222:223], s[20:21], 0, v[134:135]
	s_addc_u32 s53, s21, 0
	s_add_i32 s67, s59, s29
	global_load_lds_dwordx4 v[222:223], off
	v_lshl_add_u64 v[224:225], s[52:53], 0, v[130:131]
	s_mov_b32 m0, s67
	v_lshl_add_u64 v[226:227], s[22:23], 0, v[132:133]
	global_load_lds_dwordx4 v[224:225], off
	v_lshl_add_u64 v[224:225], s[52:53], 0, v[134:135]
	s_add_i32 m0, s67, 0x2000
	s_nop 0
	global_load_lds_dwordx4 v[224:225], off
	v_lshl_add_u64 v[224:225], s[22:23], 0, v[128:129]
	s_mov_b32 m0, s34
	s_nop 0
	global_load_lds_dwordx4 v[224:225], off
	s_mov_b32 m0, s35
	s_nop 0
	global_load_lds_dwordx4 v[226:227], off
	s_waitcnt vmcnt(8)
	s_waitcnt lgkmcnt(0)
	s_barrier
; #define PG8_STAGE(bufoff, gbase, voff) do { _Pragma("unroll") for (int _i = 0; _i < 2; ++_i) \
;         __builtin_amdgcn_global_load_lds((const unsigned*)((const char*)(gbase) + (voff)[_i]), (PG8_LAS unsigned*)(lds + (bufoff) + ldsw + _i * 8192), 16, 0, 0); } while (0)
; #define PG8_LDA(dst, b, h) do { _Pragma("unroll") for (int m = 0; m < 4; ++m) _Pragma("unroll") for (int k = 0; k < 2; ++k) dst[m][k] = *(const PG8_LAS bf16x8*)(lds + PG8_SA(b, h) + aoff + m * 2048 + k * 1024); } while (0)
; #define PG8_LDB(dst, b, h) do { _Pragma("unroll") for (int n = 0; n < 2; ++n) _Pragma("unroll") for (int k = 0; k < 2; ++k) dst[n][k] = *(const PG8_LAS bf16x8*)(lds + PG8_SB(b, h) + boff + n * 2048 + k * 1024); } while (0)
; #define PG8_MMA(ai, bj, At, Bt) do { __builtin_amdgcn_s_setprio(1); _Pragma("unroll") for (int m = 0; m < 4; ++m) _Pragma("unroll") for (int n = 0; n < 2; ++n) _Pragma("unroll") for (int k = 0; k < 2; ++k) \
;         acc[ai][bj][m][n] = __builtin_amdgcn_mfma_f32_16x16x32_bf16(Bt[n][k], At[m][k], acc[ai][bj][m][n], 0, 0, 0); __builtin_amdgcn_s_setprio(0); } while (0)
; #define PG8_WAIT_V(n) asm volatile("s_waitcnt vmcnt(" #n ")" ::: "memory")
; #define PG8_WAIT_L(n) asm volatile("s_waitcnt lgkmcnt(" #n ")" ::: "memory")
; #define PG8_BAR __builtin_amdgcn_s_barrier()
; #define PG8_SCHED __builtin_amdgcn_sched_barrier(0)
; template <class Epi, class Sched, bool ALIGN_EPI = false, bool SP2 = false>
; __device__ __forceinline__ void gemm_phase(PG8_LAS unsigned char* lds, const Gemm g, const Sched& S, const Epi& E) {
;     ...
;             PG8_WAIT_V(8); PG8_WAIT_L(0); PG8_BAR; PG8_MMA(1, 0, At, B0); PG8_MMA(1, 1, At, B1); PG8_BAR; PG8_SCHED;
;             PG8_LDB(B0, 1, 0); PG8_LDB(B1, 1, 1); PG8_SCHED; PG8_LDA(At, 1, 0); PG8_STAGE(PG8_SA(0, 1), a2 + hstep, voffA);
;             PG8_WAIT_V(8); PG8_WAIT_L(0); PG8_BAR; PG8_MMA(0, 0, At, B0); PG8_MMA(0, 1, At, B1); PG8_BAR; PG8_SCHED;
	s_setprio 1
	s_waitcnt lgkmcnt(0)
	v_mfma_f32_16x16x32_bf16 v[60:63], v[154:157], v[186:189], v[60:63]
	v_mfma_f32_16x16x32_bf16 v[56:59], v[162:165], v[186:189], v[56:59]
	v_mfma_f32_16x16x32_bf16 v[44:47], v[154:157], v[194:197], v[44:47]
	v_mfma_f32_16x16x32_bf16 v[40:43], v[162:165], v[194:197], v[40:43]
	v_mfma_f32_16x16x32_bf16 v[28:31], v[154:157], v[202:205], v[28:31]
	v_mfma_f32_16x16x32_bf16 v[24:27], v[162:165], v[202:205], v[24:27]
	v_mfma_f32_16x16x32_bf16 v[12:15], v[154:157], v[214:217], v[12:15]
	v_mfma_f32_16x16x32_bf16 v[8:11], v[162:165], v[214:217], v[8:11]
	v_mfma_f32_16x16x32_bf16 v[60:63], v[158:161], v[190:193], v[60:63]
	v_mfma_f32_16x16x32_bf16 v[56:59], v[166:169], v[190:193], v[56:59]
	v_mfma_f32_16x16x32_bf16 v[44:47], v[158:161], v[198:201], v[44:47]
	v_mfma_f32_16x16x32_bf16 v[40:43], v[166:169], v[198:201], v[40:43]
	v_mfma_f32_16x16x32_bf16 v[28:31], v[158:161], v[210:213], v[28:31]
	v_mfma_f32_16x16x32_bf16 v[24:27], v[166:169], v[210:213], v[24:27]
	v_mfma_f32_16x16x32_bf16 v[12:15], v[158:161], v[218:221], v[12:15]
	v_mfma_f32_16x16x32_bf16 v[8:11], v[166:169], v[218:221], v[8:11]
	s_setprio 0
	s_setprio 1
	v_mfma_f32_16x16x32_bf16 v[52:55], v[170:173], v[186:189], v[52:55]
	v_mfma_f32_16x16x32_bf16 v[48:51], v[178:181], v[186:189], v[48:51]
	v_mfma_f32_16x16x32_bf16 v[36:39], v[170:173], v[194:197], v[36:39]
	v_mfma_f32_16x16x32_bf16 v[32:35], v[178:181], v[194:197], v[32:35]
	v_mfma_f32_16x16x32_bf16 v[20:23], v[170:173], v[202:205], v[20:23]
	v_mfma_f32_16x16x32_bf16 v[16:19], v[178:181], v[202:205], v[16:19]
	v_mfma_f32_16x16x32_bf16 v[4:7], v[170:173], v[214:217], v[4:7]
	v_mfma_f32_16x16x32_bf16 v[0:3], v[178:181], v[214:217], v[0:3]
	v_mfma_f32_16x16x32_bf16 v[52:55], v[174:177], v[190:193], v[52:55]
	v_mfma_f32_16x16x32_bf16 v[48:51], v[182:185], v[190:193], v[48:51]
	v_mfma_f32_16x16x32_bf16 v[36:39], v[174:177], v[198:201], v[36:39]
	v_mfma_f32_16x16x32_bf16 v[32:35], v[182:185], v[198:201], v[32:35]
	v_mfma_f32_16x16x32_bf16 v[20:23], v[174:177], v[210:213], v[20:23]
	v_mfma_f32_16x16x32_bf16 v[16:19], v[182:185], v[210:213], v[16:19]
	v_mfma_f32_16x16x32_bf16 v[4:7], v[174:177], v[218:221], v[4:7]
	s_barrier
	v_mfma_f32_16x16x32_bf16 v[0:3], v[182:185], v[218:221], v[0:3]
	s_setprio 0
	s_add_i32 s52, 0, 0x18000
	v_add_u32_e32 v153, s52, v151
	s_add_i32 s53, 0, 0x1c000
	ds_read_b128 v[154:157], v153
	ds_read_b128 v[158:161], v153 offset:1024
	ds_read_b128 v[162:165], v153 offset:2048
	ds_read_b128 v[166:169], v153 offset:3072
	v_add_u32_e32 v153, s53, v151
	ds_read_b128 v[170:173], v153
	ds_read_b128 v[174:177], v153 offset:1024
	ds_read_b128 v[178:181], v153 offset:2048
	ds_read_b128 v[182:185], v153 offset:3072
	s_add_u32 s22, s22, 0xb0000
	s_addc_u32 s23, s23, 0
	s_mov_b32 m0, s36
	v_lshl_add_u64 v[228:229], s[22:23], 0, v[128:129]
	ds_read_b128 v[186:189], v152 offset:32768
	ds_read_b128 v[190:193], v152 offset:33792
	ds_read_b128 v[194:197], v152 offset:34816
	ds_read_b128 v[198:201], v152 offset:35840
	ds_read_b128 v[202:205], v152 offset:36864
	ds_read_b128 v[210:213], v152 offset:37888
	ds_read_b128 v[214:217], v152 offset:38912
	ds_read_b128 v[218:221], v152 offset:39936
	global_load_lds_dwordx4 v[228:229], off
	v_lshl_add_u64 v[228:229], s[22:23], 0, v[132:133]
	s_mov_b32 m0, s37
	s_nop 0
	global_load_lds_dwordx4 v[228:229], off
	s_waitcnt vmcnt(8)
	s_waitcnt lgkmcnt(0)
	s_barrier
	s_setprio 1
	s_waitcnt lgkmcnt(0)
	v_mfma_f32_16x16x32_bf16 v[124:127], v[154:157], v[186:189], v[124:127]
	v_mfma_f32_16x16x32_bf16 v[120:123], v[162:165], v[186:189], v[120:123]
	v_mfma_f32_16x16x32_bf16 v[108:111], v[154:157], v[194:197], v[108:111]
	v_mfma_f32_16x16x32_bf16 v[104:107], v[162:165], v[194:197], v[104:107]
	v_mfma_f32_16x16x32_bf16 v[92:95], v[154:157], v[202:205], v[92:95]
	v_mfma_f32_16x16x32_bf16 v[88:91], v[162:165], v[202:205], v[88:91]
	v_mfma_f32_16x16x32_bf16 v[76:79], v[154:157], v[214:217], v[76:79]
	v_mfma_f32_16x16x32_bf16 v[72:75], v[162:165], v[214:217], v[72:75]
	v_mfma_f32_16x16x32_bf16 v[124:127], v[158:161], v[190:193], v[124:127]
	v_mfma_f32_16x16x32_bf16 v[120:123], v[166:169], v[190:193], v[120:123]
	v_mfma_f32_16x16x32_bf16 v[108:111], v[158:161], v[198:201], v[108:111]
	v_mfma_f32_16x16x32_bf16 v[104:107], v[166:169], v[198:201], v[104:107]
	v_mfma_f32_16x16x32_bf16 v[92:95], v[158:161], v[210:213], v[92:95]
	v_mfma_f32_16x16x32_bf16 v[88:91], v[166:169], v[210:213], v[88:91]
	v_mfma_f32_16x16x32_bf16 v[76:79], v[158:161], v[218:221], v[76:79]
	v_mfma_f32_16x16x32_bf16 v[72:75], v[166:169], v[218:221], v[72:75]
	s_setprio 0
	s_setprio 1
	v_mfma_f32_16x16x32_bf16 v[116:119], v[170:173], v[186:189], v[116:119]
	v_mfma_f32_16x16x32_bf16 v[112:115], v[178:181], v[186:189], v[112:115]
	v_mfma_f32_16x16x32_bf16 v[100:103], v[170:173], v[194:197], v[100:103]
	v_mfma_f32_16x16x32_bf16 v[96:99], v[178:181], v[194:197], v[96:99]
	v_mfma_f32_16x16x32_bf16 v[84:87], v[170:173], v[202:205], v[84:87]
	v_mfma_f32_16x16x32_bf16 v[80:83], v[178:181], v[202:205], v[80:83]
	v_mfma_f32_16x16x32_bf16 v[68:71], v[170:173], v[214:217], v[68:71]
	v_mfma_f32_16x16x32_bf16 v[64:67], v[178:181], v[214:217], v[64:67]
	v_mfma_f32_16x16x32_bf16 v[116:119], v[174:177], v[190:193], v[116:119]
	v_mfma_f32_16x16x32_bf16 v[112:115], v[182:185], v[190:193], v[112:115]
	v_mfma_f32_16x16x32_bf16 v[100:103], v[174:177], v[198:201], v[100:103]
	v_mfma_f32_16x16x32_bf16 v[96:99], v[182:185], v[198:201], v[96:99]
	v_mfma_f32_16x16x32_bf16 v[84:87], v[174:177], v[210:213], v[84:87]
	v_mfma_f32_16x16x32_bf16 v[80:83], v[182:185], v[210:213], v[80:83]
	v_mfma_f32_16x16x32_bf16 v[68:71], v[174:177], v[218:221], v[68:71]
	s_barrier
; #define PG8_STAGE(bufoff, gbase, voff) do { _Pragma("unroll") for (int _i = 0; _i < 2; ++_i) \
;         __builtin_amdgcn_global_load_lds((const unsigned*)((const char*)(gbase) + (voff)[_i]), (PG8_LAS unsigned*)(lds + (bufoff) + ldsw + _i * 8192), 16, 0, 0); } while (0)
; #define PG8_LDA(dst, b, h) do { _Pragma("unroll") for (int m = 0; m < 4; ++m) _Pragma("unroll") for (int k = 0; k < 2; ++k) dst[m][k] = *(const PG8_LAS bf16x8*)(lds + PG8_SA(b, h) + aoff + m * 2048 + k * 1024); } while (0)
; #define PG8_MMA(ai, bj, At, Bt) do { __builtin_amdgcn_s_setprio(1); _Pragma("unroll") for (int m = 0; m < 4; ++m) _Pragma("unroll") for (int n = 0; n < 2; ++n) _Pragma("unroll") for (int k = 0; k < 2; ++k) \
;         acc[ai][bj][m][n] = __builtin_amdgcn_mfma_f32_16x16x32_bf16(Bt[n][k], At[m][k], acc[ai][bj][m][n], 0, 0, 0); __builtin_amdgcn_s_setprio(0); } while (0)
; #define PG8_WAIT_V(n) asm volatile("s_waitcnt vmcnt(" #n ")" ::: "memory")
; #define PG8_WAIT_L(n) asm volatile("s_waitcnt lgkmcnt(" #n ")" ::: "memory")
; #define PG8_BAR __builtin_amdgcn_s_barrier()
; #define PG8_SCHED __builtin_amdgcn_sched_barrier(0)
; template <class Epi, class Sched, bool ALIGN_EPI = false, bool SP2 = false>
; __device__ __forceinline__ void gemm_phase(PG8_LAS unsigned char* lds, const Gemm g, const Sched& S, const Epi& E) {
;     ...
;             PG8_WAIT_V(8); PG8_WAIT_L(0); PG8_BAR; PG8_MMA(0, 0, At, B0); PG8_MMA(0, 1, At, B1); PG8_BAR; PG8_SCHED;
;             PG8_LDA(At, 1, 1); PG8_STAGE(PG8_SB(1, 0), b3, voffB); PG8_STAGE(PG8_SB(1, 1), b3 + hstep, voffB); PG8_STAGE(PG8_SA(1, 0), a3, voffA);
;             PG8_WAIT_V(8); PG8_WAIT_L(0); PG8_BAR; PG8_MMA(1, 0, At, B0); PG8_MMA(1, 1, At, B1); PG8_BAR; PG8_SCHED;
;     ...
;         if (!has_next) break;
; #pragma unroll
;         for (int a = 0; a < 2; ++a)
; #pragma unroll
;             for (int b = 0; b < 2; ++b)
; #pragma unroll
;                 for (int m = 0; m < 4; ++m)
; #pragma unroll
;                     for (int n = 0; n < 2; ++n) acc[a][b][m][n] = (f32x4){0.f, 0.f, 0.f, 0.f};
;         cur = nxt; cA = nA; cB = nB; ++ui;
	v_mfma_f32_16x16x32_bf16 v[64:67], v[182:185], v[218:221], v[64:67]
	s_setprio 0
	s_add_i32 s22, s52, s29
	v_lshl_add_u64 v[206:207], v[206:207], 0, s[14:15]
	s_mov_b32 m0, s22
	ds_read_b128 v[186:189], v152 offset:49152
	ds_read_b128 v[190:193], v152 offset:50176
	ds_read_b128 v[194:197], v152 offset:51200
	ds_read_b128 v[198:201], v152 offset:52224
	ds_read_b128 v[202:205], v152 offset:53248
	ds_read_b128 v[210:213], v152 offset:54272
	ds_read_b128 v[214:217], v152 offset:55296
	ds_read_b128 v[218:221], v152 offset:56320
	global_load_lds_dwordx4 v[206:207], off
	s_add_i32 m0, s22, 0x2000
	s_add_u32 s20, s20, 0xb0080
	v_lshl_add_u64 v[206:207], v[222:223], 0, s[14:15]
	s_addc_u32 s21, s21, 0
	s_add_i32 s22, s53, s29
	global_load_lds_dwordx4 v[206:207], off
	v_lshl_add_u64 v[206:207], s[20:21], 0, v[130:131]
	s_mov_b32 m0, s22
	s_nop 0
	global_load_lds_dwordx4 v[206:207], off
	v_lshl_add_u64 v[206:207], s[20:21], 0, v[134:135]
	s_add_i32 m0, s22, 0x2000
	s_nop 0
	global_load_lds_dwordx4 v[206:207], off
	v_lshl_add_u64 v[206:207], v[224:225], 0, s[14:15]
	s_mov_b32 m0, s39
	s_nop 0
	global_load_lds_dwordx4 v[206:207], off
	v_lshl_add_u64 v[206:207], v[226:227], 0, s[14:15]
	s_mov_b32 m0, s40
	s_nop 0
	global_load_lds_dwordx4 v[206:207], off
	s_waitcnt vmcnt(8)
	s_waitcnt lgkmcnt(0)
	s_barrier
	s_setprio 1
	s_waitcnt lgkmcnt(0)
	v_mfma_f32_16x16x32_bf16 v[60:63], v[154:157], v[186:189], v[60:63]
	v_mfma_f32_16x16x32_bf16 v[56:59], v[162:165], v[186:189], v[56:59]
	v_mfma_f32_16x16x32_bf16 v[44:47], v[154:157], v[194:197], v[44:47]
	v_mfma_f32_16x16x32_bf16 v[40:43], v[162:165], v[194:197], v[40:43]
	v_mfma_f32_16x16x32_bf16 v[28:31], v[154:157], v[202:205], v[28:31]
	v_mfma_f32_16x16x32_bf16 v[24:27], v[162:165], v[202:205], v[24:27]
	v_mfma_f32_16x16x32_bf16 v[12:15], v[154:157], v[214:217], v[12:15]
	v_mfma_f32_16x16x32_bf16 v[8:11], v[162:165], v[214:217], v[8:11]
	v_mfma_f32_16x16x32_bf16 v[60:63], v[158:161], v[190:193], v[60:63]
	v_mfma_f32_16x16x32_bf16 v[56:59], v[166:169], v[190:193], v[56:59]
	v_mfma_f32_16x16x32_bf16 v[44:47], v[158:161], v[198:201], v[44:47]
	v_mfma_f32_16x16x32_bf16 v[40:43], v[166:169], v[198:201], v[40:43]
	v_mfma_f32_16x16x32_bf16 v[28:31], v[158:161], v[210:213], v[28:31]
	v_mfma_f32_16x16x32_bf16 v[24:27], v[166:169], v[210:213], v[24:27]
	v_mfma_f32_16x16x32_bf16 v[12:15], v[158:161], v[218:221], v[12:15]
	v_mfma_f32_16x16x32_bf16 v[8:11], v[166:169], v[218:221], v[8:11]
	s_setprio 0
	s_setprio 1
	v_mfma_f32_16x16x32_bf16 v[52:55], v[170:173], v[186:189], v[52:55]
	v_mfma_f32_16x16x32_bf16 v[48:51], v[178:181], v[186:189], v[48:51]
	v_mfma_f32_16x16x32_bf16 v[36:39], v[170:173], v[194:197], v[36:39]
	v_mfma_f32_16x16x32_bf16 v[32:35], v[178:181], v[194:197], v[32:35]
	v_mfma_f32_16x16x32_bf16 v[20:23], v[170:173], v[202:205], v[20:23]
	v_mfma_f32_16x16x32_bf16 v[16:19], v[178:181], v[202:205], v[16:19]
	v_mfma_f32_16x16x32_bf16 v[4:7], v[170:173], v[214:217], v[4:7]
	v_mfma_f32_16x16x32_bf16 v[0:3], v[178:181], v[214:217], v[0:3]
	v_mfma_f32_16x16x32_bf16 v[52:55], v[174:177], v[190:193], v[52:55]
	v_mfma_f32_16x16x32_bf16 v[48:51], v[182:185], v[190:193], v[48:51]
	v_mfma_f32_16x16x32_bf16 v[36:39], v[174:177], v[198:201], v[36:39]
	v_mfma_f32_16x16x32_bf16 v[32:35], v[182:185], v[198:201], v[32:35]
	v_mfma_f32_16x16x32_bf16 v[20:23], v[174:177], v[210:213], v[20:23]
	v_mfma_f32_16x16x32_bf16 v[16:19], v[182:185], v[210:213], v[16:19]
	v_mfma_f32_16x16x32_bf16 v[4:7], v[174:177], v[218:221], v[4:7]
	s_barrier
	v_mfma_f32_16x16x32_bf16 v[0:3], v[182:185], v[218:221], v[0:3]
	s_setprio 0
	s_add_i32 s66, s66, 2
	s_add_u32 s18, s18, 0x100
	s_addc_u32 s19, s19, 0
	s_cmp_gt_u32 s66, 41
	s_cbranch_scc0 .LBB0_366
	s_add_u32 s18, s64, 0xffffff00
	s_addc_u32 s19, s65, -1
	s_and_b64 vcc, exec, s[6:7]
	s_cbranch_vccnz .LBB0_369
	v_mov_b32_e32 v0, 0
	s_mov_b32 s41, s61
	s_mov_b32 s31, s62
	s_mov_b64 s[12:13], s[16:17]
	s_mov_b32 s42, s63
	v_mov_b32_e32 v1, v0
	v_mov_b32_e32 v2, v0
	v_mov_b32_e32 v3, v0
	v_mov_b32_e32 v4, v0
	v_mov_b32_e32 v5, v0
	v_mov_b32_e32 v6, v0
	v_mov_b32_e32 v7, v0
	v_mov_b32_e32 v16, v0
	v_mov_b32_e32 v17, v0
	v_mov_b32_e32 v18, v0
	v_mov_b32_e32 v19, v0
	v_mov_b32_e32 v20, v0
	v_mov_b32_e32 v21, v0
	v_mov_b32_e32 v22, v0
	v_mov_b32_e32 v23, v0
	v_mov_b32_e32 v32, v0
	v_mov_b32_e32 v33, v0
	v_mov_b32_e32 v34, v0
	v_mov_b32_e32 v35, v0
	v_mov_b32_e32 v36, v0
	v_mov_b32_e32 v37, v0
	v_mov_b32_e32 v38, v0
	v_mov_b32_e32 v39, v0
	v_mov_b32_e32 v48, v0
	v_mov_b32_e32 v49, v0
	v_mov_b32_e32 v50, v0
	v_mov_b32_e32 v51, v0
	v_mov_b32_e32 v52, v0
	v_mov_b32_e32 v53, v0
	v_mov_b32_e32 v54, v0
	v_mov_b32_e32 v55, v0
	v_mov_b32_e32 v8, v0
	v_mov_b32_e32 v9, v0
	v_mov_b32_e32 v10, v0
	v_mov_b32_e32 v11, v0
	v_mov_b32_e32 v12, v0
	v_mov_b32_e32 v13, v0
	v_mov_b32_e32 v14, v0
	v_mov_b32_e32 v15, v0
	v_mov_b32_e32 v24, v0
	v_mov_b32_e32 v25, v0
	v_mov_b32_e32 v26, v0
	v_mov_b32_e32 v27, v0
	v_mov_b32_e32 v28, v0
	v_mov_b32_e32 v29, v0
	v_mov_b32_e32 v30, v0
	v_mov_b32_e32 v31, v0
	v_mov_b32_e32 v40, v0
	v_mov_b32_e32 v41, v0
	v_mov_b32_e32 v42, v0
	v_mov_b32_e32 v43, v0
	v_mov_b32_e32 v44, v0
	v_mov_b32_e32 v45, v0
	v_mov_b32_e32 v46, v0
	v_mov_b32_e32 v47, v0
	v_mov_b32_e32 v56, v0
	v_mov_b32_e32 v57, v0
	v_mov_b32_e32 v58, v0
	v_mov_b32_e32 v59, v0
	v_mov_b32_e32 v60, v0
	v_mov_b32_e32 v61, v0
	v_mov_b32_e32 v62, v0
	v_mov_b32_e32 v63, v0
	v_mov_b32_e32 v64, v0
	v_mov_b32_e32 v65, v0
	v_mov_b32_e32 v66, v0
	v_mov_b32_e32 v67, v0
	v_mov_b32_e32 v68, v0
	v_mov_b32_e32 v69, v0
	v_mov_b32_e32 v70, v0
	v_mov_b32_e32 v71, v0
	v_mov_b32_e32 v80, v0
	v_mov_b32_e32 v81, v0
	v_mov_b32_e32 v82, v0
	v_mov_b32_e32 v83, v0
	v_mov_b32_e32 v84, v0
	v_mov_b32_e32 v85, v0
	v_mov_b32_e32 v86, v0
	v_mov_b32_e32 v87, v0
	v_mov_b32_e32 v96, v0
	v_mov_b32_e32 v97, v0
	v_mov_b32_e32 v98, v0
	v_mov_b32_e32 v99, v0
	v_mov_b32_e32 v100, v0
	v_mov_b32_e32 v101, v0
	v_mov_b32_e32 v102, v0
	v_mov_b32_e32 v103, v0
	v_mov_b32_e32 v112, v0
	v_mov_b32_e32 v113, v0
	v_mov_b32_e32 v114, v0
	v_mov_b32_e32 v115, v0
	v_mov_b32_e32 v116, v0
	v_mov_b32_e32 v117, v0
	v_mov_b32_e32 v118, v0
	v_mov_b32_e32 v119, v0
	v_mov_b32_e32 v72, v0
	v_mov_b32_e32 v73, v0
	v_mov_b32_e32 v74, v0
	v_mov_b32_e32 v75, v0
	v_mov_b32_e32 v76, v0
	v_mov_b32_e32 v77, v0
	v_mov_b32_e32 v78, v0
	v_mov_b32_e32 v79, v0
	v_mov_b32_e32 v88, v0
	v_mov_b32_e32 v89, v0
	v_mov_b32_e32 v90, v0
	v_mov_b32_e32 v91, v0
	v_mov_b32_e32 v92, v0
	v_mov_b32_e32 v93, v0
	v_mov_b32_e32 v94, v0
	v_mov_b32_e32 v95, v0
	v_mov_b32_e32 v104, v0
	v_mov_b32_e32 v105, v0
	v_mov_b32_e32 v106, v0
	v_mov_b32_e32 v107, v0
	v_mov_b32_e32 v108, v0
	v_mov_b32_e32 v109, v0
	v_mov_b32_e32 v110, v0
	v_mov_b32_e32 v111, v0
	v_mov_b32_e32 v120, v0
	v_mov_b32_e32 v121, v0
	v_mov_b32_e32 v122, v0
	v_mov_b32_e32 v123, v0
	v_mov_b32_e32 v124, v0
	v_mov_b32_e32 v125, v0
	v_mov_b32_e32 v126, v0
	v_mov_b32_e32 v127, v0
	s_andn2_b64 vcc, exec, s[4:5]
	s_cbranch_vccnz .LBB0_370
	s_branch .LBB0_371

; #define PG8_STAGE(bufoff, gbase, voff) do { _Pragma("unroll") for (int _i = 0; _i < 2; ++_i) \
;         __builtin_amdgcn_global_load_lds((const unsigned*)((const char*)(gbase) + (voff)[_i]), (PG8_LAS unsigned*)(lds + (bufoff) + ldsw + _i * 8192), 16, 0, 0); } while (0)
; #define PG8_LDA(dst, b, h) do { _Pragma("unroll") for (int m = 0; m < 4; ++m) _Pragma("unroll") for (int k = 0; k < 2; ++k) dst[m][k] = *(const PG8_LAS bf16x8*)(lds + PG8_SA(b, h) + aoff + m * 2048 + k * 1024); } while (0)
; #define PG8_LDB(dst, b, h) do { _Pragma("unroll") for (int n = 0; n < 2; ++n) _Pragma("unroll") for (int k = 0; k < 2; ++k) dst[n][k] = *(const PG8_LAS bf16x8*)(lds + PG8_SB(b, h) + boff + n * 2048 + k * 1024); } while (0)
; #define PG8_MMA(ai, bj, At, Bt) do { __builtin_amdgcn_s_setprio(1); _Pragma("unroll") for (int m = 0; m < 4; ++m) _Pragma("unroll") for (int n = 0; n < 2; ++n) _Pragma("unroll") for (int k = 0; k < 2; ++k) \
;         acc[ai][bj][m][n] = __builtin_amdgcn_mfma_f32_16x16x32_bf16(Bt[n][k], At[m][k], acc[ai][bj][m][n], 0, 0, 0); __builtin_amdgcn_s_setprio(0); } while (0)
; #define PG8_WAIT_V(n) asm volatile("s_waitcnt vmcnt(" #n ")" ::: "memory")
; #define PG8_WAIT_L(n) asm volatile("s_waitcnt lgkmcnt(" #n ")" ::: "memory")
; #define PG8_BAR __builtin_amdgcn_s_barrier()
; #define PG8_SCHED __builtin_amdgcn_sched_barrier(0)
; template <class Epi, class Sched, bool ALIGN_EPI = false, bool SP2 = false>
; __device__ __forceinline__ void gemm_phase(PG8_LAS unsigned char* lds, const Gemm g, const Sched& S, const Epi& E) {
;     ...
;             PG8_LDB(B0, 0, 0); PG8_LDB(B1, 0, 1); PG8_SCHED; PG8_LDA(At, 0, 0); PG8_STAGE(PG8_SA(1, 1), a1 + hstep, voffA);
;             PG8_WAIT_V(8); PG8_WAIT_L(0); PG8_BAR; PG8_MMA(0, 0, At, B0); PG8_MMA(0, 1, At, B1); PG8_BAR; PG8_SCHED;
;             PG8_LDA(At, 0, 1); PG8_STAGE(PG8_SB(0, 0), b2, voffB); PG8_STAGE(PG8_SB(0, 1), b2 + hstep, voffB); PG8_STAGE(PG8_SA(0, 0), a2, voffA);
.LBB0_462:
	ds_read_b128 v[148:151], v167
	ds_read_b128 v[152:155], v167 offset:1024
	ds_read_b128 v[156:159], v167 offset:2048
	ds_read_b128 v[160:163], v167 offset:3072
	ds_read_b128 v[172:175], v168
	ds_read_b128 v[176:179], v168 offset:1024
	ds_read_b128 v[180:183], v168 offset:2048
	ds_read_b128 v[184:187], v168 offset:3072
	s_add_u32 s52, s8, 0xfffc0080
	s_addc_u32 s53, s9, -1
	s_cmp_eq_u32 vcc_lo, 12
	s_cselect_b32 s75, s7, s53
	s_cselect_b32 s74, s67, s52
	s_cselect_b32 s73, s65, s97
	s_cselect_b32 s72, s95, s96
	v_lshl_add_u64 v[164:165], s[8:9], 0, v[140:141]
	s_add_i32 m0, s76, 0xc000
	ds_read_b128 v[188:191], v169
	ds_read_b128 v[192:195], v169 offset:1024
	ds_read_b128 v[196:199], v169 offset:2048
	ds_read_b128 v[200:203], v169 offset:3072
	ds_read_b128 v[204:207], v169 offset:4096
	ds_read_b128 v[210:213], v169 offset:5120
	ds_read_b128 v[214:217], v169 offset:6144
	ds_read_b128 v[218:221], v169 offset:7168
	global_load_lds_dwordx4 v[164:165], off
	v_lshl_add_u64 v[164:165], s[8:9], 0, v[142:143]
	s_add_i32 m0, s76, 0xe000
	s_nop 0
	global_load_lds_dwordx4 v[164:165], off
	s_waitcnt vmcnt(8)
	s_waitcnt lgkmcnt(0)
	s_barrier
	s_setprio 1
	s_waitcnt lgkmcnt(0)
	v_mfma_f32_16x16x32_bf16 v[124:127], v[148:151], v[188:191], v[124:127]
	v_mfma_f32_16x16x32_bf16 v[120:123], v[156:159], v[188:191], v[120:123]
	v_mfma_f32_16x16x32_bf16 v[108:111], v[148:151], v[196:199], v[108:111]
	v_mfma_f32_16x16x32_bf16 v[104:107], v[156:159], v[196:199], v[104:107]
	v_mfma_f32_16x16x32_bf16 v[92:95], v[148:151], v[204:207], v[92:95]
	v_mfma_f32_16x16x32_bf16 v[88:91], v[156:159], v[204:207], v[88:91]
	v_mfma_f32_16x16x32_bf16 v[76:79], v[148:151], v[214:217], v[76:79]
	v_mfma_f32_16x16x32_bf16 v[72:75], v[156:159], v[214:217], v[72:75]
	v_mfma_f32_16x16x32_bf16 v[124:127], v[152:155], v[192:195], v[124:127]
	v_mfma_f32_16x16x32_bf16 v[120:123], v[160:163], v[192:195], v[120:123]
	v_mfma_f32_16x16x32_bf16 v[108:111], v[152:155], v[200:203], v[108:111]
	v_mfma_f32_16x16x32_bf16 v[104:107], v[160:163], v[200:203], v[104:107]
	v_mfma_f32_16x16x32_bf16 v[92:95], v[152:155], v[210:213], v[92:95]
	v_mfma_f32_16x16x32_bf16 v[88:91], v[160:163], v[210:213], v[88:91]
	v_mfma_f32_16x16x32_bf16 v[76:79], v[152:155], v[218:221], v[76:79]
	v_mfma_f32_16x16x32_bf16 v[72:75], v[160:163], v[218:221], v[72:75]
	s_setprio 0
	s_setprio 1
	v_mfma_f32_16x16x32_bf16 v[116:119], v[172:175], v[188:191], v[116:119]
	v_mfma_f32_16x16x32_bf16 v[112:115], v[180:183], v[188:191], v[112:115]
	v_mfma_f32_16x16x32_bf16 v[100:103], v[172:175], v[196:199], v[100:103]
	v_mfma_f32_16x16x32_bf16 v[96:99], v[180:183], v[196:199], v[96:99]
	v_mfma_f32_16x16x32_bf16 v[84:87], v[172:175], v[204:207], v[84:87]
	v_mfma_f32_16x16x32_bf16 v[80:83], v[180:183], v[204:207], v[80:83]
	v_mfma_f32_16x16x32_bf16 v[68:71], v[172:175], v[214:217], v[68:71]
	v_mfma_f32_16x16x32_bf16 v[64:67], v[180:183], v[214:217], v[64:67]
	v_mfma_f32_16x16x32_bf16 v[116:119], v[176:179], v[192:195], v[116:119]
	v_mfma_f32_16x16x32_bf16 v[112:115], v[184:187], v[192:195], v[112:115]
	v_mfma_f32_16x16x32_bf16 v[100:103], v[176:179], v[200:203], v[100:103]
	v_mfma_f32_16x16x32_bf16 v[96:99], v[184:187], v[200:203], v[96:99]
	v_mfma_f32_16x16x32_bf16 v[84:87], v[176:179], v[210:213], v[84:87]
	v_mfma_f32_16x16x32_bf16 v[80:83], v[184:187], v[210:213], v[80:83]
	v_mfma_f32_16x16x32_bf16 v[68:71], v[176:179], v[218:221], v[68:71]
	s_barrier
	v_mfma_f32_16x16x32_bf16 v[64:67], v[184:187], v[218:221], v[64:67]
	s_setprio 0
	s_add_i32 s52, s85, s61
	v_lshl_add_u64 v[164:165], s[72:73], 0, v[130:131]
	s_mov_b32 m0, s52
	ds_read_b128 v[188:191], v169 offset:16384
	ds_read_b128 v[192:195], v169 offset:17408
	ds_read_b128 v[196:199], v169 offset:18432
	ds_read_b128 v[200:203], v169 offset:19456
	ds_read_b128 v[204:207], v169 offset:20480
	ds_read_b128 v[210:213], v169 offset:21504
	ds_read_b128 v[214:217], v169 offset:22528
	ds_read_b128 v[218:221], v169 offset:23552
	global_load_lds_dwordx4 v[164:165], off
	s_add_i32 m0, s52, 0x2000
	s_add_u32 s52, s72, 0x40000
	v_lshl_add_u64 v[222:223], s[72:73], 0, v[134:135]
	s_addc_u32 s53, s73, 0
	s_add_i32 s78, s86, s61
	global_load_lds_dwordx4 v[222:223], off
	v_lshl_add_u64 v[224:225], s[52:53], 0, v[130:131]
	s_mov_b32 m0, s78
	v_lshl_add_u64 v[226:227], s[74:75], 0, v[132:133]
	global_load_lds_dwordx4 v[224:225], off
	v_lshl_add_u64 v[224:225], s[52:53], 0, v[134:135]
	s_add_i32 m0, s78, 0x2000
	s_nop 0
	global_load_lds_dwordx4 v[224:225], off
	v_lshl_add_u64 v[224:225], s[74:75], 0, v[128:129]
	s_mov_b32 m0, s76
	s_nop 0
	global_load_lds_dwordx4 v[224:225], off
	s_mov_b32 m0, s77
	s_nop 0
	global_load_lds_dwordx4 v[226:227], off
	s_waitcnt vmcnt(8)
	s_waitcnt lgkmcnt(0)
	s_barrier
; #define PG8_STAGE(bufoff, gbase, voff) do { _Pragma("unroll") for (int _i = 0; _i < 2; ++_i) \
;         __builtin_amdgcn_global_load_lds((const unsigned*)((const char*)(gbase) + (voff)[_i]), (PG8_LAS unsigned*)(lds + (bufoff) + ldsw + _i * 8192), 16, 0, 0); } while (0)
; #define PG8_LDA(dst, b, h) do { _Pragma("unroll") for (int m = 0; m < 4; ++m) _Pragma("unroll") for (int k = 0; k < 2; ++k) dst[m][k] = *(const PG8_LAS bf16x8*)(lds + PG8_SA(b, h) + aoff + m * 2048 + k * 1024); } while (0)
; #define PG8_LDB(dst, b, h) do { _Pragma("unroll") for (int n = 0; n < 2; ++n) _Pragma("unroll") for (int k = 0; k < 2; ++k) dst[n][k] = *(const PG8_LAS bf16x8*)(lds + PG8_SB(b, h) + boff + n * 2048 + k * 1024); } while (0)
; #define PG8_MMA(ai, bj, At, Bt) do { __builtin_amdgcn_s_setprio(1); _Pragma("unroll") for (int m = 0; m < 4; ++m) _Pragma("unroll") for (int n = 0; n < 2; ++n) _Pragma("unroll") for (int k = 0; k < 2; ++k) \
;         acc[ai][bj][m][n] = __builtin_amdgcn_mfma_f32_16x16x32_bf16(Bt[n][k], At[m][k], acc[ai][bj][m][n], 0, 0, 0); __builtin_amdgcn_s_setprio(0); } while (0)
; #define PG8_WAIT_V(n) asm volatile("s_waitcnt vmcnt(" #n ")" ::: "memory")
; #define PG8_WAIT_L(n) asm volatile("s_waitcnt lgkmcnt(" #n ")" ::: "memory")
; #define PG8_BAR __builtin_amdgcn_s_barrier()
; #define PG8_SCHED __builtin_amdgcn_sched_barrier(0)
; template <class Epi, class Sched, bool ALIGN_EPI = false, bool SP2 = false>
; __device__ __forceinline__ void gemm_phase(PG8_LAS unsigned char* lds, const Gemm g, const Sched& S, const Epi& E) {
;     ...
;             PG8_WAIT_V(8); PG8_WAIT_L(0); PG8_BAR; PG8_MMA(1, 0, At, B0); PG8_MMA(1, 1, At, B1); PG8_BAR; PG8_SCHED;
;             PG8_LDB(B0, 1, 0); PG8_LDB(B1, 1, 1); PG8_SCHED; PG8_LDA(At, 1, 0); PG8_STAGE(PG8_SA(0, 1), a2 + hstep, voffA);
;             PG8_WAIT_V(8); PG8_WAIT_L(0); PG8_BAR; PG8_MMA(0, 0, At, B0); PG8_MMA(0, 1, At, B1); PG8_BAR; PG8_SCHED;
	s_setprio 1
	s_waitcnt lgkmcnt(0)
	v_mfma_f32_16x16x32_bf16 v[60:63], v[148:151], v[188:191], v[60:63]
	v_mfma_f32_16x16x32_bf16 v[56:59], v[156:159], v[188:191], v[56:59]
	v_mfma_f32_16x16x32_bf16 v[44:47], v[148:151], v[196:199], v[44:47]
	v_mfma_f32_16x16x32_bf16 v[40:43], v[156:159], v[196:199], v[40:43]
	v_mfma_f32_16x16x32_bf16 v[28:31], v[148:151], v[204:207], v[28:31]
	v_mfma_f32_16x16x32_bf16 v[24:27], v[156:159], v[204:207], v[24:27]
	v_mfma_f32_16x16x32_bf16 v[12:15], v[148:151], v[214:217], v[12:15]
	v_mfma_f32_16x16x32_bf16 v[8:11], v[156:159], v[214:217], v[8:11]
	v_mfma_f32_16x16x32_bf16 v[60:63], v[152:155], v[192:195], v[60:63]
	v_mfma_f32_16x16x32_bf16 v[56:59], v[160:163], v[192:195], v[56:59]
	v_mfma_f32_16x16x32_bf16 v[44:47], v[152:155], v[200:203], v[44:47]
	v_mfma_f32_16x16x32_bf16 v[40:43], v[160:163], v[200:203], v[40:43]
	v_mfma_f32_16x16x32_bf16 v[28:31], v[152:155], v[210:213], v[28:31]
	v_mfma_f32_16x16x32_bf16 v[24:27], v[160:163], v[210:213], v[24:27]
	v_mfma_f32_16x16x32_bf16 v[12:15], v[152:155], v[218:221], v[12:15]
	v_mfma_f32_16x16x32_bf16 v[8:11], v[160:163], v[218:221], v[8:11]
	s_setprio 0
	s_setprio 1
	v_mfma_f32_16x16x32_bf16 v[52:55], v[172:175], v[188:191], v[52:55]
	v_mfma_f32_16x16x32_bf16 v[48:51], v[180:183], v[188:191], v[48:51]
	v_mfma_f32_16x16x32_bf16 v[36:39], v[172:175], v[196:199], v[36:39]
	v_mfma_f32_16x16x32_bf16 v[32:35], v[180:183], v[196:199], v[32:35]
	v_mfma_f32_16x16x32_bf16 v[20:23], v[172:175], v[204:207], v[20:23]
	v_mfma_f32_16x16x32_bf16 v[16:19], v[180:183], v[204:207], v[16:19]
	v_mfma_f32_16x16x32_bf16 v[4:7], v[172:175], v[214:217], v[4:7]
	v_mfma_f32_16x16x32_bf16 v[0:3], v[180:183], v[214:217], v[0:3]
	v_mfma_f32_16x16x32_bf16 v[52:55], v[176:179], v[192:195], v[52:55]
	v_mfma_f32_16x16x32_bf16 v[48:51], v[184:187], v[192:195], v[48:51]
	v_mfma_f32_16x16x32_bf16 v[36:39], v[176:179], v[200:203], v[36:39]
	v_mfma_f32_16x16x32_bf16 v[32:35], v[184:187], v[200:203], v[32:35]
	v_mfma_f32_16x16x32_bf16 v[20:23], v[176:179], v[210:213], v[20:23]
	v_mfma_f32_16x16x32_bf16 v[16:19], v[184:187], v[210:213], v[16:19]
	v_mfma_f32_16x16x32_bf16 v[4:7], v[176:179], v[218:221], v[4:7]
	s_barrier
	v_mfma_f32_16x16x32_bf16 v[0:3], v[184:187], v[218:221], v[0:3]
	s_setprio 0
	s_add_i32 s78, 0, 0x18000
	v_add_u32_e32 v136, s78, v166
	s_add_i32 vcc_hi, 0, 0x1c000
	ds_read_b128 v[148:151], v136
	ds_read_b128 v[152:155], v136 offset:1024
	ds_read_b128 v[156:159], v136 offset:2048
	ds_read_b128 v[160:163], v136 offset:3072
	v_add_u32_e32 v136, vcc_hi, v166
	ds_read_b128 v[172:175], v136
	ds_read_b128 v[176:179], v136 offset:1024
	ds_read_b128 v[180:183], v136 offset:2048
	ds_read_b128 v[184:187], v136 offset:3072
	s_add_u32 s52, s74, 0x40000
	s_addc_u32 s53, s75, 0
	s_mov_b32 m0, s79
	v_lshl_add_u64 v[228:229], s[52:53], 0, v[128:129]
	ds_read_b128 v[188:191], v169 offset:32768
	ds_read_b128 v[192:195], v169 offset:33792
	ds_read_b128 v[196:199], v169 offset:34816
	ds_read_b128 v[200:203], v169 offset:35840
	ds_read_b128 v[204:207], v169 offset:36864
	ds_read_b128 v[210:213], v169 offset:37888
	ds_read_b128 v[214:217], v169 offset:38912
	ds_read_b128 v[218:221], v169 offset:39936
	global_load_lds_dwordx4 v[228:229], off
	v_lshl_add_u64 v[228:229], s[52:53], 0, v[132:133]
	s_mov_b32 m0, s80
	s_nop 0
	global_load_lds_dwordx4 v[228:229], off
	s_waitcnt vmcnt(8)
	s_waitcnt lgkmcnt(0)
	s_barrier
	s_setprio 1
	s_waitcnt lgkmcnt(0)
	v_mfma_f32_16x16x32_bf16 v[124:127], v[148:151], v[188:191], v[124:127]
	v_mfma_f32_16x16x32_bf16 v[120:123], v[156:159], v[188:191], v[120:123]
	v_mfma_f32_16x16x32_bf16 v[108:111], v[148:151], v[196:199], v[108:111]
	v_mfma_f32_16x16x32_bf16 v[104:107], v[156:159], v[196:199], v[104:107]
	v_mfma_f32_16x16x32_bf16 v[92:95], v[148:151], v[204:207], v[92:95]
	v_mfma_f32_16x16x32_bf16 v[88:91], v[156:159], v[204:207], v[88:91]
	v_mfma_f32_16x16x32_bf16 v[76:79], v[148:151], v[214:217], v[76:79]
	v_mfma_f32_16x16x32_bf16 v[72:75], v[156:159], v[214:217], v[72:75]
	v_mfma_f32_16x16x32_bf16 v[124:127], v[152:155], v[192:195], v[124:127]
	v_mfma_f32_16x16x32_bf16 v[120:123], v[160:163], v[192:195], v[120:123]
	v_mfma_f32_16x16x32_bf16 v[108:111], v[152:155], v[200:203], v[108:111]
	v_mfma_f32_16x16x32_bf16 v[104:107], v[160:163], v[200:203], v[104:107]
	v_mfma_f32_16x16x32_bf16 v[92:95], v[152:155], v[210:213], v[92:95]
	v_mfma_f32_16x16x32_bf16 v[88:91], v[160:163], v[210:213], v[88:91]
	v_mfma_f32_16x16x32_bf16 v[76:79], v[152:155], v[218:221], v[76:79]
	v_mfma_f32_16x16x32_bf16 v[72:75], v[160:163], v[218:221], v[72:75]
	s_setprio 0
	s_setprio 1
	v_mfma_f32_16x16x32_bf16 v[116:119], v[172:175], v[188:191], v[116:119]
	v_mfma_f32_16x16x32_bf16 v[112:115], v[180:183], v[188:191], v[112:115]
	v_mfma_f32_16x16x32_bf16 v[100:103], v[172:175], v[196:199], v[100:103]
	v_mfma_f32_16x16x32_bf16 v[96:99], v[180:183], v[196:199], v[96:99]
	v_mfma_f32_16x16x32_bf16 v[84:87], v[172:175], v[204:207], v[84:87]
	v_mfma_f32_16x16x32_bf16 v[80:83], v[180:183], v[204:207], v[80:83]
	v_mfma_f32_16x16x32_bf16 v[68:71], v[172:175], v[214:217], v[68:71]
	v_mfma_f32_16x16x32_bf16 v[64:67], v[180:183], v[214:217], v[64:67]
	v_mfma_f32_16x16x32_bf16 v[116:119], v[176:179], v[192:195], v[116:119]
	v_mfma_f32_16x16x32_bf16 v[112:115], v[184:187], v[192:195], v[112:115]
	v_mfma_f32_16x16x32_bf16 v[100:103], v[176:179], v[200:203], v[100:103]
	v_mfma_f32_16x16x32_bf16 v[96:99], v[184:187], v[200:203], v[96:99]
	v_mfma_f32_16x16x32_bf16 v[84:87], v[176:179], v[210:213], v[84:87]
	v_mfma_f32_16x16x32_bf16 v[80:83], v[184:187], v[210:213], v[80:83]
	v_mfma_f32_16x16x32_bf16 v[68:71], v[176:179], v[218:221], v[68:71]
	s_barrier
; #define PG8_STAGE(bufoff, gbase, voff) do { _Pragma("unroll") for (int _i = 0; _i < 2; ++_i) \
;         __builtin_amdgcn_global_load_lds((const unsigned*)((const char*)(gbase) + (voff)[_i]), (PG8_LAS unsigned*)(lds + (bufoff) + ldsw + _i * 8192), 16, 0, 0); } while (0)
; #define PG8_LDA(dst, b, h) do { _Pragma("unroll") for (int m = 0; m < 4; ++m) _Pragma("unroll") for (int k = 0; k < 2; ++k) dst[m][k] = *(const PG8_LAS bf16x8*)(lds + PG8_SA(b, h) + aoff + m * 2048 + k * 1024); } while (0)
; #define PG8_MMA(ai, bj, At, Bt) do { __builtin_amdgcn_s_setprio(1); _Pragma("unroll") for (int m = 0; m < 4; ++m) _Pragma("unroll") for (int n = 0; n < 2; ++n) _Pragma("unroll") for (int k = 0; k < 2; ++k) \
;         acc[ai][bj][m][n] = __builtin_amdgcn_mfma_f32_16x16x32_bf16(Bt[n][k], At[m][k], acc[ai][bj][m][n], 0, 0, 0); __builtin_amdgcn_s_setprio(0); } while (0)
; #define PG8_WAIT_V(n) asm volatile("s_waitcnt vmcnt(" #n ")" ::: "memory")
; #define PG8_WAIT_L(n) asm volatile("s_waitcnt lgkmcnt(" #n ")" ::: "memory")
; #define PG8_BAR __builtin_amdgcn_s_barrier()
; #define PG8_SCHED __builtin_amdgcn_sched_barrier(0)
; template <class Epi, class Sched, bool ALIGN_EPI = false, bool SP2 = false>
; __device__ __forceinline__ void gemm_phase(PG8_LAS unsigned char* lds, const Gemm g, const Sched& S, const Epi& E) {
;     ...
;             PG8_WAIT_V(8); PG8_WAIT_L(0); PG8_BAR; PG8_MMA(0, 0, At, B0); PG8_MMA(0, 1, At, B1); PG8_BAR; PG8_SCHED;
;             PG8_LDA(At, 1, 1); PG8_STAGE(PG8_SB(1, 0), b3, voffB); PG8_STAGE(PG8_SB(1, 1), b3 + hstep, voffB); PG8_STAGE(PG8_SA(1, 0), a3, voffA);
;             PG8_WAIT_V(8); PG8_WAIT_L(0); PG8_BAR; PG8_MMA(1, 0, At, B0); PG8_MMA(1, 1, At, B1); PG8_BAR; PG8_SCHED;
	v_mfma_f32_16x16x32_bf16 v[64:67], v[184:187], v[218:221], v[64:67]
	s_setprio 0
	s_add_i32 s52, s78, s61
	v_lshl_add_u64 v[164:165], v[164:165], 0, s[34:35]
	s_mov_b32 m0, s52
	ds_read_b128 v[188:191], v169 offset:49152
	ds_read_b128 v[192:195], v169 offset:50176
	ds_read_b128 v[196:199], v169 offset:51200
	ds_read_b128 v[200:203], v169 offset:52224
	ds_read_b128 v[204:207], v169 offset:53248
	ds_read_b128 v[210:213], v169 offset:54272
	ds_read_b128 v[214:217], v169 offset:55296
	ds_read_b128 v[218:221], v169 offset:56320
	global_load_lds_dwordx4 v[164:165], off
	s_add_i32 m0, s52, 0x2000
	s_add_u32 s52, s72, 0x40080
	v_lshl_add_u64 v[164:165], v[222:223], 0, s[34:35]
	s_addc_u32 s53, s73, 0
	s_add_i32 s72, vcc_hi, s61
	global_load_lds_dwordx4 v[164:165], off
	v_lshl_add_u64 v[164:165], s[52:53], 0, v[130:131]
	s_mov_b32 m0, s72
	s_nop 0
	global_load_lds_dwordx4 v[164:165], off
	v_lshl_add_u64 v[164:165], s[52:53], 0, v[134:135]
	s_add_i32 m0, s72, 0x2000
	s_nop 0
	global_load_lds_dwordx4 v[164:165], off
	v_lshl_add_u64 v[164:165], v[224:225], 0, s[34:35]
	s_mov_b32 m0, s83
	s_nop 0
	global_load_lds_dwordx4 v[164:165], off
	v_lshl_add_u64 v[164:165], v[226:227], 0, s[34:35]
	s_mov_b32 m0, s84
	s_nop 0
	global_load_lds_dwordx4 v[164:165], off
	s_waitcnt vmcnt(8)
	s_waitcnt lgkmcnt(0)
	s_barrier
	s_setprio 1
	s_waitcnt lgkmcnt(0)
	v_mfma_f32_16x16x32_bf16 v[60:63], v[148:151], v[188:191], v[60:63]
	v_mfma_f32_16x16x32_bf16 v[56:59], v[156:159], v[188:191], v[56:59]
	v_mfma_f32_16x16x32_bf16 v[44:47], v[148:151], v[196:199], v[44:47]
	v_mfma_f32_16x16x32_bf16 v[40:43], v[156:159], v[196:199], v[40:43]
	v_mfma_f32_16x16x32_bf16 v[28:31], v[148:151], v[204:207], v[28:31]
	v_mfma_f32_16x16x32_bf16 v[24:27], v[156:159], v[204:207], v[24:27]
	v_mfma_f32_16x16x32_bf16 v[12:15], v[148:151], v[214:217], v[12:15]
	v_mfma_f32_16x16x32_bf16 v[8:11], v[156:159], v[214:217], v[8:11]
	v_mfma_f32_16x16x32_bf16 v[60:63], v[152:155], v[192:195], v[60:63]
	v_mfma_f32_16x16x32_bf16 v[56:59], v[160:163], v[192:195], v[56:59]
	v_mfma_f32_16x16x32_bf16 v[44:47], v[152:155], v[200:203], v[44:47]
	v_mfma_f32_16x16x32_bf16 v[40:43], v[160:163], v[200:203], v[40:43]
	v_mfma_f32_16x16x32_bf16 v[28:31], v[152:155], v[210:213], v[28:31]
	v_mfma_f32_16x16x32_bf16 v[24:27], v[160:163], v[210:213], v[24:27]
	v_mfma_f32_16x16x32_bf16 v[12:15], v[152:155], v[218:221], v[12:15]
	v_mfma_f32_16x16x32_bf16 v[8:11], v[160:163], v[218:221], v[8:11]
	s_setprio 0
	s_setprio 1
	v_mfma_f32_16x16x32_bf16 v[52:55], v[172:175], v[188:191], v[52:55]
	v_mfma_f32_16x16x32_bf16 v[48:51], v[180:183], v[188:191], v[48:51]
	v_mfma_f32_16x16x32_bf16 v[36:39], v[172:175], v[196:199], v[36:39]
	v_mfma_f32_16x16x32_bf16 v[32:35], v[180:183], v[196:199], v[32:35]
	v_mfma_f32_16x16x32_bf16 v[20:23], v[172:175], v[204:207], v[20:23]
	v_mfma_f32_16x16x32_bf16 v[16:19], v[180:183], v[204:207], v[16:19]
	v_mfma_f32_16x16x32_bf16 v[4:7], v[172:175], v[214:217], v[4:7]
	v_mfma_f32_16x16x32_bf16 v[0:3], v[180:183], v[214:217], v[0:3]
	v_mfma_f32_16x16x32_bf16 v[52:55], v[176:179], v[192:195], v[52:55]
	v_mfma_f32_16x16x32_bf16 v[48:51], v[184:187], v[192:195], v[48:51]
	v_mfma_f32_16x16x32_bf16 v[36:39], v[176:179], v[200:203], v[36:39]
	v_mfma_f32_16x16x32_bf16 v[32:35], v[184:187], v[200:203], v[32:35]
	v_mfma_f32_16x16x32_bf16 v[20:23], v[176:179], v[210:213], v[20:23]
	v_mfma_f32_16x16x32_bf16 v[16:19], v[184:187], v[210:213], v[16:19]
	v_mfma_f32_16x16x32_bf16 v[4:7], v[176:179], v[218:221], v[4:7]
	s_barrier
	v_mfma_f32_16x16x32_bf16 v[0:3], v[184:187], v[218:221], v[0:3]
	s_setprio 0
	s_add_i32 vcc_lo, vcc_lo, 2
	s_add_u32 s8, s8, 0x100
	s_addc_u32 s9, s9, 0
	s_add_u32 s96, s96, 0x100
	s_addc_u32 s97, s97, 0
	s_cmp_gt_u32 vcc_lo, 13
	s_cbranch_scc0 .LBB0_462
	s_cmp_eq_u32 s101, 0
	s_cbranch_scc1 .Lp3_war_ok
	s_mov_b64 exec, 1
	s_lshl_b32 s98, s33, 8
	s_add_u32 s98, s46, s98
	s_addc_u32 s99, s47, 0
	v_mov_b32_e32 v176, 0x10000
	s_mov_b32 s73, 0

; #define PG8_STAGE(bufoff, gbase, voff) do { _Pragma("unroll") for (int _i = 0; _i < 2; ++_i) \
;         __builtin_amdgcn_global_load_lds((const unsigned*)((const char*)(gbase) + (voff)[_i]), (PG8_LAS unsigned*)(lds + (bufoff) + ldsw + _i * 8192), 16, 0, 0); } while (0)
; #define PG8_LDA(dst, b, h) do { _Pragma("unroll") for (int m = 0; m < 4; ++m) _Pragma("unroll") for (int k = 0; k < 2; ++k) dst[m][k] = *(const PG8_LAS bf16x8*)(lds + PG8_SA(b, h) + aoff + m * 2048 + k * 1024); } while (0)
; #define PG8_LDB(dst, b, h) do { _Pragma("unroll") for (int n = 0; n < 2; ++n) _Pragma("unroll") for (int k = 0; k < 2; ++k) dst[n][k] = *(const PG8_LAS bf16x8*)(lds + PG8_SB(b, h) + boff + n * 2048 + k * 1024); } while (0)
; #define PG8_MMA(ai, bj, At, Bt) do { __builtin_amdgcn_s_setprio(1); _Pragma("unroll") for (int m = 0; m < 4; ++m) _Pragma("unroll") for (int n = 0; n < 2; ++n) _Pragma("unroll") for (int k = 0; k < 2; ++k) \
;         acc[ai][bj][m][n] = __builtin_amdgcn_mfma_f32_16x16x32_bf16(Bt[n][k], At[m][k], acc[ai][bj][m][n], 0, 0, 0); __builtin_amdgcn_s_setprio(0); } while (0)
; #define PG8_WAIT_V(n) asm volatile("s_waitcnt vmcnt(" #n ")" ::: "memory")
; #define PG8_WAIT_L(n) asm volatile("s_waitcnt lgkmcnt(" #n ")" ::: "memory")
; #define PG8_BAR __builtin_amdgcn_s_barrier()
; #define PG8_SCHED __builtin_amdgcn_sched_barrier(0)
; template <class Epi, class Sched, bool ALIGN_EPI = false, bool SP2 = false>
; __device__ __forceinline__ void gemm_phase(PG8_LAS unsigned char* lds, const Gemm g, const Sched& S, const Epi& E) {
;     ...
;             PG8_LDB(B0, 0, 0); PG8_LDB(B1, 0, 1); PG8_SCHED; PG8_LDA(At, 0, 0); PG8_STAGE(PG8_SA(1, 1), a1 + hstep, voffA);
;             PG8_WAIT_V(8); PG8_WAIT_L(0); PG8_BAR; PG8_MMA(0, 0, At, B0); PG8_MMA(0, 1, At, B1); PG8_BAR; PG8_SCHED;
;             PG8_LDA(At, 0, 1); PG8_STAGE(PG8_SB(0, 0), b2, voffB); PG8_STAGE(PG8_SB(0, 1), b2 + hstep, voffB); PG8_STAGE(PG8_SA(0, 0), a2, voffA);
.LBB0_596:
	ds_read_b128 v[148:151], v167
	ds_read_b128 v[152:155], v167 offset:1024
	ds_read_b128 v[156:159], v167 offset:2048
	ds_read_b128 v[160:163], v167 offset:3072
	ds_read_b128 v[172:175], v168
	ds_read_b128 v[176:179], v168 offset:1024
	ds_read_b128 v[180:183], v168 offset:2048
	ds_read_b128 v[184:187], v168 offset:3072
	s_add_u32 s52, s72, 0xfffc0080
	s_addc_u32 s53, s73, -1
	s_cmp_eq_u32 vcc_hi, 12
	s_cselect_b32 s77, s7, s53
	s_cselect_b32 s76, s9, s52
	s_cselect_b32 s75, s18, vcc_lo
	s_cselect_b32 s74, s65, s67
	v_lshl_add_u64 v[164:165], s[72:73], 0, v[140:141]
	s_add_i32 m0, s81, 0xc000
	ds_read_b128 v[188:191], v169
	ds_read_b128 v[192:195], v169 offset:1024
	ds_read_b128 v[196:199], v169 offset:2048
	ds_read_b128 v[200:203], v169 offset:3072
	ds_read_b128 v[204:207], v169 offset:4096
	ds_read_b128 v[210:213], v169 offset:5120
	ds_read_b128 v[214:217], v169 offset:6144
	ds_read_b128 v[218:221], v169 offset:7168
	global_load_lds_dwordx4 v[164:165], off
	v_lshl_add_u64 v[164:165], s[72:73], 0, v[142:143]
	s_add_i32 m0, s81, 0xe000
	s_nop 0
	global_load_lds_dwordx4 v[164:165], off
	s_waitcnt vmcnt(8)
	s_waitcnt lgkmcnt(0)
	s_barrier
	s_setprio 1
	s_waitcnt lgkmcnt(0)
	v_mfma_f32_16x16x32_bf16 v[124:127], v[148:151], v[188:191], v[124:127]
	v_mfma_f32_16x16x32_bf16 v[120:123], v[156:159], v[188:191], v[120:123]
	v_mfma_f32_16x16x32_bf16 v[108:111], v[148:151], v[196:199], v[108:111]
	v_mfma_f32_16x16x32_bf16 v[104:107], v[156:159], v[196:199], v[104:107]
	v_mfma_f32_16x16x32_bf16 v[92:95], v[148:151], v[204:207], v[92:95]
	v_mfma_f32_16x16x32_bf16 v[88:91], v[156:159], v[204:207], v[88:91]
	v_mfma_f32_16x16x32_bf16 v[76:79], v[148:151], v[214:217], v[76:79]
	v_mfma_f32_16x16x32_bf16 v[72:75], v[156:159], v[214:217], v[72:75]
	v_mfma_f32_16x16x32_bf16 v[124:127], v[152:155], v[192:195], v[124:127]
	v_mfma_f32_16x16x32_bf16 v[120:123], v[160:163], v[192:195], v[120:123]
	v_mfma_f32_16x16x32_bf16 v[108:111], v[152:155], v[200:203], v[108:111]
	v_mfma_f32_16x16x32_bf16 v[104:107], v[160:163], v[200:203], v[104:107]
	v_mfma_f32_16x16x32_bf16 v[92:95], v[152:155], v[210:213], v[92:95]
	v_mfma_f32_16x16x32_bf16 v[88:91], v[160:163], v[210:213], v[88:91]
	v_mfma_f32_16x16x32_bf16 v[76:79], v[152:155], v[218:221], v[76:79]
	v_mfma_f32_16x16x32_bf16 v[72:75], v[160:163], v[218:221], v[72:75]
	s_setprio 0
	s_setprio 1
	v_mfma_f32_16x16x32_bf16 v[116:119], v[172:175], v[188:191], v[116:119]
	v_mfma_f32_16x16x32_bf16 v[112:115], v[180:183], v[188:191], v[112:115]
	v_mfma_f32_16x16x32_bf16 v[100:103], v[172:175], v[196:199], v[100:103]
	v_mfma_f32_16x16x32_bf16 v[96:99], v[180:183], v[196:199], v[96:99]
	v_mfma_f32_16x16x32_bf16 v[84:87], v[172:175], v[204:207], v[84:87]
	v_mfma_f32_16x16x32_bf16 v[80:83], v[180:183], v[204:207], v[80:83]
	v_mfma_f32_16x16x32_bf16 v[68:71], v[172:175], v[214:217], v[68:71]
	v_mfma_f32_16x16x32_bf16 v[64:67], v[180:183], v[214:217], v[64:67]
	v_mfma_f32_16x16x32_bf16 v[116:119], v[176:179], v[192:195], v[116:119]
	v_mfma_f32_16x16x32_bf16 v[112:115], v[184:187], v[192:195], v[112:115]
	v_mfma_f32_16x16x32_bf16 v[100:103], v[176:179], v[200:203], v[100:103]
	v_mfma_f32_16x16x32_bf16 v[96:99], v[184:187], v[200:203], v[96:99]
	v_mfma_f32_16x16x32_bf16 v[84:87], v[176:179], v[210:213], v[84:87]
	v_mfma_f32_16x16x32_bf16 v[80:83], v[184:187], v[210:213], v[80:83]
	v_mfma_f32_16x16x32_bf16 v[68:71], v[176:179], v[218:221], v[68:71]
	s_barrier
	v_mfma_f32_16x16x32_bf16 v[64:67], v[184:187], v[218:221], v[64:67]
	s_setprio 0
	s_add_i32 s52, s88, s61
	v_lshl_add_u64 v[164:165], s[74:75], 0, v[130:131]
	s_mov_b32 m0, s52
	ds_read_b128 v[188:191], v169 offset:16384
	ds_read_b128 v[192:195], v169 offset:17408
	ds_read_b128 v[196:199], v169 offset:18432
	ds_read_b128 v[200:203], v169 offset:19456
	ds_read_b128 v[204:207], v169 offset:20480
	ds_read_b128 v[210:213], v169 offset:21504
	ds_read_b128 v[214:217], v169 offset:22528
	ds_read_b128 v[218:221], v169 offset:23552
	global_load_lds_dwordx4 v[164:165], off
	s_add_i32 m0, s52, 0x2000
	s_add_u32 s52, s74, 0x40000
	v_lshl_add_u64 v[222:223], s[74:75], 0, v[134:135]
	s_addc_u32 s53, s75, 0
	s_add_i32 s78, s89, s61
	global_load_lds_dwordx4 v[222:223], off
	v_lshl_add_u64 v[224:225], s[52:53], 0, v[130:131]
	s_mov_b32 m0, s78
	v_lshl_add_u64 v[226:227], s[76:77], 0, v[132:133]
	global_load_lds_dwordx4 v[224:225], off
	v_lshl_add_u64 v[224:225], s[52:53], 0, v[134:135]
	s_add_i32 m0, s78, 0x2000
	s_nop 0
	global_load_lds_dwordx4 v[224:225], off
	v_lshl_add_u64 v[224:225], s[76:77], 0, v[128:129]
	s_mov_b32 m0, s81
	s_nop 0
	global_load_lds_dwordx4 v[224:225], off
	s_mov_b32 m0, s82
	s_nop 0
	global_load_lds_dwordx4 v[226:227], off
	s_waitcnt vmcnt(8)
	s_waitcnt lgkmcnt(0)
	s_barrier
; #define PG8_STAGE(bufoff, gbase, voff) do { _Pragma("unroll") for (int _i = 0; _i < 2; ++_i) \
;         __builtin_amdgcn_global_load_lds((const unsigned*)((const char*)(gbase) + (voff)[_i]), (PG8_LAS unsigned*)(lds + (bufoff) + ldsw + _i * 8192), 16, 0, 0); } while (0)
; #define PG8_LDA(dst, b, h) do { _Pragma("unroll") for (int m = 0; m < 4; ++m) _Pragma("unroll") for (int k = 0; k < 2; ++k) dst[m][k] = *(const PG8_LAS bf16x8*)(lds + PG8_SA(b, h) + aoff + m * 2048 + k * 1024); } while (0)
; #define PG8_LDB(dst, b, h) do { _Pragma("unroll") for (int n = 0; n < 2; ++n) _Pragma("unroll") for (int k = 0; k < 2; ++k) dst[n][k] = *(const PG8_LAS bf16x8*)(lds + PG8_SB(b, h) + boff + n * 2048 + k * 1024); } while (0)
; #define PG8_MMA(ai, bj, At, Bt) do { __builtin_amdgcn_s_setprio(1); _Pragma("unroll") for (int m = 0; m < 4; ++m) _Pragma("unroll") for (int n = 0; n < 2; ++n) _Pragma("unroll") for (int k = 0; k < 2; ++k) \
;         acc[ai][bj][m][n] = __builtin_amdgcn_mfma_f32_16x16x32_bf16(Bt[n][k], At[m][k], acc[ai][bj][m][n], 0, 0, 0); __builtin_amdgcn_s_setprio(0); } while (0)
; #define PG8_WAIT_V(n) asm volatile("s_waitcnt vmcnt(" #n ")" ::: "memory")
; #define PG8_WAIT_L(n) asm volatile("s_waitcnt lgkmcnt(" #n ")" ::: "memory")
; #define PG8_BAR __builtin_amdgcn_s_barrier()
; #define PG8_SCHED __builtin_amdgcn_sched_barrier(0)
; template <class Epi, class Sched, bool ALIGN_EPI = false, bool SP2 = false>
; __device__ __forceinline__ void gemm_phase(PG8_LAS unsigned char* lds, const Gemm g, const Sched& S, const Epi& E) {
;     ...
;             PG8_WAIT_V(8); PG8_WAIT_L(0); PG8_BAR; PG8_MMA(1, 0, At, B0); PG8_MMA(1, 1, At, B1); PG8_BAR; PG8_SCHED;
;             PG8_LDB(B0, 1, 0); PG8_LDB(B1, 1, 1); PG8_SCHED; PG8_LDA(At, 1, 0); PG8_STAGE(PG8_SA(0, 1), a2 + hstep, voffA);
;             PG8_WAIT_V(8); PG8_WAIT_L(0); PG8_BAR; PG8_MMA(0, 0, At, B0); PG8_MMA(0, 1, At, B1); PG8_BAR; PG8_SCHED;
	s_setprio 1
	s_waitcnt lgkmcnt(0)
	v_mfma_f32_16x16x32_bf16 v[60:63], v[148:151], v[188:191], v[60:63]
	v_mfma_f32_16x16x32_bf16 v[56:59], v[156:159], v[188:191], v[56:59]
	v_mfma_f32_16x16x32_bf16 v[44:47], v[148:151], v[196:199], v[44:47]
	v_mfma_f32_16x16x32_bf16 v[40:43], v[156:159], v[196:199], v[40:43]
	v_mfma_f32_16x16x32_bf16 v[28:31], v[148:151], v[204:207], v[28:31]
	v_mfma_f32_16x16x32_bf16 v[24:27], v[156:159], v[204:207], v[24:27]
	v_mfma_f32_16x16x32_bf16 v[12:15], v[148:151], v[214:217], v[12:15]
	v_mfma_f32_16x16x32_bf16 v[8:11], v[156:159], v[214:217], v[8:11]
	v_mfma_f32_16x16x32_bf16 v[60:63], v[152:155], v[192:195], v[60:63]
	v_mfma_f32_16x16x32_bf16 v[56:59], v[160:163], v[192:195], v[56:59]
	v_mfma_f32_16x16x32_bf16 v[44:47], v[152:155], v[200:203], v[44:47]
	v_mfma_f32_16x16x32_bf16 v[40:43], v[160:163], v[200:203], v[40:43]
	v_mfma_f32_16x16x32_bf16 v[28:31], v[152:155], v[210:213], v[28:31]
	v_mfma_f32_16x16x32_bf16 v[24:27], v[160:163], v[210:213], v[24:27]
	v_mfma_f32_16x16x32_bf16 v[12:15], v[152:155], v[218:221], v[12:15]
	v_mfma_f32_16x16x32_bf16 v[8:11], v[160:163], v[218:221], v[8:11]
	s_setprio 0
	s_setprio 1
	v_mfma_f32_16x16x32_bf16 v[52:55], v[172:175], v[188:191], v[52:55]
	v_mfma_f32_16x16x32_bf16 v[48:51], v[180:183], v[188:191], v[48:51]
	v_mfma_f32_16x16x32_bf16 v[36:39], v[172:175], v[196:199], v[36:39]
	v_mfma_f32_16x16x32_bf16 v[32:35], v[180:183], v[196:199], v[32:35]
	v_mfma_f32_16x16x32_bf16 v[20:23], v[172:175], v[204:207], v[20:23]
	v_mfma_f32_16x16x32_bf16 v[16:19], v[180:183], v[204:207], v[16:19]
	v_mfma_f32_16x16x32_bf16 v[4:7], v[172:175], v[214:217], v[4:7]
	v_mfma_f32_16x16x32_bf16 v[0:3], v[180:183], v[214:217], v[0:3]
	v_mfma_f32_16x16x32_bf16 v[52:55], v[176:179], v[192:195], v[52:55]
	v_mfma_f32_16x16x32_bf16 v[48:51], v[184:187], v[192:195], v[48:51]
	v_mfma_f32_16x16x32_bf16 v[36:39], v[176:179], v[200:203], v[36:39]
	v_mfma_f32_16x16x32_bf16 v[32:35], v[184:187], v[200:203], v[32:35]
	v_mfma_f32_16x16x32_bf16 v[20:23], v[176:179], v[210:213], v[20:23]
	v_mfma_f32_16x16x32_bf16 v[16:19], v[184:187], v[210:213], v[16:19]
	v_mfma_f32_16x16x32_bf16 v[4:7], v[176:179], v[218:221], v[4:7]
	s_barrier
	v_mfma_f32_16x16x32_bf16 v[0:3], v[184:187], v[218:221], v[0:3]
	s_setprio 0
	s_add_i32 s78, 0, 0x18000
	v_add_u32_e32 v136, s78, v166
	s_add_i32 s26, 0, 0x1c000
	ds_read_b128 v[148:151], v136
	ds_read_b128 v[152:155], v136 offset:1024
	ds_read_b128 v[156:159], v136 offset:2048
	ds_read_b128 v[160:163], v136 offset:3072
	v_add_u32_e32 v136, s26, v166
	ds_read_b128 v[172:175], v136
	ds_read_b128 v[176:179], v136 offset:1024
	ds_read_b128 v[180:183], v136 offset:2048
	ds_read_b128 v[184:187], v136 offset:3072
	s_add_u32 s52, s76, 0x40000
	s_addc_u32 s53, s77, 0
	s_mov_b32 m0, s83
	v_lshl_add_u64 v[228:229], s[52:53], 0, v[128:129]
	ds_read_b128 v[188:191], v169 offset:32768
	ds_read_b128 v[192:195], v169 offset:33792
	ds_read_b128 v[196:199], v169 offset:34816
	ds_read_b128 v[200:203], v169 offset:35840
	ds_read_b128 v[204:207], v169 offset:36864
	ds_read_b128 v[210:213], v169 offset:37888
	ds_read_b128 v[214:217], v169 offset:38912
	ds_read_b128 v[218:221], v169 offset:39936
	global_load_lds_dwordx4 v[228:229], off
	v_lshl_add_u64 v[228:229], s[52:53], 0, v[132:133]
	s_mov_b32 m0, s84
	s_nop 0
	global_load_lds_dwordx4 v[228:229], off
	s_waitcnt vmcnt(8)
	s_waitcnt lgkmcnt(0)
	s_barrier
	s_setprio 1
	s_waitcnt lgkmcnt(0)
	v_mfma_f32_16x16x32_bf16 v[124:127], v[148:151], v[188:191], v[124:127]
	v_mfma_f32_16x16x32_bf16 v[120:123], v[156:159], v[188:191], v[120:123]
	v_mfma_f32_16x16x32_bf16 v[108:111], v[148:151], v[196:199], v[108:111]
	v_mfma_f32_16x16x32_bf16 v[104:107], v[156:159], v[196:199], v[104:107]
	v_mfma_f32_16x16x32_bf16 v[92:95], v[148:151], v[204:207], v[92:95]
	v_mfma_f32_16x16x32_bf16 v[88:91], v[156:159], v[204:207], v[88:91]
	v_mfma_f32_16x16x32_bf16 v[76:79], v[148:151], v[214:217], v[76:79]
	v_mfma_f32_16x16x32_bf16 v[72:75], v[156:159], v[214:217], v[72:75]
	v_mfma_f32_16x16x32_bf16 v[124:127], v[152:155], v[192:195], v[124:127]
	v_mfma_f32_16x16x32_bf16 v[120:123], v[160:163], v[192:195], v[120:123]
	v_mfma_f32_16x16x32_bf16 v[108:111], v[152:155], v[200:203], v[108:111]
	v_mfma_f32_16x16x32_bf16 v[104:107], v[160:163], v[200:203], v[104:107]
	v_mfma_f32_16x16x32_bf16 v[92:95], v[152:155], v[210:213], v[92:95]
	v_mfma_f32_16x16x32_bf16 v[88:91], v[160:163], v[210:213], v[88:91]
	v_mfma_f32_16x16x32_bf16 v[76:79], v[152:155], v[218:221], v[76:79]
	v_mfma_f32_16x16x32_bf16 v[72:75], v[160:163], v[218:221], v[72:75]
	s_setprio 0
	s_setprio 1
	v_mfma_f32_16x16x32_bf16 v[116:119], v[172:175], v[188:191], v[116:119]
	v_mfma_f32_16x16x32_bf16 v[112:115], v[180:183], v[188:191], v[112:115]
	v_mfma_f32_16x16x32_bf16 v[100:103], v[172:175], v[196:199], v[100:103]
	v_mfma_f32_16x16x32_bf16 v[96:99], v[180:183], v[196:199], v[96:99]
	v_mfma_f32_16x16x32_bf16 v[84:87], v[172:175], v[204:207], v[84:87]
	v_mfma_f32_16x16x32_bf16 v[80:83], v[180:183], v[204:207], v[80:83]
	v_mfma_f32_16x16x32_bf16 v[68:71], v[172:175], v[214:217], v[68:71]
	v_mfma_f32_16x16x32_bf16 v[64:67], v[180:183], v[214:217], v[64:67]
	v_mfma_f32_16x16x32_bf16 v[116:119], v[176:179], v[192:195], v[116:119]
	v_mfma_f32_16x16x32_bf16 v[112:115], v[184:187], v[192:195], v[112:115]
	v_mfma_f32_16x16x32_bf16 v[100:103], v[176:179], v[200:203], v[100:103]
	v_mfma_f32_16x16x32_bf16 v[96:99], v[184:187], v[200:203], v[96:99]
	v_mfma_f32_16x16x32_bf16 v[84:87], v[176:179], v[210:213], v[84:87]
	v_mfma_f32_16x16x32_bf16 v[80:83], v[184:187], v[210:213], v[80:83]
	v_mfma_f32_16x16x32_bf16 v[68:71], v[176:179], v[218:221], v[68:71]
	s_barrier
; #define PG8_STAGE(bufoff, gbase, voff) do { _Pragma("unroll") for (int _i = 0; _i < 2; ++_i) \
;         __builtin_amdgcn_global_load_lds((const unsigned*)((const char*)(gbase) + (voff)[_i]), (PG8_LAS unsigned*)(lds + (bufoff) + ldsw + _i * 8192), 16, 0, 0); } while (0)
; #define PG8_LDA(dst, b, h) do { _Pragma("unroll") for (int m = 0; m < 4; ++m) _Pragma("unroll") for (int k = 0; k < 2; ++k) dst[m][k] = *(const PG8_LAS bf16x8*)(lds + PG8_SA(b, h) + aoff + m * 2048 + k * 1024); } while (0)
; #define PG8_MMA(ai, bj, At, Bt) do { __builtin_amdgcn_s_setprio(1); _Pragma("unroll") for (int m = 0; m < 4; ++m) _Pragma("unroll") for (int n = 0; n < 2; ++n) _Pragma("unroll") for (int k = 0; k < 2; ++k) \
;         acc[ai][bj][m][n] = __builtin_amdgcn_mfma_f32_16x16x32_bf16(Bt[n][k], At[m][k], acc[ai][bj][m][n], 0, 0, 0); __builtin_amdgcn_s_setprio(0); } while (0)
; #define PG8_WAIT_V(n) asm volatile("s_waitcnt vmcnt(" #n ")" ::: "memory")
; #define PG8_WAIT_L(n) asm volatile("s_waitcnt lgkmcnt(" #n ")" ::: "memory")
; #define PG8_BAR __builtin_amdgcn_s_barrier()
; #define PG8_SCHED __builtin_amdgcn_sched_barrier(0)
; template <class Epi, class Sched, bool ALIGN_EPI = false, bool SP2 = false>
; __device__ __forceinline__ void gemm_phase(PG8_LAS unsigned char* lds, const Gemm g, const Sched& S, const Epi& E) {
;     ...
;             PG8_WAIT_V(8); PG8_WAIT_L(0); PG8_BAR; PG8_MMA(0, 0, At, B0); PG8_MMA(0, 1, At, B1); PG8_BAR; PG8_SCHED;
;             PG8_LDA(At, 1, 1); PG8_STAGE(PG8_SB(1, 0), b3, voffB); PG8_STAGE(PG8_SB(1, 1), b3 + hstep, voffB); PG8_STAGE(PG8_SA(1, 0), a3, voffA);
;             PG8_WAIT_V(8); PG8_WAIT_L(0); PG8_BAR; PG8_MMA(1, 0, At, B0); PG8_MMA(1, 1, At, B1); PG8_BAR; PG8_SCHED;
;     ...
;         if constexpr (ALIGN_EPI) { if (wr == 0) PG8_BAR; }
	v_mfma_f32_16x16x32_bf16 v[64:67], v[184:187], v[218:221], v[64:67]
	s_setprio 0
	s_add_i32 s27, s78, s61
	v_lshl_add_u64 v[164:165], v[164:165], 0, s[34:35]
	s_mov_b32 m0, s27
	ds_read_b128 v[188:191], v169 offset:49152
	ds_read_b128 v[192:195], v169 offset:50176
	ds_read_b128 v[196:199], v169 offset:51200
	ds_read_b128 v[200:203], v169 offset:52224
	ds_read_b128 v[204:207], v169 offset:53248
	ds_read_b128 v[210:213], v169 offset:54272
	ds_read_b128 v[214:217], v169 offset:55296
	ds_read_b128 v[218:221], v169 offset:56320
	global_load_lds_dwordx4 v[164:165], off
	s_add_i32 m0, s27, 0x2000
	s_add_u32 s52, s74, 0x40080
	v_lshl_add_u64 v[164:165], v[222:223], 0, s[34:35]
	s_addc_u32 s53, s75, 0
	s_add_i32 s26, s26, s61
	global_load_lds_dwordx4 v[164:165], off
	v_lshl_add_u64 v[164:165], s[52:53], 0, v[130:131]
	s_mov_b32 m0, s26
	s_nop 0
	global_load_lds_dwordx4 v[164:165], off
	v_lshl_add_u64 v[164:165], s[52:53], 0, v[134:135]
	s_add_i32 m0, s26, 0x2000
	s_nop 0
	global_load_lds_dwordx4 v[164:165], off
	v_lshl_add_u64 v[164:165], v[224:225], 0, s[34:35]
	s_mov_b32 m0, s86
	s_nop 0
	global_load_lds_dwordx4 v[164:165], off
	v_lshl_add_u64 v[164:165], v[226:227], 0, s[34:35]
	s_mov_b32 m0, s87
	s_nop 0
	global_load_lds_dwordx4 v[164:165], off
	s_waitcnt vmcnt(8)
	s_waitcnt lgkmcnt(0)
	s_barrier
	s_setprio 1
	s_waitcnt lgkmcnt(0)
	v_mfma_f32_16x16x32_bf16 v[60:63], v[148:151], v[188:191], v[60:63]
	v_mfma_f32_16x16x32_bf16 v[56:59], v[156:159], v[188:191], v[56:59]
	v_mfma_f32_16x16x32_bf16 v[44:47], v[148:151], v[196:199], v[44:47]
	v_mfma_f32_16x16x32_bf16 v[40:43], v[156:159], v[196:199], v[40:43]
	v_mfma_f32_16x16x32_bf16 v[28:31], v[148:151], v[204:207], v[28:31]
	v_mfma_f32_16x16x32_bf16 v[24:27], v[156:159], v[204:207], v[24:27]
	v_mfma_f32_16x16x32_bf16 v[12:15], v[148:151], v[214:217], v[12:15]
	v_mfma_f32_16x16x32_bf16 v[8:11], v[156:159], v[214:217], v[8:11]
	v_mfma_f32_16x16x32_bf16 v[60:63], v[152:155], v[192:195], v[60:63]
	v_mfma_f32_16x16x32_bf16 v[56:59], v[160:163], v[192:195], v[56:59]
	v_mfma_f32_16x16x32_bf16 v[44:47], v[152:155], v[200:203], v[44:47]
	v_mfma_f32_16x16x32_bf16 v[40:43], v[160:163], v[200:203], v[40:43]
	v_mfma_f32_16x16x32_bf16 v[28:31], v[152:155], v[210:213], v[28:31]
	v_mfma_f32_16x16x32_bf16 v[24:27], v[160:163], v[210:213], v[24:27]
	v_mfma_f32_16x16x32_bf16 v[12:15], v[152:155], v[218:221], v[12:15]
	v_mfma_f32_16x16x32_bf16 v[8:11], v[160:163], v[218:221], v[8:11]
	s_setprio 0
	s_setprio 1
	v_mfma_f32_16x16x32_bf16 v[52:55], v[172:175], v[188:191], v[52:55]
	v_mfma_f32_16x16x32_bf16 v[48:51], v[180:183], v[188:191], v[48:51]
	v_mfma_f32_16x16x32_bf16 v[36:39], v[172:175], v[196:199], v[36:39]
	v_mfma_f32_16x16x32_bf16 v[32:35], v[180:183], v[196:199], v[32:35]
	v_mfma_f32_16x16x32_bf16 v[20:23], v[172:175], v[204:207], v[20:23]
	v_mfma_f32_16x16x32_bf16 v[16:19], v[180:183], v[204:207], v[16:19]
	v_mfma_f32_16x16x32_bf16 v[4:7], v[172:175], v[214:217], v[4:7]
	v_mfma_f32_16x16x32_bf16 v[0:3], v[180:183], v[214:217], v[0:3]
	v_mfma_f32_16x16x32_bf16 v[52:55], v[176:179], v[192:195], v[52:55]
	v_mfma_f32_16x16x32_bf16 v[48:51], v[184:187], v[192:195], v[48:51]
	v_mfma_f32_16x16x32_bf16 v[36:39], v[176:179], v[200:203], v[36:39]
	v_mfma_f32_16x16x32_bf16 v[32:35], v[184:187], v[200:203], v[32:35]
	v_mfma_f32_16x16x32_bf16 v[20:23], v[176:179], v[210:213], v[20:23]
	v_mfma_f32_16x16x32_bf16 v[16:19], v[184:187], v[210:213], v[16:19]
	v_mfma_f32_16x16x32_bf16 v[4:7], v[176:179], v[218:221], v[4:7]
	s_barrier
	v_mfma_f32_16x16x32_bf16 v[0:3], v[184:187], v[218:221], v[0:3]
	s_setprio 0
	s_add_i32 vcc_hi, vcc_hi, 2
	s_add_u32 s72, s72, 0x100
	s_addc_u32 s73, s73, 0
	s_add_u32 s67, s67, 0x100
	s_addc_u32 vcc_lo, vcc_lo, 0
	s_cmp_gt_u32 vcc_hi, 13
	s_cbranch_scc0 .LBB0_596
	s_and_b64 vcc, exec, s[36:37]
	s_cbranch_vccz .LBB0_599
	s_barrier

; #define PG8_STAGE(bufoff, gbase, voff) do { _Pragma("unroll") for (int _i = 0; _i < 2; ++_i) \
;         __builtin_amdgcn_global_load_lds((const unsigned*)((const char*)(gbase) + (voff)[_i]), (PG8_LAS unsigned*)(lds + (bufoff) + ldsw + _i * 8192), 16, 0, 0); } while (0)
; #define PG8_LDA(dst, b, h) do { _Pragma("unroll") for (int m = 0; m < 4; ++m) _Pragma("unroll") for (int k = 0; k < 2; ++k) dst[m][k] = *(const PG8_LAS bf16x8*)(lds + PG8_SA(b, h) + aoff + m * 2048 + k * 1024); } while (0)
; #define PG8_LDB(dst, b, h) do { _Pragma("unroll") for (int n = 0; n < 2; ++n) _Pragma("unroll") for (int k = 0; k < 2; ++k) dst[n][k] = *(const PG8_LAS bf16x8*)(lds + PG8_SB(b, h) + boff + n * 2048 + k * 1024); } while (0)
; #define PG8_MMA(ai, bj, At, Bt) do { __builtin_amdgcn_s_setprio(1); _Pragma("unroll") for (int m = 0; m < 4; ++m) _Pragma("unroll") for (int n = 0; n < 2; ++n) _Pragma("unroll") for (int k = 0; k < 2; ++k) \
;         acc[ai][bj][m][n] = __builtin_amdgcn_mfma_f32_16x16x32_bf16(Bt[n][k], At[m][k], acc[ai][bj][m][n], 0, 0, 0); __builtin_amdgcn_s_setprio(0); } while (0)
; #define PG8_WAIT_V(n) asm volatile("s_waitcnt vmcnt(" #n ")" ::: "memory")
; #define PG8_BAR __builtin_amdgcn_s_barrier()
; template <class Epi, class Sched, bool ALIGN_EPI = false, bool SP2 = false>
; __device__ __forceinline__ void gemm_phase(PG8_LAS unsigned char* lds, const Gemm g, const Sched& S, const Epi& E) {
;     ...
;         for (int t = 0; t < nt; t += 2) {
;             const bool last = (t == nt - 2);
;             const char* a1 = cA + (size_t)(t + 1) * kstep;
;             const char* a2 = last ? nA : cA + (size_t)(t + 2) * kstep; const char* b2 = last ? nB : cB + (size_t)(t + 2) * kstep;
;             const char* a3 = a2 + kstep; const char* b3 = b2 + kstep;
;             if (last && has_next) S.a_ready(nxt);
;             if constexpr (SP2) {
;             PG8_LDB(B0, 0, 0); PG8_LDB(B1, 0, 1); PG8_SCHED; PG8_LDA(At, 0, 0); PG8_STAGE(PG8_SA(1, 1), a1 + hstep, voffA);
;             PG8_WAIT_V(8); PG8_WAIT_L(0); PG8_BAR; PG8_MMA(0, 0, At, B0); PG8_MMA(0, 1, At, B1); PG8_BAR; PG8_SCHED;
;             PG8_LDA(At, 0, 1); PG8_STAGE(PG8_SB(0, 0), b2, voffB); PG8_STAGE(PG8_SB(0, 1), b2 + hstep, voffB); PG8_STAGE(PG8_SA(0, 0), a2, voffA);
;             PG8_WAIT_V(8); PG8_WAIT_L(0); PG8_BAR; PG8_MMA(1, 0, At, B0); PG8_MMA(1, 1, At, B1); PG8_BAR; PG8_SCHED;
.LBB0_1009:
	v_add_u32_e32 v153, s63, v151
	ds_read_b128 v[154:157], v153
	ds_read_b128 v[158:161], v153 offset:1024
	ds_read_b128 v[162:165], v153 offset:2048
	ds_read_b128 v[166:169], v153 offset:3072
	v_add_u32_e32 v153, s64, v151
	s_add_u32 s26, s12, s24
	ds_read_b128 v[170:173], v153
	ds_read_b128 v[174:177], v153 offset:1024
	ds_read_b128 v[178:181], v153 offset:2048
	ds_read_b128 v[182:185], v153 offset:3072
	s_addc_u32 s27, s13, s25
	s_add_u32 s26, s26, 0x100
	s_addc_u32 s27, s27, 0
	s_add_u32 s52, s66, s24
	s_addc_u32 s53, s67, s25
	s_cmpk_eq_i32 s24, 0x700
	s_cselect_b32 s29, s19, s27
	s_cselect_b32 s28, s68, s26
	s_cselect_b32 s27, s17, s53
	s_cselect_b32 s26, s69, s52
	v_lshl_add_u64 v[206:207], v[144:145], 0, s[24:25]
	s_add_i32 m0, s39, 0xc000
	ds_read_b128 v[186:189], v152
	ds_read_b128 v[190:193], v152 offset:1024
	ds_read_b128 v[194:197], v152 offset:2048
	ds_read_b128 v[198:201], v152 offset:3072
	ds_read_b128 v[202:205], v152 offset:4096
	ds_read_b128 v[210:213], v152 offset:5120
	ds_read_b128 v[214:217], v152 offset:6144
	ds_read_b128 v[218:221], v152 offset:7168
	global_load_lds_dwordx4 v[206:207], off
	v_lshl_add_u64 v[206:207], v[146:147], 0, s[24:25]
	s_add_i32 m0, s39, 0xe000
	s_nop 0
	global_load_lds_dwordx4 v[206:207], off
	s_waitcnt vmcnt(8)
	s_waitcnt lgkmcnt(0)
	s_barrier
	s_setprio 1
	s_waitcnt lgkmcnt(0)
	v_mfma_f32_16x16x32_bf16 v[124:127], v[154:157], v[186:189], v[124:127]
	v_mfma_f32_16x16x32_bf16 v[120:123], v[162:165], v[186:189], v[120:123]
	v_mfma_f32_16x16x32_bf16 v[108:111], v[154:157], v[194:197], v[108:111]
	v_mfma_f32_16x16x32_bf16 v[104:107], v[162:165], v[194:197], v[104:107]
	v_mfma_f32_16x16x32_bf16 v[92:95], v[154:157], v[202:205], v[92:95]
	v_mfma_f32_16x16x32_bf16 v[88:91], v[162:165], v[202:205], v[88:91]
	v_mfma_f32_16x16x32_bf16 v[76:79], v[154:157], v[214:217], v[76:79]
	v_mfma_f32_16x16x32_bf16 v[72:75], v[162:165], v[214:217], v[72:75]
	v_mfma_f32_16x16x32_bf16 v[124:127], v[158:161], v[190:193], v[124:127]
	v_mfma_f32_16x16x32_bf16 v[120:123], v[166:169], v[190:193], v[120:123]
	v_mfma_f32_16x16x32_bf16 v[108:111], v[158:161], v[198:201], v[108:111]
	v_mfma_f32_16x16x32_bf16 v[104:107], v[166:169], v[198:201], v[104:107]
	v_mfma_f32_16x16x32_bf16 v[92:95], v[158:161], v[210:213], v[92:95]
	v_mfma_f32_16x16x32_bf16 v[88:91], v[166:169], v[210:213], v[88:91]
	v_mfma_f32_16x16x32_bf16 v[76:79], v[158:161], v[218:221], v[76:79]
	v_mfma_f32_16x16x32_bf16 v[72:75], v[166:169], v[218:221], v[72:75]
	s_setprio 0
	s_setprio 1
	v_mfma_f32_16x16x32_bf16 v[116:119], v[170:173], v[186:189], v[116:119]
	v_mfma_f32_16x16x32_bf16 v[112:115], v[178:181], v[186:189], v[112:115]
	v_mfma_f32_16x16x32_bf16 v[100:103], v[170:173], v[194:197], v[100:103]
	v_mfma_f32_16x16x32_bf16 v[96:99], v[178:181], v[194:197], v[96:99]
	v_mfma_f32_16x16x32_bf16 v[84:87], v[170:173], v[202:205], v[84:87]
	v_mfma_f32_16x16x32_bf16 v[80:83], v[178:181], v[202:205], v[80:83]
	v_mfma_f32_16x16x32_bf16 v[68:71], v[170:173], v[214:217], v[68:71]
	v_mfma_f32_16x16x32_bf16 v[64:67], v[178:181], v[214:217], v[64:67]
	v_mfma_f32_16x16x32_bf16 v[116:119], v[174:177], v[190:193], v[116:119]
	v_mfma_f32_16x16x32_bf16 v[112:115], v[182:185], v[190:193], v[112:115]
	v_mfma_f32_16x16x32_bf16 v[100:103], v[174:177], v[198:201], v[100:103]
	v_mfma_f32_16x16x32_bf16 v[96:99], v[182:185], v[198:201], v[96:99]
	v_mfma_f32_16x16x32_bf16 v[84:87], v[174:177], v[210:213], v[84:87]
	v_mfma_f32_16x16x32_bf16 v[80:83], v[182:185], v[210:213], v[80:83]
	v_mfma_f32_16x16x32_bf16 v[68:71], v[174:177], v[218:221], v[68:71]
	s_barrier
	v_mfma_f32_16x16x32_bf16 v[64:67], v[182:185], v[218:221], v[64:67]
	s_setprio 0
	s_add_i32 s52, s63, s38
	v_lshl_add_u64 v[206:207], s[26:27], 0, v[130:131]
	s_mov_b32 m0, s52
	ds_read_b128 v[186:189], v152 offset:16384
	ds_read_b128 v[190:193], v152 offset:17408
	ds_read_b128 v[194:197], v152 offset:18432
	ds_read_b128 v[198:201], v152 offset:19456
	ds_read_b128 v[202:205], v152 offset:20480
	ds_read_b128 v[210:213], v152 offset:21504
	ds_read_b128 v[214:217], v152 offset:22528
	ds_read_b128 v[218:221], v152 offset:23552
	global_load_lds_dwordx4 v[206:207], off
	s_add_i32 m0, s52, 0x2000
	s_add_u32 s52, s26, 0x40000
	v_lshl_add_u64 v[222:223], s[26:27], 0, v[134:135]
	s_addc_u32 s53, s27, 0
	s_add_i32 s71, s64, s38
	global_load_lds_dwordx4 v[222:223], off
	v_lshl_add_u64 v[224:225], s[52:53], 0, v[130:131]
	s_mov_b32 m0, s71
	v_lshl_add_u64 v[226:227], s[28:29], 0, v[132:133]
	global_load_lds_dwordx4 v[224:225], off
	v_lshl_add_u64 v[224:225], s[52:53], 0, v[134:135]
	s_add_i32 m0, s71, 0x2000
	s_nop 0
	global_load_lds_dwordx4 v[224:225], off
	v_lshl_add_u64 v[224:225], s[28:29], 0, v[128:129]
	s_mov_b32 m0, s39
	s_nop 0
	global_load_lds_dwordx4 v[224:225], off
	s_mov_b32 m0, s40
	s_nop 0
	global_load_lds_dwordx4 v[226:227], off
	s_waitcnt vmcnt(8)
	s_waitcnt lgkmcnt(0)
	s_barrier
; #define PG8_STAGE(bufoff, gbase, voff) do { _Pragma("unroll") for (int _i = 0; _i < 2; ++_i) \
;         __builtin_amdgcn_global_load_lds((const unsigned*)((const char*)(gbase) + (voff)[_i]), (PG8_LAS unsigned*)(lds + (bufoff) + ldsw + _i * 8192), 16, 0, 0); } while (0)
; #define PG8_LDA(dst, b, h) do { _Pragma("unroll") for (int m = 0; m < 4; ++m) _Pragma("unroll") for (int k = 0; k < 2; ++k) dst[m][k] = *(const PG8_LAS bf16x8*)(lds + PG8_SA(b, h) + aoff + m * 2048 + k * 1024); } while (0)
; #define PG8_LDB(dst, b, h) do { _Pragma("unroll") for (int n = 0; n < 2; ++n) _Pragma("unroll") for (int k = 0; k < 2; ++k) dst[n][k] = *(const PG8_LAS bf16x8*)(lds + PG8_SB(b, h) + boff + n * 2048 + k * 1024); } while (0)
; #define PG8_MMA(ai, bj, At, Bt) do { __builtin_amdgcn_s_setprio(1); _Pragma("unroll") for (int m = 0; m < 4; ++m) _Pragma("unroll") for (int n = 0; n < 2; ++n) _Pragma("unroll") for (int k = 0; k < 2; ++k) \
;         acc[ai][bj][m][n] = __builtin_amdgcn_mfma_f32_16x16x32_bf16(Bt[n][k], At[m][k], acc[ai][bj][m][n], 0, 0, 0); __builtin_amdgcn_s_setprio(0); } while (0)
; #define PG8_WAIT_V(n) asm volatile("s_waitcnt vmcnt(" #n ")" ::: "memory")
; #define PG8_WAIT_L(n) asm volatile("s_waitcnt lgkmcnt(" #n ")" ::: "memory")
; #define PG8_BAR __builtin_amdgcn_s_barrier()
; #define PG8_SCHED __builtin_amdgcn_sched_barrier(0)
; template <class Epi, class Sched, bool ALIGN_EPI = false, bool SP2 = false>
; __device__ __forceinline__ void gemm_phase(PG8_LAS unsigned char* lds, const Gemm g, const Sched& S, const Epi& E) {
;     ...
;             PG8_WAIT_V(8); PG8_WAIT_L(0); PG8_BAR; PG8_MMA(1, 0, At, B0); PG8_MMA(1, 1, At, B1); PG8_BAR; PG8_SCHED;
;             PG8_LDB(B0, 1, 0); PG8_LDB(B1, 1, 1); PG8_SCHED; PG8_LDA(At, 1, 0); PG8_STAGE(PG8_SA(0, 1), a2 + hstep, voffA);
;             PG8_WAIT_V(8); PG8_WAIT_L(0); PG8_BAR; PG8_MMA(0, 0, At, B0); PG8_MMA(0, 1, At, B1); PG8_BAR; PG8_SCHED;
;             PG8_LDA(At, 1, 1); PG8_STAGE(PG8_SB(1, 0), b3, voffB); PG8_STAGE(PG8_SB(1, 1), b3 + hstep, voffB); PG8_STAGE(PG8_SA(1, 0), a3, voffA);
	s_setprio 1
	s_waitcnt lgkmcnt(0)
	v_mfma_f32_16x16x32_bf16 v[60:63], v[154:157], v[186:189], v[60:63]
	v_mfma_f32_16x16x32_bf16 v[56:59], v[162:165], v[186:189], v[56:59]
	v_mfma_f32_16x16x32_bf16 v[44:47], v[154:157], v[194:197], v[44:47]
	v_mfma_f32_16x16x32_bf16 v[40:43], v[162:165], v[194:197], v[40:43]
	v_mfma_f32_16x16x32_bf16 v[28:31], v[154:157], v[202:205], v[28:31]
	v_mfma_f32_16x16x32_bf16 v[24:27], v[162:165], v[202:205], v[24:27]
	v_mfma_f32_16x16x32_bf16 v[12:15], v[154:157], v[214:217], v[12:15]
	v_mfma_f32_16x16x32_bf16 v[8:11], v[162:165], v[214:217], v[8:11]
	v_mfma_f32_16x16x32_bf16 v[60:63], v[158:161], v[190:193], v[60:63]
	v_mfma_f32_16x16x32_bf16 v[56:59], v[166:169], v[190:193], v[56:59]
	v_mfma_f32_16x16x32_bf16 v[44:47], v[158:161], v[198:201], v[44:47]
	v_mfma_f32_16x16x32_bf16 v[40:43], v[166:169], v[198:201], v[40:43]
	v_mfma_f32_16x16x32_bf16 v[28:31], v[158:161], v[210:213], v[28:31]
	v_mfma_f32_16x16x32_bf16 v[24:27], v[166:169], v[210:213], v[24:27]
	v_mfma_f32_16x16x32_bf16 v[12:15], v[158:161], v[218:221], v[12:15]
	v_mfma_f32_16x16x32_bf16 v[8:11], v[166:169], v[218:221], v[8:11]
	s_setprio 0
	s_setprio 1
	v_mfma_f32_16x16x32_bf16 v[52:55], v[170:173], v[186:189], v[52:55]
	v_mfma_f32_16x16x32_bf16 v[48:51], v[178:181], v[186:189], v[48:51]
	v_mfma_f32_16x16x32_bf16 v[36:39], v[170:173], v[194:197], v[36:39]
	v_mfma_f32_16x16x32_bf16 v[32:35], v[178:181], v[194:197], v[32:35]
	v_mfma_f32_16x16x32_bf16 v[20:23], v[170:173], v[202:205], v[20:23]
	v_mfma_f32_16x16x32_bf16 v[16:19], v[178:181], v[202:205], v[16:19]
	v_mfma_f32_16x16x32_bf16 v[4:7], v[170:173], v[214:217], v[4:7]
	v_mfma_f32_16x16x32_bf16 v[0:3], v[178:181], v[214:217], v[0:3]
	v_mfma_f32_16x16x32_bf16 v[52:55], v[174:177], v[190:193], v[52:55]
	v_mfma_f32_16x16x32_bf16 v[48:51], v[182:185], v[190:193], v[48:51]
	v_mfma_f32_16x16x32_bf16 v[36:39], v[174:177], v[198:201], v[36:39]
	v_mfma_f32_16x16x32_bf16 v[32:35], v[182:185], v[198:201], v[32:35]
	v_mfma_f32_16x16x32_bf16 v[20:23], v[174:177], v[210:213], v[20:23]
	v_mfma_f32_16x16x32_bf16 v[16:19], v[182:185], v[210:213], v[16:19]
	v_mfma_f32_16x16x32_bf16 v[4:7], v[174:177], v[218:221], v[4:7]
	s_barrier
	v_mfma_f32_16x16x32_bf16 v[0:3], v[182:185], v[218:221], v[0:3]
	s_setprio 0
	s_add_i32 s52, 0, 0x18000
	v_add_u32_e32 v153, s52, v151
	s_add_i32 s53, 0, 0x1c000
	ds_read_b128 v[154:157], v153
	ds_read_b128 v[158:161], v153 offset:1024
	ds_read_b128 v[162:165], v153 offset:2048
	ds_read_b128 v[166:169], v153 offset:3072
	v_add_u32_e32 v153, s53, v151
	ds_read_b128 v[170:173], v153
	ds_read_b128 v[174:177], v153 offset:1024
	ds_read_b128 v[178:181], v153 offset:2048
	ds_read_b128 v[182:185], v153 offset:3072
	s_add_u32 s28, s28, 0x40000
	s_addc_u32 s29, s29, 0
	s_mov_b32 m0, s41
	v_lshl_add_u64 v[228:229], s[28:29], 0, v[128:129]
	ds_read_b128 v[186:189], v152 offset:32768
	ds_read_b128 v[190:193], v152 offset:33792
	ds_read_b128 v[194:197], v152 offset:34816
	ds_read_b128 v[198:201], v152 offset:35840
	ds_read_b128 v[202:205], v152 offset:36864
	ds_read_b128 v[210:213], v152 offset:37888
	ds_read_b128 v[214:217], v152 offset:38912
	ds_read_b128 v[218:221], v152 offset:39936
	global_load_lds_dwordx4 v[228:229], off
	v_lshl_add_u64 v[228:229], s[28:29], 0, v[132:133]
	s_mov_b32 m0, s42
	s_nop 0
	global_load_lds_dwordx4 v[228:229], off
	s_waitcnt vmcnt(8)
	s_waitcnt lgkmcnt(0)
	s_barrier
	s_setprio 1
	s_waitcnt lgkmcnt(0)
	v_mfma_f32_16x16x32_bf16 v[124:127], v[154:157], v[186:189], v[124:127]
	v_mfma_f32_16x16x32_bf16 v[120:123], v[162:165], v[186:189], v[120:123]
	v_mfma_f32_16x16x32_bf16 v[108:111], v[154:157], v[194:197], v[108:111]
	v_mfma_f32_16x16x32_bf16 v[104:107], v[162:165], v[194:197], v[104:107]
	v_mfma_f32_16x16x32_bf16 v[92:95], v[154:157], v[202:205], v[92:95]
	v_mfma_f32_16x16x32_bf16 v[88:91], v[162:165], v[202:205], v[88:91]
	v_mfma_f32_16x16x32_bf16 v[76:79], v[154:157], v[214:217], v[76:79]
	v_mfma_f32_16x16x32_bf16 v[72:75], v[162:165], v[214:217], v[72:75]
	v_mfma_f32_16x16x32_bf16 v[124:127], v[158:161], v[190:193], v[124:127]
	v_mfma_f32_16x16x32_bf16 v[120:123], v[166:169], v[190:193], v[120:123]
	v_mfma_f32_16x16x32_bf16 v[108:111], v[158:161], v[198:201], v[108:111]
	v_mfma_f32_16x16x32_bf16 v[104:107], v[166:169], v[198:201], v[104:107]
	v_mfma_f32_16x16x32_bf16 v[92:95], v[158:161], v[210:213], v[92:95]
	v_mfma_f32_16x16x32_bf16 v[88:91], v[166:169], v[210:213], v[88:91]
	v_mfma_f32_16x16x32_bf16 v[76:79], v[158:161], v[218:221], v[76:79]
	v_mfma_f32_16x16x32_bf16 v[72:75], v[166:169], v[218:221], v[72:75]
	s_setprio 0
	s_setprio 1
	v_mfma_f32_16x16x32_bf16 v[116:119], v[170:173], v[186:189], v[116:119]
	v_mfma_f32_16x16x32_bf16 v[112:115], v[178:181], v[186:189], v[112:115]
	v_mfma_f32_16x16x32_bf16 v[100:103], v[170:173], v[194:197], v[100:103]
	v_mfma_f32_16x16x32_bf16 v[96:99], v[178:181], v[194:197], v[96:99]
	v_mfma_f32_16x16x32_bf16 v[84:87], v[170:173], v[202:205], v[84:87]
	v_mfma_f32_16x16x32_bf16 v[80:83], v[178:181], v[202:205], v[80:83]
	v_mfma_f32_16x16x32_bf16 v[68:71], v[170:173], v[214:217], v[68:71]
	v_mfma_f32_16x16x32_bf16 v[64:67], v[178:181], v[214:217], v[64:67]
	v_mfma_f32_16x16x32_bf16 v[116:119], v[174:177], v[190:193], v[116:119]
	v_mfma_f32_16x16x32_bf16 v[112:115], v[182:185], v[190:193], v[112:115]
	v_mfma_f32_16x16x32_bf16 v[100:103], v[174:177], v[198:201], v[100:103]
	v_mfma_f32_16x16x32_bf16 v[96:99], v[182:185], v[198:201], v[96:99]
	v_mfma_f32_16x16x32_bf16 v[84:87], v[174:177], v[210:213], v[84:87]
	v_mfma_f32_16x16x32_bf16 v[80:83], v[182:185], v[210:213], v[80:83]
	v_mfma_f32_16x16x32_bf16 v[68:71], v[174:177], v[218:221], v[68:71]
	s_barrier
; #define PG8_STAGE(bufoff, gbase, voff) do { _Pragma("unroll") for (int _i = 0; _i < 2; ++_i) \
;         __builtin_amdgcn_global_load_lds((const unsigned*)((const char*)(gbase) + (voff)[_i]), (PG8_LAS unsigned*)(lds + (bufoff) + ldsw + _i * 8192), 16, 0, 0); } while (0)
; #define PG8_LDA(dst, b, h) do { _Pragma("unroll") for (int m = 0; m < 4; ++m) _Pragma("unroll") for (int k = 0; k < 2; ++k) dst[m][k] = *(const PG8_LAS bf16x8*)(lds + PG8_SA(b, h) + aoff + m * 2048 + k * 1024); } while (0)
; #define PG8_MMA(ai, bj, At, Bt) do { __builtin_amdgcn_s_setprio(1); _Pragma("unroll") for (int m = 0; m < 4; ++m) _Pragma("unroll") for (int n = 0; n < 2; ++n) _Pragma("unroll") for (int k = 0; k < 2; ++k) \
;         acc[ai][bj][m][n] = __builtin_amdgcn_mfma_f32_16x16x32_bf16(Bt[n][k], At[m][k], acc[ai][bj][m][n], 0, 0, 0); __builtin_amdgcn_s_setprio(0); } while (0)
; #define PG8_WAIT_V(n) asm volatile("s_waitcnt vmcnt(" #n ")" ::: "memory")
; #define PG8_WAIT_L(n) asm volatile("s_waitcnt lgkmcnt(" #n ")" ::: "memory")
; #define PG8_BAR __builtin_amdgcn_s_barrier()
; #define PG8_SCHED __builtin_amdgcn_sched_barrier(0)
; template <class Epi, class Sched, bool ALIGN_EPI = false, bool SP2 = false>
; __device__ __forceinline__ void gemm_phase(PG8_LAS unsigned char* lds, const Gemm g, const Sched& S, const Epi& E) {
;     ...
;             PG8_WAIT_V(8); PG8_WAIT_L(0); PG8_BAR; PG8_MMA(0, 0, At, B0); PG8_MMA(0, 1, At, B1); PG8_BAR; PG8_SCHED;
;             PG8_LDA(At, 1, 1); PG8_STAGE(PG8_SB(1, 0), b3, voffB); PG8_STAGE(PG8_SB(1, 1), b3 + hstep, voffB); PG8_STAGE(PG8_SA(1, 0), a3, voffA);
;             PG8_WAIT_V(8); PG8_WAIT_L(0); PG8_BAR; PG8_MMA(1, 0, At, B0); PG8_MMA(1, 1, At, B1); PG8_BAR; PG8_SCHED;
;     ...
; #pragma unroll
;         for (int a = 0; a < 2; ++a)
; #pragma unroll
;             for (int b = 0; b < 2; ++b)
; #pragma unroll
;                 for (int m = 0; m < 4; ++m)
; #pragma unroll
;                     for (int n = 0; n < 2; ++n) acc[a][b][m][n] = (f32x4){0.f, 0.f, 0.f, 0.f};
;         cur = nxt; cA = nA; cB = nB; ++ui;
	v_mfma_f32_16x16x32_bf16 v[64:67], v[182:185], v[218:221], v[64:67]
	s_setprio 0
	s_add_i32 s28, s52, s38
	v_lshl_add_u64 v[206:207], v[206:207], 0, s[14:15]
	s_mov_b32 m0, s28
	ds_read_b128 v[186:189], v152 offset:49152
	ds_read_b128 v[190:193], v152 offset:50176
	ds_read_b128 v[194:197], v152 offset:51200
	ds_read_b128 v[198:201], v152 offset:52224
	ds_read_b128 v[202:205], v152 offset:53248
	ds_read_b128 v[210:213], v152 offset:54272
	ds_read_b128 v[214:217], v152 offset:55296
	ds_read_b128 v[218:221], v152 offset:56320
	global_load_lds_dwordx4 v[206:207], off
	s_add_i32 m0, s28, 0x2000
	s_add_u32 s26, s26, 0x40080
	v_lshl_add_u64 v[206:207], v[222:223], 0, s[14:15]
	s_addc_u32 s27, s27, 0
	s_add_i32 s28, s53, s38
	global_load_lds_dwordx4 v[206:207], off
	v_lshl_add_u64 v[206:207], s[26:27], 0, v[130:131]
	s_mov_b32 m0, s28
	s_nop 0
	global_load_lds_dwordx4 v[206:207], off
	v_lshl_add_u64 v[206:207], s[26:27], 0, v[134:135]
	s_add_i32 m0, s28, 0x2000
	s_nop 0
	global_load_lds_dwordx4 v[206:207], off
	v_lshl_add_u64 v[206:207], v[224:225], 0, s[14:15]
	s_mov_b32 m0, s59
	s_nop 0
	global_load_lds_dwordx4 v[206:207], off
	v_lshl_add_u64 v[206:207], v[226:227], 0, s[14:15]
	s_mov_b32 m0, s60
	s_nop 0
	global_load_lds_dwordx4 v[206:207], off
	s_waitcnt vmcnt(8)
	s_waitcnt lgkmcnt(0)
	s_barrier
	s_setprio 1
	s_waitcnt lgkmcnt(0)
	v_mfma_f32_16x16x32_bf16 v[60:63], v[154:157], v[186:189], v[60:63]
	v_mfma_f32_16x16x32_bf16 v[56:59], v[162:165], v[186:189], v[56:59]
	v_mfma_f32_16x16x32_bf16 v[44:47], v[154:157], v[194:197], v[44:47]
	v_mfma_f32_16x16x32_bf16 v[40:43], v[162:165], v[194:197], v[40:43]
	v_mfma_f32_16x16x32_bf16 v[28:31], v[154:157], v[202:205], v[28:31]
	v_mfma_f32_16x16x32_bf16 v[24:27], v[162:165], v[202:205], v[24:27]
	v_mfma_f32_16x16x32_bf16 v[12:15], v[154:157], v[214:217], v[12:15]
	v_mfma_f32_16x16x32_bf16 v[8:11], v[162:165], v[214:217], v[8:11]
	v_mfma_f32_16x16x32_bf16 v[60:63], v[158:161], v[190:193], v[60:63]
	v_mfma_f32_16x16x32_bf16 v[56:59], v[166:169], v[190:193], v[56:59]
	v_mfma_f32_16x16x32_bf16 v[44:47], v[158:161], v[198:201], v[44:47]
	v_mfma_f32_16x16x32_bf16 v[40:43], v[166:169], v[198:201], v[40:43]
	v_mfma_f32_16x16x32_bf16 v[28:31], v[158:161], v[210:213], v[28:31]
	v_mfma_f32_16x16x32_bf16 v[24:27], v[166:169], v[210:213], v[24:27]
	v_mfma_f32_16x16x32_bf16 v[12:15], v[158:161], v[218:221], v[12:15]
	v_mfma_f32_16x16x32_bf16 v[8:11], v[166:169], v[218:221], v[8:11]
	s_setprio 0
	s_setprio 1
	v_mfma_f32_16x16x32_bf16 v[52:55], v[170:173], v[186:189], v[52:55]
	v_mfma_f32_16x16x32_bf16 v[48:51], v[178:181], v[186:189], v[48:51]
	v_mfma_f32_16x16x32_bf16 v[36:39], v[170:173], v[194:197], v[36:39]
	v_mfma_f32_16x16x32_bf16 v[32:35], v[178:181], v[194:197], v[32:35]
	v_mfma_f32_16x16x32_bf16 v[20:23], v[170:173], v[202:205], v[20:23]
	v_mfma_f32_16x16x32_bf16 v[16:19], v[178:181], v[202:205], v[16:19]
	v_mfma_f32_16x16x32_bf16 v[4:7], v[170:173], v[214:217], v[4:7]
	v_mfma_f32_16x16x32_bf16 v[0:3], v[178:181], v[214:217], v[0:3]
	v_mfma_f32_16x16x32_bf16 v[52:55], v[174:177], v[190:193], v[52:55]
	v_mfma_f32_16x16x32_bf16 v[48:51], v[182:185], v[190:193], v[48:51]
	v_mfma_f32_16x16x32_bf16 v[36:39], v[174:177], v[198:201], v[36:39]
	v_mfma_f32_16x16x32_bf16 v[32:35], v[182:185], v[198:201], v[32:35]
	v_mfma_f32_16x16x32_bf16 v[20:23], v[174:177], v[210:213], v[20:23]
	v_mfma_f32_16x16x32_bf16 v[16:19], v[182:185], v[210:213], v[16:19]
	v_mfma_f32_16x16x32_bf16 v[4:7], v[174:177], v[218:221], v[4:7]
	s_barrier
	v_mfma_f32_16x16x32_bf16 v[0:3], v[182:185], v[218:221], v[0:3]
	s_setprio 0
	s_add_i32 s70, s70, 2
	s_add_u32 s24, s24, 0x100
	s_addc_u32 s25, s25, 0
	s_cmp_gt_u32 s70, 13
	s_cbranch_scc0 .LBB0_1009
	s_add_u32 s24, s66, 0xffffff00
	s_addc_u32 s25, s67, -1
	s_andn2_b64 vcc, exec, s[6:7]
	s_cbranch_vccnz .LBB0_1012
	v_mov_b32_e32 v0, 0
	s_mov_b32 s61, s16
	s_mov_b32 s10, s18
	s_mov_b64 s[12:13], s[22:23]
	s_mov_b32 s62, s65
	v_mov_b32_e32 v1, v0
	v_mov_b32_e32 v2, v0
	v_mov_b32_e32 v3, v0
	v_mov_b32_e32 v4, v0
	v_mov_b32_e32 v5, v0
	v_mov_b32_e32 v6, v0
	v_mov_b32_e32 v7, v0
	v_mov_b32_e32 v16, v0
	v_mov_b32_e32 v17, v0
	v_mov_b32_e32 v18, v0
	v_mov_b32_e32 v19, v0
	v_mov_b32_e32 v20, v0
	v_mov_b32_e32 v21, v0
	v_mov_b32_e32 v22, v0
	v_mov_b32_e32 v23, v0
	v_mov_b32_e32 v32, v0
	v_mov_b32_e32 v33, v0
	v_mov_b32_e32 v34, v0
	v_mov_b32_e32 v35, v0
	v_mov_b32_e32 v36, v0
	v_mov_b32_e32 v37, v0
	v_mov_b32_e32 v38, v0
	v_mov_b32_e32 v39, v0
	v_mov_b32_e32 v48, v0
	v_mov_b32_e32 v49, v0
	v_mov_b32_e32 v50, v0
	v_mov_b32_e32 v51, v0
	v_mov_b32_e32 v52, v0
	v_mov_b32_e32 v53, v0
	v_mov_b32_e32 v54, v0
	v_mov_b32_e32 v55, v0
	v_mov_b32_e32 v8, v0
	v_mov_b32_e32 v9, v0
	v_mov_b32_e32 v10, v0
	v_mov_b32_e32 v11, v0
	v_mov_b32_e32 v12, v0
	v_mov_b32_e32 v13, v0
	v_mov_b32_e32 v14, v0
	v_mov_b32_e32 v15, v0
	v_mov_b32_e32 v24, v0
	v_mov_b32_e32 v25, v0
	v_mov_b32_e32 v26, v0
	v_mov_b32_e32 v27, v0
	v_mov_b32_e32 v28, v0
	v_mov_b32_e32 v29, v0
	v_mov_b32_e32 v30, v0
	v_mov_b32_e32 v31, v0
	v_mov_b32_e32 v40, v0
	v_mov_b32_e32 v41, v0
	v_mov_b32_e32 v42, v0
	v_mov_b32_e32 v43, v0
	v_mov_b32_e32 v44, v0
	v_mov_b32_e32 v45, v0
	v_mov_b32_e32 v46, v0
	v_mov_b32_e32 v47, v0
	v_mov_b32_e32 v56, v0
	v_mov_b32_e32 v57, v0
	v_mov_b32_e32 v58, v0
	v_mov_b32_e32 v59, v0
	v_mov_b32_e32 v60, v0
	v_mov_b32_e32 v61, v0
	v_mov_b32_e32 v62, v0
	v_mov_b32_e32 v63, v0
	v_mov_b32_e32 v64, v0
	v_mov_b32_e32 v65, v0
	v_mov_b32_e32 v66, v0
	v_mov_b32_e32 v67, v0
	v_mov_b32_e32 v68, v0
	v_mov_b32_e32 v69, v0
	v_mov_b32_e32 v70, v0
	v_mov_b32_e32 v71, v0
	v_mov_b32_e32 v80, v0
	v_mov_b32_e32 v81, v0
	v_mov_b32_e32 v82, v0
	v_mov_b32_e32 v83, v0
	v_mov_b32_e32 v84, v0
	v_mov_b32_e32 v85, v0
	v_mov_b32_e32 v86, v0
	v_mov_b32_e32 v87, v0
	v_mov_b32_e32 v96, v0
	v_mov_b32_e32 v97, v0
	v_mov_b32_e32 v98, v0
	v_mov_b32_e32 v99, v0
	v_mov_b32_e32 v100, v0
	v_mov_b32_e32 v101, v0
	v_mov_b32_e32 v102, v0
	v_mov_b32_e32 v103, v0
	v_mov_b32_e32 v112, v0
	v_mov_b32_e32 v113, v0
	v_mov_b32_e32 v114, v0
	v_mov_b32_e32 v115, v0
	v_mov_b32_e32 v116, v0
	v_mov_b32_e32 v117, v0
	v_mov_b32_e32 v118, v0
	v_mov_b32_e32 v119, v0
	v_mov_b32_e32 v72, v0
	v_mov_b32_e32 v73, v0
	v_mov_b32_e32 v74, v0
	v_mov_b32_e32 v75, v0
	v_mov_b32_e32 v76, v0
	v_mov_b32_e32 v77, v0
	v_mov_b32_e32 v78, v0
	v_mov_b32_e32 v79, v0
	v_mov_b32_e32 v88, v0
	v_mov_b32_e32 v89, v0
	v_mov_b32_e32 v90, v0
	v_mov_b32_e32 v91, v0
	v_mov_b32_e32 v92, v0
	v_mov_b32_e32 v93, v0
	v_mov_b32_e32 v94, v0
	v_mov_b32_e32 v95, v0
	v_mov_b32_e32 v104, v0
	v_mov_b32_e32 v105, v0
	v_mov_b32_e32 v106, v0
	v_mov_b32_e32 v107, v0
	v_mov_b32_e32 v108, v0
	v_mov_b32_e32 v109, v0
	v_mov_b32_e32 v110, v0
	v_mov_b32_e32 v111, v0
	v_mov_b32_e32 v120, v0
	v_mov_b32_e32 v121, v0
	v_mov_b32_e32 v122, v0
	v_mov_b32_e32 v123, v0
	v_mov_b32_e32 v124, v0
	v_mov_b32_e32 v125, v0
	v_mov_b32_e32 v126, v0
	v_mov_b32_e32 v127, v0
	s_andn2_b64 vcc, exec, s[4:5]
	s_cbranch_vccnz .LBB0_1013
	s_branch .LBB0_1014

; #define PG8_STAGE(bufoff, gbase, voff) do { _Pragma("unroll") for (int _i = 0; _i < 2; ++_i) \
;         __builtin_amdgcn_global_load_lds((const unsigned*)((const char*)(gbase) + (voff)[_i]), (PG8_LAS unsigned*)(lds + (bufoff) + ldsw + _i * 8192), 16, 0, 0); } while (0)
; #define PG8_LDA(dst, b, h) do { _Pragma("unroll") for (int m = 0; m < 4; ++m) _Pragma("unroll") for (int k = 0; k < 2; ++k) dst[m][k] = *(const PG8_LAS bf16x8*)(lds + PG8_SA(b, h) + aoff + m * 2048 + k * 1024); } while (0)
; #define PG8_LDB(dst, b, h) do { _Pragma("unroll") for (int n = 0; n < 2; ++n) _Pragma("unroll") for (int k = 0; k < 2; ++k) dst[n][k] = *(const PG8_LAS bf16x8*)(lds + PG8_SB(b, h) + boff + n * 2048 + k * 1024); } while (0)
; #define PG8_MMA(ai, bj, At, Bt) do { __builtin_amdgcn_s_setprio(1); _Pragma("unroll") for (int m = 0; m < 4; ++m) _Pragma("unroll") for (int n = 0; n < 2; ++n) _Pragma("unroll") for (int k = 0; k < 2; ++k) \
;         acc[ai][bj][m][n] = __builtin_amdgcn_mfma_f32_16x16x32_bf16(Bt[n][k], At[m][k], acc[ai][bj][m][n], 0, 0, 0); __builtin_amdgcn_s_setprio(0); } while (0)
; #define PG8_WAIT_V(n) asm volatile("s_waitcnt vmcnt(" #n ")" ::: "memory")
; #define PG8_BAR __builtin_amdgcn_s_barrier()
; template <class Epi, class Sched, bool ALIGN_EPI = false, bool SP2 = false>
; __device__ __forceinline__ void gemm_phase(PG8_LAS unsigned char* lds, const Gemm g, const Sched& S, const Epi& E) {
;     ...
;         for (int t = 0; t < nt; t += 2) {
;             const bool last = (t == nt - 2);
;             const char* a1 = cA + (size_t)(t + 1) * kstep;
;             const char* a2 = last ? nA : cA + (size_t)(t + 2) * kstep; const char* b2 = last ? nB : cB + (size_t)(t + 2) * kstep;
;             const char* a3 = a2 + kstep; const char* b3 = b2 + kstep;
;             if (last && has_next) S.a_ready(nxt);
;             if constexpr (SP2) {
;             PG8_LDB(B0, 0, 0); PG8_LDB(B1, 0, 1); PG8_SCHED; PG8_LDA(At, 0, 0); PG8_STAGE(PG8_SA(1, 1), a1 + hstep, voffA);
;             PG8_WAIT_V(8); PG8_WAIT_L(0); PG8_BAR; PG8_MMA(0, 0, At, B0); PG8_MMA(0, 1, At, B1); PG8_BAR; PG8_SCHED;
;             PG8_LDA(At, 0, 1); PG8_STAGE(PG8_SB(0, 0), b2, voffB); PG8_STAGE(PG8_SB(0, 1), b2 + hstep, voffB); PG8_STAGE(PG8_SA(0, 0), a2, voffA);
;             PG8_WAIT_V(8); PG8_WAIT_L(0); PG8_BAR; PG8_MMA(1, 0, At, B0); PG8_MMA(1, 1, At, B1); PG8_BAR; PG8_SCHED;
.LBB0_1101:
	v_add_u32_e32 v162, s61, v148
	v_add_u32_e32 v178, s62, v148
	s_add_u32 s26, s12, s24
	ds_read_b128 v[150:153], v162
	ds_read_b128 v[154:157], v162 offset:1024
	ds_read_b128 v[158:161], v162 offset:2048
	ds_read_b128 v[162:165], v162 offset:3072
	ds_read_b128 v[166:169], v178
	ds_read_b128 v[170:173], v178 offset:1024
	ds_read_b128 v[174:177], v178 offset:2048
	ds_read_b128 v[178:181], v178 offset:3072
	s_addc_u32 s27, s13, s25
	s_add_u32 s26, s26, 0x100
	s_addc_u32 s27, s27, 0
	s_add_u32 s52, s64, s24
	s_addc_u32 s53, s65, s25
	s_cmpk_eq_i32 s24, 0x700
	s_cselect_b32 s29, s19, s27
	s_cselect_b32 s28, s66, s26
	s_cselect_b32 s27, s17, s53
	s_cselect_b32 s26, s67, s52
	v_lshl_add_u64 v[206:207], v[140:141], 0, s[24:25]
	s_add_i32 m0, s11, 0xc000
	ds_read_b128 v[182:185], v149
	ds_read_b128 v[186:189], v149 offset:1024
	ds_read_b128 v[190:193], v149 offset:2048
	ds_read_b128 v[194:197], v149 offset:3072
	ds_read_b128 v[198:201], v149 offset:4096
	ds_read_b128 v[202:205], v149 offset:5120
	ds_read_b128 v[210:213], v149 offset:6144
	ds_read_b128 v[214:217], v149 offset:7168
	global_load_lds_dwordx4 v[206:207], off
	v_lshl_add_u64 v[206:207], v[142:143], 0, s[24:25]
	s_add_i32 m0, s11, 0xe000
	s_nop 0
	global_load_lds_dwordx4 v[206:207], off
	s_waitcnt vmcnt(8)
	s_waitcnt lgkmcnt(0)
	s_barrier
	s_setprio 1
	s_waitcnt lgkmcnt(0)
	v_mfma_f32_16x16x32_bf16 v[124:127], v[150:153], v[182:185], v[124:127]
	v_mfma_f32_16x16x32_bf16 v[120:123], v[158:161], v[182:185], v[120:123]
	v_mfma_f32_16x16x32_bf16 v[108:111], v[150:153], v[190:193], v[108:111]
	v_mfma_f32_16x16x32_bf16 v[104:107], v[158:161], v[190:193], v[104:107]
	v_mfma_f32_16x16x32_bf16 v[92:95], v[150:153], v[198:201], v[92:95]
	v_mfma_f32_16x16x32_bf16 v[88:91], v[158:161], v[198:201], v[88:91]
	v_mfma_f32_16x16x32_bf16 v[76:79], v[150:153], v[210:213], v[76:79]
	v_mfma_f32_16x16x32_bf16 v[72:75], v[158:161], v[210:213], v[72:75]
	v_mfma_f32_16x16x32_bf16 v[124:127], v[154:157], v[186:189], v[124:127]
	v_mfma_f32_16x16x32_bf16 v[120:123], v[162:165], v[186:189], v[120:123]
	v_mfma_f32_16x16x32_bf16 v[108:111], v[154:157], v[194:197], v[108:111]
	v_mfma_f32_16x16x32_bf16 v[104:107], v[162:165], v[194:197], v[104:107]
	v_mfma_f32_16x16x32_bf16 v[92:95], v[154:157], v[202:205], v[92:95]
	v_mfma_f32_16x16x32_bf16 v[88:91], v[162:165], v[202:205], v[88:91]
	v_mfma_f32_16x16x32_bf16 v[76:79], v[154:157], v[214:217], v[76:79]
	v_mfma_f32_16x16x32_bf16 v[72:75], v[162:165], v[214:217], v[72:75]
	s_setprio 0
	s_setprio 1
	v_mfma_f32_16x16x32_bf16 v[116:119], v[166:169], v[182:185], v[116:119]
	v_mfma_f32_16x16x32_bf16 v[112:115], v[174:177], v[182:185], v[112:115]
	v_mfma_f32_16x16x32_bf16 v[100:103], v[166:169], v[190:193], v[100:103]
	v_mfma_f32_16x16x32_bf16 v[96:99], v[174:177], v[190:193], v[96:99]
	v_mfma_f32_16x16x32_bf16 v[84:87], v[166:169], v[198:201], v[84:87]
	v_mfma_f32_16x16x32_bf16 v[80:83], v[174:177], v[198:201], v[80:83]
	v_mfma_f32_16x16x32_bf16 v[68:71], v[166:169], v[210:213], v[68:71]
	v_mfma_f32_16x16x32_bf16 v[64:67], v[174:177], v[210:213], v[64:67]
	v_mfma_f32_16x16x32_bf16 v[116:119], v[170:173], v[186:189], v[116:119]
	v_mfma_f32_16x16x32_bf16 v[112:115], v[178:181], v[186:189], v[112:115]
	v_mfma_f32_16x16x32_bf16 v[100:103], v[170:173], v[194:197], v[100:103]
	v_mfma_f32_16x16x32_bf16 v[96:99], v[178:181], v[194:197], v[96:99]
	v_mfma_f32_16x16x32_bf16 v[84:87], v[170:173], v[202:205], v[84:87]
	v_mfma_f32_16x16x32_bf16 v[80:83], v[178:181], v[202:205], v[80:83]
	v_mfma_f32_16x16x32_bf16 v[68:71], v[170:173], v[214:217], v[68:71]
	s_barrier
	v_mfma_f32_16x16x32_bf16 v[64:67], v[178:181], v[214:217], v[64:67]
	s_setprio 0
	s_add_i32 s52, s61, s37
	v_lshl_add_u64 v[206:207], s[26:27], 0, v[128:129]
	s_mov_b32 m0, s52
	ds_read_b128 v[182:185], v149 offset:16384
	ds_read_b128 v[186:189], v149 offset:17408
	ds_read_b128 v[190:193], v149 offset:18432
	ds_read_b128 v[194:197], v149 offset:19456
	ds_read_b128 v[198:201], v149 offset:20480
	ds_read_b128 v[202:205], v149 offset:21504
	ds_read_b128 v[210:213], v149 offset:22528
	ds_read_b128 v[214:217], v149 offset:23552
	global_load_lds_dwordx4 v[206:207], off
	s_add_i32 m0, s52, 0x2000
	s_add_u32 s52, s26, 0x40000
	v_lshl_add_u64 v[218:219], s[26:27], 0, v[130:131]
	s_addc_u32 s53, s27, 0
	s_add_i32 s69, s62, s37
	global_load_lds_dwordx4 v[218:219], off
	v_lshl_add_u64 v[220:221], s[52:53], 0, v[128:129]
	s_mov_b32 m0, s69
	v_lshl_add_u64 v[222:223], s[28:29], 0, v[130:131]
	global_load_lds_dwordx4 v[220:221], off
	v_lshl_add_u64 v[220:221], s[52:53], 0, v[130:131]
	s_add_i32 m0, s69, 0x2000
	s_nop 0
	global_load_lds_dwordx4 v[220:221], off
	v_lshl_add_u64 v[220:221], s[28:29], 0, v[128:129]
	s_mov_b32 m0, s11
	s_nop 0
	global_load_lds_dwordx4 v[220:221], off
	s_mov_b32 m0, s40
	s_nop 0
	global_load_lds_dwordx4 v[222:223], off
	s_waitcnt vmcnt(8)
	s_waitcnt lgkmcnt(0)
	s_barrier
; #define PG8_STAGE(bufoff, gbase, voff) do { _Pragma("unroll") for (int _i = 0; _i < 2; ++_i) \
;         __builtin_amdgcn_global_load_lds((const unsigned*)((const char*)(gbase) + (voff)[_i]), (PG8_LAS unsigned*)(lds + (bufoff) + ldsw + _i * 8192), 16, 0, 0); } while (0)
; #define PG8_LDA(dst, b, h) do { _Pragma("unroll") for (int m = 0; m < 4; ++m) _Pragma("unroll") for (int k = 0; k < 2; ++k) dst[m][k] = *(const PG8_LAS bf16x8*)(lds + PG8_SA(b, h) + aoff + m * 2048 + k * 1024); } while (0)
; #define PG8_LDB(dst, b, h) do { _Pragma("unroll") for (int n = 0; n < 2; ++n) _Pragma("unroll") for (int k = 0; k < 2; ++k) dst[n][k] = *(const PG8_LAS bf16x8*)(lds + PG8_SB(b, h) + boff + n * 2048 + k * 1024); } while (0)
; #define PG8_MMA(ai, bj, At, Bt) do { __builtin_amdgcn_s_setprio(1); _Pragma("unroll") for (int m = 0; m < 4; ++m) _Pragma("unroll") for (int n = 0; n < 2; ++n) _Pragma("unroll") for (int k = 0; k < 2; ++k) \
;         acc[ai][bj][m][n] = __builtin_amdgcn_mfma_f32_16x16x32_bf16(Bt[n][k], At[m][k], acc[ai][bj][m][n], 0, 0, 0); __builtin_amdgcn_s_setprio(0); } while (0)
; #define PG8_WAIT_V(n) asm volatile("s_waitcnt vmcnt(" #n ")" ::: "memory")
; #define PG8_WAIT_L(n) asm volatile("s_waitcnt lgkmcnt(" #n ")" ::: "memory")
; #define PG8_BAR __builtin_amdgcn_s_barrier()
; #define PG8_SCHED __builtin_amdgcn_sched_barrier(0)
; template <class Epi, class Sched, bool ALIGN_EPI = false, bool SP2 = false>
; __device__ __forceinline__ void gemm_phase(PG8_LAS unsigned char* lds, const Gemm g, const Sched& S, const Epi& E) {
;     ...
;             PG8_WAIT_V(8); PG8_WAIT_L(0); PG8_BAR; PG8_MMA(1, 0, At, B0); PG8_MMA(1, 1, At, B1); PG8_BAR; PG8_SCHED;
;             PG8_LDB(B0, 1, 0); PG8_LDB(B1, 1, 1); PG8_SCHED; PG8_LDA(At, 1, 0); PG8_STAGE(PG8_SA(0, 1), a2 + hstep, voffA);
;             PG8_WAIT_V(8); PG8_WAIT_L(0); PG8_BAR; PG8_MMA(0, 0, At, B0); PG8_MMA(0, 1, At, B1); PG8_BAR; PG8_SCHED;
;             PG8_LDA(At, 1, 1); PG8_STAGE(PG8_SB(1, 0), b3, voffB); PG8_STAGE(PG8_SB(1, 1), b3 + hstep, voffB); PG8_STAGE(PG8_SA(1, 0), a3, voffA);
	s_setprio 1
	s_waitcnt lgkmcnt(0)
	v_mfma_f32_16x16x32_bf16 v[60:63], v[150:153], v[182:185], v[60:63]
	v_mfma_f32_16x16x32_bf16 v[56:59], v[158:161], v[182:185], v[56:59]
	v_mfma_f32_16x16x32_bf16 v[44:47], v[150:153], v[190:193], v[44:47]
	v_mfma_f32_16x16x32_bf16 v[40:43], v[158:161], v[190:193], v[40:43]
	v_mfma_f32_16x16x32_bf16 v[28:31], v[150:153], v[198:201], v[28:31]
	v_mfma_f32_16x16x32_bf16 v[24:27], v[158:161], v[198:201], v[24:27]
	v_mfma_f32_16x16x32_bf16 v[12:15], v[150:153], v[210:213], v[12:15]
	v_mfma_f32_16x16x32_bf16 v[8:11], v[158:161], v[210:213], v[8:11]
	v_mfma_f32_16x16x32_bf16 v[60:63], v[154:157], v[186:189], v[60:63]
	v_mfma_f32_16x16x32_bf16 v[56:59], v[162:165], v[186:189], v[56:59]
	v_mfma_f32_16x16x32_bf16 v[44:47], v[154:157], v[194:197], v[44:47]
	v_mfma_f32_16x16x32_bf16 v[40:43], v[162:165], v[194:197], v[40:43]
	v_mfma_f32_16x16x32_bf16 v[28:31], v[154:157], v[202:205], v[28:31]
	v_mfma_f32_16x16x32_bf16 v[24:27], v[162:165], v[202:205], v[24:27]
	v_mfma_f32_16x16x32_bf16 v[12:15], v[154:157], v[214:217], v[12:15]
	v_mfma_f32_16x16x32_bf16 v[8:11], v[162:165], v[214:217], v[8:11]
	s_setprio 0
	s_setprio 1
	v_mfma_f32_16x16x32_bf16 v[52:55], v[166:169], v[182:185], v[52:55]
	v_mfma_f32_16x16x32_bf16 v[48:51], v[174:177], v[182:185], v[48:51]
	v_mfma_f32_16x16x32_bf16 v[36:39], v[166:169], v[190:193], v[36:39]
	v_mfma_f32_16x16x32_bf16 v[32:35], v[174:177], v[190:193], v[32:35]
	v_mfma_f32_16x16x32_bf16 v[20:23], v[166:169], v[198:201], v[20:23]
	v_mfma_f32_16x16x32_bf16 v[16:19], v[174:177], v[198:201], v[16:19]
	v_mfma_f32_16x16x32_bf16 v[4:7], v[166:169], v[210:213], v[4:7]
	v_mfma_f32_16x16x32_bf16 v[0:3], v[174:177], v[210:213], v[0:3]
	v_mfma_f32_16x16x32_bf16 v[52:55], v[170:173], v[186:189], v[52:55]
	v_mfma_f32_16x16x32_bf16 v[48:51], v[178:181], v[186:189], v[48:51]
	v_mfma_f32_16x16x32_bf16 v[36:39], v[170:173], v[194:197], v[36:39]
	v_mfma_f32_16x16x32_bf16 v[32:35], v[178:181], v[194:197], v[32:35]
	v_mfma_f32_16x16x32_bf16 v[20:23], v[170:173], v[202:205], v[20:23]
	v_mfma_f32_16x16x32_bf16 v[16:19], v[178:181], v[202:205], v[16:19]
	v_mfma_f32_16x16x32_bf16 v[4:7], v[170:173], v[214:217], v[4:7]
	s_barrier
	v_mfma_f32_16x16x32_bf16 v[0:3], v[178:181], v[214:217], v[0:3]
	s_setprio 0
	s_add_i32 s52, 0, 0x18000
	s_add_i32 s53, 0, 0x1c000
	v_add_u32_e32 v162, s52, v148
	v_add_u32_e32 v178, s53, v148
	ds_read_b128 v[150:153], v162
	ds_read_b128 v[154:157], v162 offset:1024
	ds_read_b128 v[158:161], v162 offset:2048
	ds_read_b128 v[162:165], v162 offset:3072
	ds_read_b128 v[166:169], v178
	ds_read_b128 v[170:173], v178 offset:1024
	ds_read_b128 v[174:177], v178 offset:2048
	ds_read_b128 v[178:181], v178 offset:3072
	s_add_u32 s28, s28, 0x40000
	s_addc_u32 s29, s29, 0
	s_mov_b32 m0, s41
	v_lshl_add_u64 v[224:225], s[28:29], 0, v[128:129]
	ds_read_b128 v[182:185], v149 offset:32768
	ds_read_b128 v[186:189], v149 offset:33792
	ds_read_b128 v[190:193], v149 offset:34816
	ds_read_b128 v[194:197], v149 offset:35840
	ds_read_b128 v[198:201], v149 offset:36864
	ds_read_b128 v[202:205], v149 offset:37888
	ds_read_b128 v[210:213], v149 offset:38912
	ds_read_b128 v[214:217], v149 offset:39936
	global_load_lds_dwordx4 v[224:225], off
	v_lshl_add_u64 v[224:225], s[28:29], 0, v[130:131]
	s_mov_b32 m0, s42
	s_nop 0
	global_load_lds_dwordx4 v[224:225], off
	s_waitcnt vmcnt(8)
	s_waitcnt lgkmcnt(0)
	s_barrier
	s_setprio 1
	s_waitcnt lgkmcnt(0)
	v_mfma_f32_16x16x32_bf16 v[124:127], v[150:153], v[182:185], v[124:127]
	v_mfma_f32_16x16x32_bf16 v[120:123], v[158:161], v[182:185], v[120:123]
	v_mfma_f32_16x16x32_bf16 v[108:111], v[150:153], v[190:193], v[108:111]
	v_mfma_f32_16x16x32_bf16 v[104:107], v[158:161], v[190:193], v[104:107]
	v_mfma_f32_16x16x32_bf16 v[92:95], v[150:153], v[198:201], v[92:95]
	v_mfma_f32_16x16x32_bf16 v[88:91], v[158:161], v[198:201], v[88:91]
	v_mfma_f32_16x16x32_bf16 v[76:79], v[150:153], v[210:213], v[76:79]
	v_mfma_f32_16x16x32_bf16 v[72:75], v[158:161], v[210:213], v[72:75]
	v_mfma_f32_16x16x32_bf16 v[124:127], v[154:157], v[186:189], v[124:127]
	v_mfma_f32_16x16x32_bf16 v[120:123], v[162:165], v[186:189], v[120:123]
	v_mfma_f32_16x16x32_bf16 v[108:111], v[154:157], v[194:197], v[108:111]
	v_mfma_f32_16x16x32_bf16 v[104:107], v[162:165], v[194:197], v[104:107]
	v_mfma_f32_16x16x32_bf16 v[92:95], v[154:157], v[202:205], v[92:95]
	v_mfma_f32_16x16x32_bf16 v[88:91], v[162:165], v[202:205], v[88:91]
	v_mfma_f32_16x16x32_bf16 v[76:79], v[154:157], v[214:217], v[76:79]
	v_mfma_f32_16x16x32_bf16 v[72:75], v[162:165], v[214:217], v[72:75]
	s_setprio 0
	s_setprio 1
	v_mfma_f32_16x16x32_bf16 v[116:119], v[166:169], v[182:185], v[116:119]
	v_mfma_f32_16x16x32_bf16 v[112:115], v[174:177], v[182:185], v[112:115]
	v_mfma_f32_16x16x32_bf16 v[100:103], v[166:169], v[190:193], v[100:103]
	v_mfma_f32_16x16x32_bf16 v[96:99], v[174:177], v[190:193], v[96:99]
	v_mfma_f32_16x16x32_bf16 v[84:87], v[166:169], v[198:201], v[84:87]
	v_mfma_f32_16x16x32_bf16 v[80:83], v[174:177], v[198:201], v[80:83]
	v_mfma_f32_16x16x32_bf16 v[68:71], v[166:169], v[210:213], v[68:71]
	v_mfma_f32_16x16x32_bf16 v[64:67], v[174:177], v[210:213], v[64:67]
	v_mfma_f32_16x16x32_bf16 v[116:119], v[170:173], v[186:189], v[116:119]
	v_mfma_f32_16x16x32_bf16 v[112:115], v[178:181], v[186:189], v[112:115]
	v_mfma_f32_16x16x32_bf16 v[100:103], v[170:173], v[194:197], v[100:103]
	v_mfma_f32_16x16x32_bf16 v[96:99], v[178:181], v[194:197], v[96:99]
	v_mfma_f32_16x16x32_bf16 v[84:87], v[170:173], v[202:205], v[84:87]
	v_mfma_f32_16x16x32_bf16 v[80:83], v[178:181], v[202:205], v[80:83]
	v_mfma_f32_16x16x32_bf16 v[68:71], v[170:173], v[214:217], v[68:71]
	s_barrier
; #define PG8_STAGE(bufoff, gbase, voff) do { _Pragma("unroll") for (int _i = 0; _i < 2; ++_i) \
;         __builtin_amdgcn_global_load_lds((const unsigned*)((const char*)(gbase) + (voff)[_i]), (PG8_LAS unsigned*)(lds + (bufoff) + ldsw + _i * 8192), 16, 0, 0); } while (0)
; #define PG8_LDA(dst, b, h) do { _Pragma("unroll") for (int m = 0; m < 4; ++m) _Pragma("unroll") for (int k = 0; k < 2; ++k) dst[m][k] = *(const PG8_LAS bf16x8*)(lds + PG8_SA(b, h) + aoff + m * 2048 + k * 1024); } while (0)
; #define PG8_MMA(ai, bj, At, Bt) do { __builtin_amdgcn_s_setprio(1); _Pragma("unroll") for (int m = 0; m < 4; ++m) _Pragma("unroll") for (int n = 0; n < 2; ++n) _Pragma("unroll") for (int k = 0; k < 2; ++k) \
;         acc[ai][bj][m][n] = __builtin_amdgcn_mfma_f32_16x16x32_bf16(Bt[n][k], At[m][k], acc[ai][bj][m][n], 0, 0, 0); __builtin_amdgcn_s_setprio(0); } while (0)
; #define PG8_WAIT_V(n) asm volatile("s_waitcnt vmcnt(" #n ")" ::: "memory")
; #define PG8_WAIT_L(n) asm volatile("s_waitcnt lgkmcnt(" #n ")" ::: "memory")
; #define PG8_BAR __builtin_amdgcn_s_barrier()
; #define PG8_SCHED __builtin_amdgcn_sched_barrier(0)
; template <class Epi, class Sched, bool ALIGN_EPI = false, bool SP2 = false>
; __device__ __forceinline__ void gemm_phase(PG8_LAS unsigned char* lds, const Gemm g, const Sched& S, const Epi& E) {
;     ...
;             PG8_WAIT_V(8); PG8_WAIT_L(0); PG8_BAR; PG8_MMA(0, 0, At, B0); PG8_MMA(0, 1, At, B1); PG8_BAR; PG8_SCHED;
;             PG8_LDA(At, 1, 1); PG8_STAGE(PG8_SB(1, 0), b3, voffB); PG8_STAGE(PG8_SB(1, 1), b3 + hstep, voffB); PG8_STAGE(PG8_SA(1, 0), a3, voffA);
;             PG8_WAIT_V(8); PG8_WAIT_L(0); PG8_BAR; PG8_MMA(1, 0, At, B0); PG8_MMA(1, 1, At, B1); PG8_BAR; PG8_SCHED;
;     ...
; #pragma unroll
;         for (int a = 0; a < 2; ++a)
; #pragma unroll
;             for (int b = 0; b < 2; ++b)
; #pragma unroll
;                 for (int m = 0; m < 4; ++m)
; #pragma unroll
;                     for (int n = 0; n < 2; ++n) acc[a][b][m][n] = (f32x4){0.f, 0.f, 0.f, 0.f};
;         cur = nxt; cA = nA; cB = nB; ++ui;
	v_mfma_f32_16x16x32_bf16 v[64:67], v[178:181], v[214:217], v[64:67]
	s_setprio 0
	s_add_i32 s28, s52, s37
	v_lshl_add_u64 v[206:207], v[206:207], 0, s[14:15]
	s_mov_b32 m0, s28
	ds_read_b128 v[182:185], v149 offset:49152
	ds_read_b128 v[186:189], v149 offset:50176
	ds_read_b128 v[190:193], v149 offset:51200
	ds_read_b128 v[194:197], v149 offset:52224
	ds_read_b128 v[198:201], v149 offset:53248
	ds_read_b128 v[202:205], v149 offset:54272
	ds_read_b128 v[210:213], v149 offset:55296
	ds_read_b128 v[214:217], v149 offset:56320
	global_load_lds_dwordx4 v[206:207], off
	s_add_i32 m0, s28, 0x2000
	s_add_u32 s26, s26, 0x40080
	v_lshl_add_u64 v[206:207], v[218:219], 0, s[14:15]
	s_addc_u32 s27, s27, 0
	s_add_i32 s28, s53, s37
	global_load_lds_dwordx4 v[206:207], off
	v_lshl_add_u64 v[206:207], s[26:27], 0, v[128:129]
	s_mov_b32 m0, s28
	s_nop 0
	global_load_lds_dwordx4 v[206:207], off
	v_lshl_add_u64 v[206:207], s[26:27], 0, v[130:131]
	s_add_i32 m0, s28, 0x2000
	s_nop 0
	global_load_lds_dwordx4 v[206:207], off
	v_lshl_add_u64 v[206:207], v[220:221], 0, s[14:15]
	s_mov_b32 m0, s59
	s_nop 0
	global_load_lds_dwordx4 v[206:207], off
	v_lshl_add_u64 v[206:207], v[222:223], 0, s[14:15]
	s_mov_b32 m0, s60
	s_nop 0
	global_load_lds_dwordx4 v[206:207], off
	s_waitcnt vmcnt(8)
	s_waitcnt lgkmcnt(0)
	s_barrier
	s_setprio 1
	s_waitcnt lgkmcnt(0)
	v_mfma_f32_16x16x32_bf16 v[60:63], v[150:153], v[182:185], v[60:63]
	v_mfma_f32_16x16x32_bf16 v[56:59], v[158:161], v[182:185], v[56:59]
	v_mfma_f32_16x16x32_bf16 v[44:47], v[150:153], v[190:193], v[44:47]
	v_mfma_f32_16x16x32_bf16 v[40:43], v[158:161], v[190:193], v[40:43]
	v_mfma_f32_16x16x32_bf16 v[28:31], v[150:153], v[198:201], v[28:31]
	v_mfma_f32_16x16x32_bf16 v[24:27], v[158:161], v[198:201], v[24:27]
	v_mfma_f32_16x16x32_bf16 v[12:15], v[150:153], v[210:213], v[12:15]
	v_mfma_f32_16x16x32_bf16 v[8:11], v[158:161], v[210:213], v[8:11]
	v_mfma_f32_16x16x32_bf16 v[60:63], v[154:157], v[186:189], v[60:63]
	v_mfma_f32_16x16x32_bf16 v[56:59], v[162:165], v[186:189], v[56:59]
	v_mfma_f32_16x16x32_bf16 v[44:47], v[154:157], v[194:197], v[44:47]
	v_mfma_f32_16x16x32_bf16 v[40:43], v[162:165], v[194:197], v[40:43]
	v_mfma_f32_16x16x32_bf16 v[28:31], v[154:157], v[202:205], v[28:31]
	v_mfma_f32_16x16x32_bf16 v[24:27], v[162:165], v[202:205], v[24:27]
	v_mfma_f32_16x16x32_bf16 v[12:15], v[154:157], v[214:217], v[12:15]
	v_mfma_f32_16x16x32_bf16 v[8:11], v[162:165], v[214:217], v[8:11]
	s_setprio 0
	s_setprio 1
	v_mfma_f32_16x16x32_bf16 v[52:55], v[166:169], v[182:185], v[52:55]
	v_mfma_f32_16x16x32_bf16 v[48:51], v[174:177], v[182:185], v[48:51]
	v_mfma_f32_16x16x32_bf16 v[36:39], v[166:169], v[190:193], v[36:39]
	v_mfma_f32_16x16x32_bf16 v[32:35], v[174:177], v[190:193], v[32:35]
	v_mfma_f32_16x16x32_bf16 v[20:23], v[166:169], v[198:201], v[20:23]
	v_mfma_f32_16x16x32_bf16 v[16:19], v[174:177], v[198:201], v[16:19]
	v_mfma_f32_16x16x32_bf16 v[4:7], v[166:169], v[210:213], v[4:7]
	v_mfma_f32_16x16x32_bf16 v[0:3], v[174:177], v[210:213], v[0:3]
	v_mfma_f32_16x16x32_bf16 v[52:55], v[170:173], v[186:189], v[52:55]
	v_mfma_f32_16x16x32_bf16 v[48:51], v[178:181], v[186:189], v[48:51]
	v_mfma_f32_16x16x32_bf16 v[36:39], v[170:173], v[194:197], v[36:39]
	v_mfma_f32_16x16x32_bf16 v[32:35], v[178:181], v[194:197], v[32:35]
	v_mfma_f32_16x16x32_bf16 v[20:23], v[170:173], v[202:205], v[20:23]
	v_mfma_f32_16x16x32_bf16 v[16:19], v[178:181], v[202:205], v[16:19]
	v_mfma_f32_16x16x32_bf16 v[4:7], v[170:173], v[214:217], v[4:7]
	s_barrier
	v_mfma_f32_16x16x32_bf16 v[0:3], v[178:181], v[214:217], v[0:3]
	s_setprio 0
	s_add_i32 s68, s68, 2
	s_add_u32 s24, s24, 0x100
	s_addc_u32 s25, s25, 0
	s_cmp_gt_u32 s68, 13
	s_cbranch_scc0 .LBB0_1101
	s_add_u32 s24, s64, 0xffffff00
	s_addc_u32 s25, s65, -1
	s_andn2_b64 vcc, exec, s[6:7]
	s_cbranch_vccnz .LBB0_1104
	v_mov_b32_e32 v0, 0
	s_mov_b32 s34, s16
	s_mov_b32 s10, s18
	s_mov_b64 s[12:13], s[22:23]
	s_mov_b32 s43, s63
	v_mov_b32_e32 v1, v0
	v_mov_b32_e32 v2, v0
	v_mov_b32_e32 v3, v0
	v_mov_b32_e32 v4, v0
	v_mov_b32_e32 v5, v0
	v_mov_b32_e32 v6, v0
	v_mov_b32_e32 v7, v0
	v_mov_b32_e32 v16, v0
	v_mov_b32_e32 v17, v0
	v_mov_b32_e32 v18, v0
	v_mov_b32_e32 v19, v0
	v_mov_b32_e32 v20, v0
	v_mov_b32_e32 v21, v0
	v_mov_b32_e32 v22, v0
	v_mov_b32_e32 v23, v0
	v_mov_b32_e32 v32, v0
	v_mov_b32_e32 v33, v0
	v_mov_b32_e32 v34, v0
	v_mov_b32_e32 v35, v0
	v_mov_b32_e32 v36, v0
	v_mov_b32_e32 v37, v0
	v_mov_b32_e32 v38, v0
	v_mov_b32_e32 v39, v0
	v_mov_b32_e32 v48, v0
	v_mov_b32_e32 v49, v0
	v_mov_b32_e32 v50, v0
	v_mov_b32_e32 v51, v0
	v_mov_b32_e32 v52, v0
	v_mov_b32_e32 v53, v0
	v_mov_b32_e32 v54, v0
	v_mov_b32_e32 v55, v0
	v_mov_b32_e32 v8, v0
	v_mov_b32_e32 v9, v0
	v_mov_b32_e32 v10, v0
	v_mov_b32_e32 v11, v0
	v_mov_b32_e32 v12, v0
	v_mov_b32_e32 v13, v0
	v_mov_b32_e32 v14, v0
	v_mov_b32_e32 v15, v0
	v_mov_b32_e32 v24, v0
	v_mov_b32_e32 v25, v0
	v_mov_b32_e32 v26, v0
	v_mov_b32_e32 v27, v0
	v_mov_b32_e32 v28, v0
	v_mov_b32_e32 v29, v0
	v_mov_b32_e32 v30, v0
	v_mov_b32_e32 v31, v0
	v_mov_b32_e32 v40, v0
	v_mov_b32_e32 v41, v0
	v_mov_b32_e32 v42, v0
	v_mov_b32_e32 v43, v0
	v_mov_b32_e32 v44, v0
	v_mov_b32_e32 v45, v0
	v_mov_b32_e32 v46, v0
	v_mov_b32_e32 v47, v0
	v_mov_b32_e32 v56, v0
	v_mov_b32_e32 v57, v0
	v_mov_b32_e32 v58, v0
	v_mov_b32_e32 v59, v0
	v_mov_b32_e32 v60, v0
	v_mov_b32_e32 v61, v0
	v_mov_b32_e32 v62, v0
	v_mov_b32_e32 v63, v0
	v_mov_b32_e32 v64, v0
	v_mov_b32_e32 v65, v0
	v_mov_b32_e32 v66, v0
	v_mov_b32_e32 v67, v0
	v_mov_b32_e32 v68, v0
	v_mov_b32_e32 v69, v0
	v_mov_b32_e32 v70, v0
	v_mov_b32_e32 v71, v0
	v_mov_b32_e32 v80, v0
	v_mov_b32_e32 v81, v0
	v_mov_b32_e32 v82, v0
	v_mov_b32_e32 v83, v0
	v_mov_b32_e32 v84, v0
	v_mov_b32_e32 v85, v0
	v_mov_b32_e32 v86, v0
	v_mov_b32_e32 v87, v0
	v_mov_b32_e32 v96, v0
	v_mov_b32_e32 v97, v0
	v_mov_b32_e32 v98, v0
	v_mov_b32_e32 v99, v0
	v_mov_b32_e32 v100, v0
	v_mov_b32_e32 v101, v0
	v_mov_b32_e32 v102, v0
	v_mov_b32_e32 v103, v0
	v_mov_b32_e32 v112, v0
	v_mov_b32_e32 v113, v0
	v_mov_b32_e32 v114, v0
	v_mov_b32_e32 v115, v0
	v_mov_b32_e32 v116, v0
	v_mov_b32_e32 v117, v0
	v_mov_b32_e32 v118, v0
	v_mov_b32_e32 v119, v0
	v_mov_b32_e32 v72, v0
	v_mov_b32_e32 v73, v0
	v_mov_b32_e32 v74, v0
	v_mov_b32_e32 v75, v0
	v_mov_b32_e32 v76, v0
	v_mov_b32_e32 v77, v0
	v_mov_b32_e32 v78, v0
	v_mov_b32_e32 v79, v0
	v_mov_b32_e32 v88, v0
	v_mov_b32_e32 v89, v0
	v_mov_b32_e32 v90, v0
	v_mov_b32_e32 v91, v0
	v_mov_b32_e32 v92, v0
	v_mov_b32_e32 v93, v0
	v_mov_b32_e32 v94, v0
	v_mov_b32_e32 v95, v0
	v_mov_b32_e32 v104, v0
	v_mov_b32_e32 v105, v0
	v_mov_b32_e32 v106, v0
	v_mov_b32_e32 v107, v0
	v_mov_b32_e32 v108, v0
	v_mov_b32_e32 v109, v0
	v_mov_b32_e32 v110, v0
	v_mov_b32_e32 v111, v0
	v_mov_b32_e32 v120, v0
	v_mov_b32_e32 v121, v0
	v_mov_b32_e32 v122, v0
	v_mov_b32_e32 v123, v0
	v_mov_b32_e32 v124, v0
	v_mov_b32_e32 v125, v0
	v_mov_b32_e32 v126, v0
	v_mov_b32_e32 v127, v0
	s_andn2_b64 vcc, exec, s[4:5]
	s_cbranch_vccnz .LBB0_1105
	s_branch .LBB0_1106

; #define PG8_STAGE(bufoff, gbase, voff) do { _Pragma("unroll") for (int _i = 0; _i < 2; ++_i) \
;         __builtin_amdgcn_global_load_lds((const unsigned*)((const char*)(gbase) + (voff)[_i]), (PG8_LAS unsigned*)(lds + (bufoff) + ldsw + _i * 8192), 16, 0, 0); } while (0)
; #define PG8_LDA(dst, b, h) do { _Pragma("unroll") for (int m = 0; m < 4; ++m) _Pragma("unroll") for (int k = 0; k < 2; ++k) dst[m][k] = *(const PG8_LAS bf16x8*)(lds + PG8_SA(b, h) + aoff + m * 2048 + k * 1024); } while (0)
; #define PG8_LDB(dst, b, h) do { _Pragma("unroll") for (int n = 0; n < 2; ++n) _Pragma("unroll") for (int k = 0; k < 2; ++k) dst[n][k] = *(const PG8_LAS bf16x8*)(lds + PG8_SB(b, h) + boff + n * 2048 + k * 1024); } while (0)
; #define PG8_MMA(ai, bj, At, Bt) do { __builtin_amdgcn_s_setprio(1); _Pragma("unroll") for (int m = 0; m < 4; ++m) _Pragma("unroll") for (int n = 0; n < 2; ++n) _Pragma("unroll") for (int k = 0; k < 2; ++k) \
;         acc[ai][bj][m][n] = __builtin_amdgcn_mfma_f32_16x16x32_bf16(Bt[n][k], At[m][k], acc[ai][bj][m][n], 0, 0, 0); __builtin_amdgcn_s_setprio(0); } while (0)
; #define PG8_WAIT_V(n) asm volatile("s_waitcnt vmcnt(" #n ")" ::: "memory")
; #define PG8_BAR __builtin_amdgcn_s_barrier()
; template <class Epi, class Sched, bool ALIGN_EPI = false, bool SP2 = false>
; __device__ __forceinline__ void gemm_phase(PG8_LAS unsigned char* lds, const Gemm g, const Sched& S, const Epi& E) {
;     ...
;         for (int t = 0; t < nt; t += 2) {
;             const bool last = (t == nt - 2);
;             const char* a1 = cA + (size_t)(t + 1) * kstep;
;             const char* a2 = last ? nA : cA + (size_t)(t + 2) * kstep; const char* b2 = last ? nB : cB + (size_t)(t + 2) * kstep;
;             const char* a3 = a2 + kstep; const char* b3 = b2 + kstep;
;             if (last && has_next) S.a_ready(nxt);
;             if constexpr (SP2) {
;             PG8_LDB(B0, 0, 0); PG8_LDB(B1, 0, 1); PG8_SCHED; PG8_LDA(At, 0, 0); PG8_STAGE(PG8_SA(1, 1), a1 + hstep, voffA);
;             PG8_WAIT_V(8); PG8_WAIT_L(0); PG8_BAR; PG8_MMA(0, 0, At, B0); PG8_MMA(0, 1, At, B1); PG8_BAR; PG8_SCHED;
;             PG8_LDA(At, 0, 1); PG8_STAGE(PG8_SB(0, 0), b2, voffB); PG8_STAGE(PG8_SB(0, 1), b2 + hstep, voffB); PG8_STAGE(PG8_SA(0, 0), a2, voffA);
;             PG8_WAIT_V(8); PG8_WAIT_L(0); PG8_BAR; PG8_MMA(1, 0, At, B0); PG8_MMA(1, 1, At, B1); PG8_BAR; PG8_SCHED;
.LBB0_1271:
	ds_read_b128 v[144:147], v155
	ds_read_b128 v[148:151], v155 offset:1024
	ds_read_b128 v[160:163], v155 offset:2048
	ds_read_b128 v[164:167], v155 offset:3072
	ds_read_b128 v[168:171], v156
	ds_read_b128 v[172:175], v156 offset:1024
	ds_read_b128 v[176:179], v156 offset:2048
	ds_read_b128 v[180:183], v156 offset:3072
	s_add_u32 s36, s34, 0xfffc0080
	s_addc_u32 s37, s35, -1
	s_cmp_eq_u32 s84, 12
	s_cselect_b32 s39, s27, s37
	s_cselect_b32 s38, s80, s36
	s_cselect_b32 s37, s25, s83
	s_cselect_b32 s36, s81, s82
	v_lshl_add_u64 v[218:219], s[34:35], 0, v[136:137]
	s_add_i32 m0, s67, 0xc000
	ds_read_b128 v[184:187], v157
	ds_read_b128 v[188:191], v157 offset:1024
	ds_read_b128 v[192:195], v157 offset:2048
	ds_read_b128 v[196:199], v157 offset:3072
	ds_read_b128 v[200:203], v157 offset:4096
	ds_read_b128 v[204:207], v157 offset:5120
	ds_read_b128 v[210:213], v157 offset:6144
	ds_read_b128 v[214:217], v157 offset:7168
	global_load_lds_dwordx4 v[218:219], off
	v_lshl_add_u64 v[218:219], s[34:35], 0, v[138:139]
	s_add_i32 m0, s67, 0xe000
	s_nop 0
	global_load_lds_dwordx4 v[218:219], off
	s_waitcnt vmcnt(8)
	s_waitcnt lgkmcnt(0)
	s_barrier
	s_setprio 1
	s_waitcnt lgkmcnt(0)
	v_mfma_f32_16x16x32_bf16 v[124:127], v[144:147], v[184:187], v[124:127]
	v_mfma_f32_16x16x32_bf16 v[120:123], v[160:163], v[184:187], v[120:123]
	v_mfma_f32_16x16x32_bf16 v[108:111], v[144:147], v[192:195], v[108:111]
	v_mfma_f32_16x16x32_bf16 v[104:107], v[160:163], v[192:195], v[104:107]
	v_mfma_f32_16x16x32_bf16 v[92:95], v[144:147], v[200:203], v[92:95]
	v_mfma_f32_16x16x32_bf16 v[88:91], v[160:163], v[200:203], v[88:91]
	v_mfma_f32_16x16x32_bf16 v[76:79], v[144:147], v[210:213], v[76:79]
	v_mfma_f32_16x16x32_bf16 v[72:75], v[160:163], v[210:213], v[72:75]
	v_mfma_f32_16x16x32_bf16 v[124:127], v[148:151], v[188:191], v[124:127]
	v_mfma_f32_16x16x32_bf16 v[120:123], v[164:167], v[188:191], v[120:123]
	v_mfma_f32_16x16x32_bf16 v[108:111], v[148:151], v[196:199], v[108:111]
	v_mfma_f32_16x16x32_bf16 v[104:107], v[164:167], v[196:199], v[104:107]
	v_mfma_f32_16x16x32_bf16 v[92:95], v[148:151], v[204:207], v[92:95]
	v_mfma_f32_16x16x32_bf16 v[88:91], v[164:167], v[204:207], v[88:91]
	v_mfma_f32_16x16x32_bf16 v[76:79], v[148:151], v[214:217], v[76:79]
	v_mfma_f32_16x16x32_bf16 v[72:75], v[164:167], v[214:217], v[72:75]
	s_setprio 0
	s_setprio 1
	v_mfma_f32_16x16x32_bf16 v[116:119], v[168:171], v[184:187], v[116:119]
	v_mfma_f32_16x16x32_bf16 v[112:115], v[176:179], v[184:187], v[112:115]
	v_mfma_f32_16x16x32_bf16 v[100:103], v[168:171], v[192:195], v[100:103]
	v_mfma_f32_16x16x32_bf16 v[96:99], v[176:179], v[192:195], v[96:99]
	v_mfma_f32_16x16x32_bf16 v[84:87], v[168:171], v[200:203], v[84:87]
	v_mfma_f32_16x16x32_bf16 v[80:83], v[176:179], v[200:203], v[80:83]
	v_mfma_f32_16x16x32_bf16 v[68:71], v[168:171], v[210:213], v[68:71]
	v_mfma_f32_16x16x32_bf16 v[64:67], v[176:179], v[210:213], v[64:67]
	v_mfma_f32_16x16x32_bf16 v[116:119], v[172:175], v[188:191], v[116:119]
	v_mfma_f32_16x16x32_bf16 v[112:115], v[180:183], v[188:191], v[112:115]
	v_mfma_f32_16x16x32_bf16 v[100:103], v[172:175], v[196:199], v[100:103]
	v_mfma_f32_16x16x32_bf16 v[96:99], v[180:183], v[196:199], v[96:99]
	v_mfma_f32_16x16x32_bf16 v[84:87], v[172:175], v[204:207], v[84:87]
	v_mfma_f32_16x16x32_bf16 v[80:83], v[180:183], v[204:207], v[80:83]
	v_mfma_f32_16x16x32_bf16 v[68:71], v[172:175], v[214:217], v[68:71]
	s_barrier
	v_mfma_f32_16x16x32_bf16 v[64:67], v[180:183], v[214:217], v[64:67]
	s_setprio 0
	s_add_i32 s52, s75, s64
	v_lshl_add_u64 v[218:219], s[36:37], 0, v[130:131]
	s_mov_b32 m0, s52
	ds_read_b128 v[184:187], v157 offset:16384
	ds_read_b128 v[188:191], v157 offset:17408
	ds_read_b128 v[192:195], v157 offset:18432
	ds_read_b128 v[196:199], v157 offset:19456
	ds_read_b128 v[200:203], v157 offset:20480
	ds_read_b128 v[204:207], v157 offset:21504
	ds_read_b128 v[210:213], v157 offset:22528
	ds_read_b128 v[214:217], v157 offset:23552
	global_load_lds_dwordx4 v[218:219], off
	s_add_i32 m0, s52, 0x2000
	s_add_u32 s52, s36, 0x40000
	v_lshl_add_u64 v[220:221], s[36:37], 0, v[134:135]
	s_addc_u32 s53, s37, 0
	s_add_i32 s78, s76, s64
	global_load_lds_dwordx4 v[220:221], off
	v_lshl_add_u64 v[222:223], s[52:53], 0, v[130:131]
	s_mov_b32 m0, s78
	v_lshl_add_u64 v[224:225], s[38:39], 0, v[132:133]
	global_load_lds_dwordx4 v[222:223], off
	v_lshl_add_u64 v[222:223], s[52:53], 0, v[134:135]
	s_add_i32 m0, s78, 0x2000
	s_nop 0
	global_load_lds_dwordx4 v[222:223], off
	v_lshl_add_u64 v[222:223], s[38:39], 0, v[128:129]
	s_mov_b32 m0, s67
	s_nop 0
	global_load_lds_dwordx4 v[222:223], off
	s_mov_b32 m0, s68
	s_nop 0
	global_load_lds_dwordx4 v[224:225], off
	s_waitcnt vmcnt(8)
	s_waitcnt lgkmcnt(0)
	s_barrier
; #define PG8_STAGE(bufoff, gbase, voff) do { _Pragma("unroll") for (int _i = 0; _i < 2; ++_i) \
;         __builtin_amdgcn_global_load_lds((const unsigned*)((const char*)(gbase) + (voff)[_i]), (PG8_LAS unsigned*)(lds + (bufoff) + ldsw + _i * 8192), 16, 0, 0); } while (0)
; #define PG8_LDA(dst, b, h) do { _Pragma("unroll") for (int m = 0; m < 4; ++m) _Pragma("unroll") for (int k = 0; k < 2; ++k) dst[m][k] = *(const PG8_LAS bf16x8*)(lds + PG8_SA(b, h) + aoff + m * 2048 + k * 1024); } while (0)
; #define PG8_LDB(dst, b, h) do { _Pragma("unroll") for (int n = 0; n < 2; ++n) _Pragma("unroll") for (int k = 0; k < 2; ++k) dst[n][k] = *(const PG8_LAS bf16x8*)(lds + PG8_SB(b, h) + boff + n * 2048 + k * 1024); } while (0)
; #define PG8_MMA(ai, bj, At, Bt) do { __builtin_amdgcn_s_setprio(1); _Pragma("unroll") for (int m = 0; m < 4; ++m) _Pragma("unroll") for (int n = 0; n < 2; ++n) _Pragma("unroll") for (int k = 0; k < 2; ++k) \
;         acc[ai][bj][m][n] = __builtin_amdgcn_mfma_f32_16x16x32_bf16(Bt[n][k], At[m][k], acc[ai][bj][m][n], 0, 0, 0); __builtin_amdgcn_s_setprio(0); } while (0)
; #define PG8_WAIT_V(n) asm volatile("s_waitcnt vmcnt(" #n ")" ::: "memory")
; #define PG8_WAIT_L(n) asm volatile("s_waitcnt lgkmcnt(" #n ")" ::: "memory")
; #define PG8_BAR __builtin_amdgcn_s_barrier()
; #define PG8_SCHED __builtin_amdgcn_sched_barrier(0)
; template <class Epi, class Sched, bool ALIGN_EPI = false, bool SP2 = false>
; __device__ __forceinline__ void gemm_phase(PG8_LAS unsigned char* lds, const Gemm g, const Sched& S, const Epi& E) {
;     ...
;             PG8_WAIT_V(8); PG8_WAIT_L(0); PG8_BAR; PG8_MMA(1, 0, At, B0); PG8_MMA(1, 1, At, B1); PG8_BAR; PG8_SCHED;
;             PG8_LDB(B0, 1, 0); PG8_LDB(B1, 1, 1); PG8_SCHED; PG8_LDA(At, 1, 0); PG8_STAGE(PG8_SA(0, 1), a2 + hstep, voffA);
;             PG8_WAIT_V(8); PG8_WAIT_L(0); PG8_BAR; PG8_MMA(0, 0, At, B0); PG8_MMA(0, 1, At, B1); PG8_BAR; PG8_SCHED;
;             PG8_LDA(At, 1, 1); PG8_STAGE(PG8_SB(1, 0), b3, voffB); PG8_STAGE(PG8_SB(1, 1), b3 + hstep, voffB); PG8_STAGE(PG8_SA(1, 0), a3, voffA);
	s_setprio 1
	s_waitcnt lgkmcnt(0)
	v_mfma_f32_16x16x32_bf16 v[60:63], v[144:147], v[184:187], v[60:63]
	v_mfma_f32_16x16x32_bf16 v[56:59], v[160:163], v[184:187], v[56:59]
	v_mfma_f32_16x16x32_bf16 v[44:47], v[144:147], v[192:195], v[44:47]
	v_mfma_f32_16x16x32_bf16 v[40:43], v[160:163], v[192:195], v[40:43]
	v_mfma_f32_16x16x32_bf16 v[28:31], v[144:147], v[200:203], v[28:31]
	v_mfma_f32_16x16x32_bf16 v[24:27], v[160:163], v[200:203], v[24:27]
	v_mfma_f32_16x16x32_bf16 v[12:15], v[144:147], v[210:213], v[12:15]
	v_mfma_f32_16x16x32_bf16 v[8:11], v[160:163], v[210:213], v[8:11]
	v_mfma_f32_16x16x32_bf16 v[60:63], v[148:151], v[188:191], v[60:63]
	v_mfma_f32_16x16x32_bf16 v[56:59], v[164:167], v[188:191], v[56:59]
	v_mfma_f32_16x16x32_bf16 v[44:47], v[148:151], v[196:199], v[44:47]
	v_mfma_f32_16x16x32_bf16 v[40:43], v[164:167], v[196:199], v[40:43]
	v_mfma_f32_16x16x32_bf16 v[28:31], v[148:151], v[204:207], v[28:31]
	v_mfma_f32_16x16x32_bf16 v[24:27], v[164:167], v[204:207], v[24:27]
	v_mfma_f32_16x16x32_bf16 v[12:15], v[148:151], v[214:217], v[12:15]
	v_mfma_f32_16x16x32_bf16 v[8:11], v[164:167], v[214:217], v[8:11]
	s_setprio 0
	s_setprio 1
	v_mfma_f32_16x16x32_bf16 v[52:55], v[168:171], v[184:187], v[52:55]
	v_mfma_f32_16x16x32_bf16 v[48:51], v[176:179], v[184:187], v[48:51]
	v_mfma_f32_16x16x32_bf16 v[36:39], v[168:171], v[192:195], v[36:39]
	v_mfma_f32_16x16x32_bf16 v[32:35], v[176:179], v[192:195], v[32:35]
	v_mfma_f32_16x16x32_bf16 v[20:23], v[168:171], v[200:203], v[20:23]
	v_mfma_f32_16x16x32_bf16 v[16:19], v[176:179], v[200:203], v[16:19]
	v_mfma_f32_16x16x32_bf16 v[4:7], v[168:171], v[210:213], v[4:7]
	v_mfma_f32_16x16x32_bf16 v[0:3], v[176:179], v[210:213], v[0:3]
	v_mfma_f32_16x16x32_bf16 v[52:55], v[172:175], v[188:191], v[52:55]
	v_mfma_f32_16x16x32_bf16 v[48:51], v[180:183], v[188:191], v[48:51]
	v_mfma_f32_16x16x32_bf16 v[36:39], v[172:175], v[196:199], v[36:39]
	v_mfma_f32_16x16x32_bf16 v[32:35], v[180:183], v[196:199], v[32:35]
	v_mfma_f32_16x16x32_bf16 v[20:23], v[172:175], v[204:207], v[20:23]
	v_mfma_f32_16x16x32_bf16 v[16:19], v[180:183], v[204:207], v[16:19]
	v_mfma_f32_16x16x32_bf16 v[4:7], v[172:175], v[214:217], v[4:7]
	s_barrier
	v_mfma_f32_16x16x32_bf16 v[0:3], v[180:183], v[214:217], v[0:3]
	s_setprio 0
	s_add_i32 s52, 0, 0x18000
	v_add_u32_e32 v159, s52, v153
	s_add_i32 s53, 0, 0x1c000
	ds_read_b128 v[144:147], v159
	ds_read_b128 v[148:151], v159 offset:1024
	ds_read_b128 v[160:163], v159 offset:2048
	ds_read_b128 v[164:167], v159 offset:3072
	v_add_u32_e32 v159, s53, v153
	ds_read_b128 v[168:171], v159
	ds_read_b128 v[172:175], v159 offset:1024
	ds_read_b128 v[176:179], v159 offset:2048
	ds_read_b128 v[180:183], v159 offset:3072
	s_add_u32 s38, s38, 0x40000
	s_addc_u32 s39, s39, 0
	s_mov_b32 m0, s69
	v_lshl_add_u64 v[226:227], s[38:39], 0, v[128:129]
	ds_read_b128 v[184:187], v157 offset:32768
	ds_read_b128 v[188:191], v157 offset:33792
	ds_read_b128 v[192:195], v157 offset:34816
	ds_read_b128 v[196:199], v157 offset:35840
	ds_read_b128 v[200:203], v157 offset:36864
	ds_read_b128 v[204:207], v157 offset:37888
	ds_read_b128 v[210:213], v157 offset:38912
	ds_read_b128 v[214:217], v157 offset:39936
	global_load_lds_dwordx4 v[226:227], off
	v_lshl_add_u64 v[226:227], s[38:39], 0, v[132:133]
	s_mov_b32 m0, s70
	s_nop 0
	global_load_lds_dwordx4 v[226:227], off
	s_waitcnt vmcnt(8)
	s_waitcnt lgkmcnt(0)
	s_barrier
	s_setprio 1
	s_waitcnt lgkmcnt(0)
	v_mfma_f32_16x16x32_bf16 v[124:127], v[144:147], v[184:187], v[124:127]
	v_mfma_f32_16x16x32_bf16 v[120:123], v[160:163], v[184:187], v[120:123]
	v_mfma_f32_16x16x32_bf16 v[108:111], v[144:147], v[192:195], v[108:111]
	v_mfma_f32_16x16x32_bf16 v[104:107], v[160:163], v[192:195], v[104:107]
	v_mfma_f32_16x16x32_bf16 v[92:95], v[144:147], v[200:203], v[92:95]
	v_mfma_f32_16x16x32_bf16 v[88:91], v[160:163], v[200:203], v[88:91]
	v_mfma_f32_16x16x32_bf16 v[76:79], v[144:147], v[210:213], v[76:79]
	v_mfma_f32_16x16x32_bf16 v[72:75], v[160:163], v[210:213], v[72:75]
	v_mfma_f32_16x16x32_bf16 v[124:127], v[148:151], v[188:191], v[124:127]
	v_mfma_f32_16x16x32_bf16 v[120:123], v[164:167], v[188:191], v[120:123]
	v_mfma_f32_16x16x32_bf16 v[108:111], v[148:151], v[196:199], v[108:111]
	v_mfma_f32_16x16x32_bf16 v[104:107], v[164:167], v[196:199], v[104:107]
	v_mfma_f32_16x16x32_bf16 v[92:95], v[148:151], v[204:207], v[92:95]
	v_mfma_f32_16x16x32_bf16 v[88:91], v[164:167], v[204:207], v[88:91]
	v_mfma_f32_16x16x32_bf16 v[76:79], v[148:151], v[214:217], v[76:79]
	v_mfma_f32_16x16x32_bf16 v[72:75], v[164:167], v[214:217], v[72:75]
	s_setprio 0
	s_setprio 1
	v_mfma_f32_16x16x32_bf16 v[116:119], v[168:171], v[184:187], v[116:119]
	v_mfma_f32_16x16x32_bf16 v[112:115], v[176:179], v[184:187], v[112:115]
	v_mfma_f32_16x16x32_bf16 v[100:103], v[168:171], v[192:195], v[100:103]
	v_mfma_f32_16x16x32_bf16 v[96:99], v[176:179], v[192:195], v[96:99]
	v_mfma_f32_16x16x32_bf16 v[84:87], v[168:171], v[200:203], v[84:87]
	v_mfma_f32_16x16x32_bf16 v[80:83], v[176:179], v[200:203], v[80:83]
	v_mfma_f32_16x16x32_bf16 v[68:71], v[168:171], v[210:213], v[68:71]
	v_mfma_f32_16x16x32_bf16 v[64:67], v[176:179], v[210:213], v[64:67]
	v_mfma_f32_16x16x32_bf16 v[116:119], v[172:175], v[188:191], v[116:119]
	v_mfma_f32_16x16x32_bf16 v[112:115], v[180:183], v[188:191], v[112:115]
	v_mfma_f32_16x16x32_bf16 v[100:103], v[172:175], v[196:199], v[100:103]
	v_mfma_f32_16x16x32_bf16 v[96:99], v[180:183], v[196:199], v[96:99]
	v_mfma_f32_16x16x32_bf16 v[84:87], v[172:175], v[204:207], v[84:87]
	v_mfma_f32_16x16x32_bf16 v[80:83], v[180:183], v[204:207], v[80:83]
	v_mfma_f32_16x16x32_bf16 v[68:71], v[172:175], v[214:217], v[68:71]
	s_barrier
; #define PG8_STAGE(bufoff, gbase, voff) do { _Pragma("unroll") for (int _i = 0; _i < 2; ++_i) \
;         __builtin_amdgcn_global_load_lds((const unsigned*)((const char*)(gbase) + (voff)[_i]), (PG8_LAS unsigned*)(lds + (bufoff) + ldsw + _i * 8192), 16, 0, 0); } while (0)
; #define PG8_LDA(dst, b, h) do { _Pragma("unroll") for (int m = 0; m < 4; ++m) _Pragma("unroll") for (int k = 0; k < 2; ++k) dst[m][k] = *(const PG8_LAS bf16x8*)(lds + PG8_SA(b, h) + aoff + m * 2048 + k * 1024); } while (0)
; #define PG8_MMA(ai, bj, At, Bt) do { __builtin_amdgcn_s_setprio(1); _Pragma("unroll") for (int m = 0; m < 4; ++m) _Pragma("unroll") for (int n = 0; n < 2; ++n) _Pragma("unroll") for (int k = 0; k < 2; ++k) \
;         acc[ai][bj][m][n] = __builtin_amdgcn_mfma_f32_16x16x32_bf16(Bt[n][k], At[m][k], acc[ai][bj][m][n], 0, 0, 0); __builtin_amdgcn_s_setprio(0); } while (0)
; #define PG8_WAIT_V(n) asm volatile("s_waitcnt vmcnt(" #n ")" ::: "memory")
; #define PG8_WAIT_L(n) asm volatile("s_waitcnt lgkmcnt(" #n ")" ::: "memory")
; #define PG8_BAR __builtin_amdgcn_s_barrier()
; #define PG8_SCHED __builtin_amdgcn_sched_barrier(0)
; template <class Epi, class Sched, bool ALIGN_EPI = false, bool SP2 = false>
; __device__ __forceinline__ void gemm_phase(PG8_LAS unsigned char* lds, const Gemm g, const Sched& S, const Epi& E) {
;     ...
;             PG8_WAIT_V(8); PG8_WAIT_L(0); PG8_BAR; PG8_MMA(0, 0, At, B0); PG8_MMA(0, 1, At, B1); PG8_BAR; PG8_SCHED;
;             PG8_LDA(At, 1, 1); PG8_STAGE(PG8_SB(1, 0), b3, voffB); PG8_STAGE(PG8_SB(1, 1), b3 + hstep, voffB); PG8_STAGE(PG8_SA(1, 0), a3, voffA);
;             PG8_WAIT_V(8); PG8_WAIT_L(0); PG8_BAR; PG8_MMA(1, 0, At, B0); PG8_MMA(1, 1, At, B1); PG8_BAR; PG8_SCHED;
;     ...
;         if constexpr (ALIGN_EPI) { if (wr == 0) PG8_BAR; }
	v_mfma_f32_16x16x32_bf16 v[64:67], v[180:183], v[214:217], v[64:67]
	s_setprio 0
	s_add_i32 s38, s52, s64
	v_lshl_add_u64 v[218:219], v[218:219], 0, s[16:17]
	s_mov_b32 m0, s38
	ds_read_b128 v[184:187], v157 offset:49152
	ds_read_b128 v[188:191], v157 offset:50176
	ds_read_b128 v[192:195], v157 offset:51200
	ds_read_b128 v[196:199], v157 offset:52224
	ds_read_b128 v[200:203], v157 offset:53248
	ds_read_b128 v[204:207], v157 offset:54272
	ds_read_b128 v[210:213], v157 offset:55296
	ds_read_b128 v[214:217], v157 offset:56320
	global_load_lds_dwordx4 v[218:219], off
	s_add_i32 m0, s38, 0x2000
	s_add_u32 s36, s36, 0x40080
	v_lshl_add_u64 v[218:219], v[220:221], 0, s[16:17]
	s_addc_u32 s37, s37, 0
	s_add_i32 s38, s53, s64
	global_load_lds_dwordx4 v[218:219], off
	v_lshl_add_u64 v[218:219], s[36:37], 0, v[130:131]
	s_mov_b32 m0, s38
	s_nop 0
	global_load_lds_dwordx4 v[218:219], off
	v_lshl_add_u64 v[218:219], s[36:37], 0, v[134:135]
	s_add_i32 m0, s38, 0x2000
	s_nop 0
	global_load_lds_dwordx4 v[218:219], off
	v_lshl_add_u64 v[218:219], v[222:223], 0, s[16:17]
	s_mov_b32 m0, s72
	s_nop 0
	global_load_lds_dwordx4 v[218:219], off
	v_lshl_add_u64 v[218:219], v[224:225], 0, s[16:17]
	s_mov_b32 m0, s73
	s_nop 0
	global_load_lds_dwordx4 v[218:219], off
	s_waitcnt vmcnt(8)
	s_waitcnt lgkmcnt(0)
	s_barrier
	s_setprio 1
	s_waitcnt lgkmcnt(0)
	v_mfma_f32_16x16x32_bf16 v[60:63], v[144:147], v[184:187], v[60:63]
	v_mfma_f32_16x16x32_bf16 v[56:59], v[160:163], v[184:187], v[56:59]
	v_mfma_f32_16x16x32_bf16 v[44:47], v[144:147], v[192:195], v[44:47]
	v_mfma_f32_16x16x32_bf16 v[40:43], v[160:163], v[192:195], v[40:43]
	v_mfma_f32_16x16x32_bf16 v[28:31], v[144:147], v[200:203], v[28:31]
	v_mfma_f32_16x16x32_bf16 v[24:27], v[160:163], v[200:203], v[24:27]
	v_mfma_f32_16x16x32_bf16 v[12:15], v[144:147], v[210:213], v[12:15]
	v_mfma_f32_16x16x32_bf16 v[8:11], v[160:163], v[210:213], v[8:11]
	v_mfma_f32_16x16x32_bf16 v[60:63], v[148:151], v[188:191], v[60:63]
	v_mfma_f32_16x16x32_bf16 v[56:59], v[164:167], v[188:191], v[56:59]
	v_mfma_f32_16x16x32_bf16 v[44:47], v[148:151], v[196:199], v[44:47]
	v_mfma_f32_16x16x32_bf16 v[40:43], v[164:167], v[196:199], v[40:43]
	v_mfma_f32_16x16x32_bf16 v[28:31], v[148:151], v[204:207], v[28:31]
	v_mfma_f32_16x16x32_bf16 v[24:27], v[164:167], v[204:207], v[24:27]
	v_mfma_f32_16x16x32_bf16 v[12:15], v[148:151], v[214:217], v[12:15]
	v_mfma_f32_16x16x32_bf16 v[8:11], v[164:167], v[214:217], v[8:11]
	s_setprio 0
	s_setprio 1
	v_mfma_f32_16x16x32_bf16 v[52:55], v[168:171], v[184:187], v[52:55]
	v_mfma_f32_16x16x32_bf16 v[48:51], v[176:179], v[184:187], v[48:51]
	v_mfma_f32_16x16x32_bf16 v[36:39], v[168:171], v[192:195], v[36:39]
	v_mfma_f32_16x16x32_bf16 v[32:35], v[176:179], v[192:195], v[32:35]
	v_mfma_f32_16x16x32_bf16 v[20:23], v[168:171], v[200:203], v[20:23]
	v_mfma_f32_16x16x32_bf16 v[16:19], v[176:179], v[200:203], v[16:19]
	v_mfma_f32_16x16x32_bf16 v[4:7], v[168:171], v[210:213], v[4:7]
	v_mfma_f32_16x16x32_bf16 v[0:3], v[176:179], v[210:213], v[0:3]
	v_mfma_f32_16x16x32_bf16 v[52:55], v[172:175], v[188:191], v[52:55]
	v_mfma_f32_16x16x32_bf16 v[48:51], v[180:183], v[188:191], v[48:51]
	v_mfma_f32_16x16x32_bf16 v[36:39], v[172:175], v[196:199], v[36:39]
	v_mfma_f32_16x16x32_bf16 v[32:35], v[180:183], v[196:199], v[32:35]
	v_mfma_f32_16x16x32_bf16 v[20:23], v[172:175], v[204:207], v[20:23]
	v_mfma_f32_16x16x32_bf16 v[16:19], v[180:183], v[204:207], v[16:19]
	v_mfma_f32_16x16x32_bf16 v[4:7], v[172:175], v[214:217], v[4:7]
	s_barrier
	v_mfma_f32_16x16x32_bf16 v[0:3], v[180:183], v[214:217], v[0:3]
	s_setprio 0
	s_add_i32 s84, s84, 2
	s_add_u32 s34, s34, 0x100
	s_addc_u32 s35, s35, 0
	s_add_u32 s82, s82, 0x100
	s_addc_u32 s83, s83, 0
	s_cmp_gt_u32 s84, 13
	s_cbranch_scc0 .LBB0_1271
	s_and_b64 vcc, exec, s[18:19]
	s_cbranch_vccz .LBB0_1274
	s_barrier

; #define PG8_STAGE(bufoff, gbase, voff) do { _Pragma("unroll") for (int _i = 0; _i < 2; ++_i) \
;         __builtin_amdgcn_global_load_lds((const unsigned*)((const char*)(gbase) + (voff)[_i]), (PG8_LAS unsigned*)(lds + (bufoff) + ldsw + _i * 8192), 16, 0, 0); } while (0)
; #define PG8_LDA(dst, b, h) do { _Pragma("unroll") for (int m = 0; m < 4; ++m) _Pragma("unroll") for (int k = 0; k < 2; ++k) dst[m][k] = *(const PG8_LAS bf16x8*)(lds + PG8_SA(b, h) + aoff + m * 2048 + k * 1024); } while (0)
; #define PG8_LDB(dst, b, h) do { _Pragma("unroll") for (int n = 0; n < 2; ++n) _Pragma("unroll") for (int k = 0; k < 2; ++k) dst[n][k] = *(const PG8_LAS bf16x8*)(lds + PG8_SB(b, h) + boff + n * 2048 + k * 1024); } while (0)
; #define PG8_MMA(ai, bj, At, Bt) do { __builtin_amdgcn_s_setprio(1); _Pragma("unroll") for (int m = 0; m < 4; ++m) _Pragma("unroll") for (int n = 0; n < 2; ++n) _Pragma("unroll") for (int k = 0; k < 2; ++k) \
;         acc[ai][bj][m][n] = __builtin_amdgcn_mfma_f32_16x16x32_bf16(Bt[n][k], At[m][k], acc[ai][bj][m][n], 0, 0, 0); __builtin_amdgcn_s_setprio(0); } while (0)
; #define PG8_WAIT_V(n) asm volatile("s_waitcnt vmcnt(" #n ")" ::: "memory")
; #define PG8_BAR __builtin_amdgcn_s_barrier()
; template <class Epi, class Sched, bool ALIGN_EPI = false, bool SP2 = false>
; __device__ __forceinline__ void gemm_phase(PG8_LAS unsigned char* lds, const Gemm g, const Sched& S, const Epi& E) {
;     ...
;         for (int t = 0; t < nt; t += 2) {
;             const bool last = (t == nt - 2);
;             const char* a1 = cA + (size_t)(t + 1) * kstep;
;             const char* a2 = last ? nA : cA + (size_t)(t + 2) * kstep; const char* b2 = last ? nB : cB + (size_t)(t + 2) * kstep;
;             const char* a3 = a2 + kstep; const char* b3 = b2 + kstep;
;             if (last && has_next) S.a_ready(nxt);
;             if constexpr (SP2) {
;             PG8_LDB(B0, 0, 0); PG8_LDB(B1, 0, 1); PG8_SCHED; PG8_LDA(At, 0, 0); PG8_STAGE(PG8_SA(1, 1), a1 + hstep, voffA);
;             PG8_WAIT_V(8); PG8_WAIT_L(0); PG8_BAR; PG8_MMA(0, 0, At, B0); PG8_MMA(0, 1, At, B1); PG8_BAR; PG8_SCHED;
;             PG8_LDA(At, 0, 1); PG8_STAGE(PG8_SB(0, 0), b2, voffB); PG8_STAGE(PG8_SB(0, 1), b2 + hstep, voffB); PG8_STAGE(PG8_SA(0, 0), a2, voffA);
;             PG8_WAIT_V(8); PG8_WAIT_L(0); PG8_BAR; PG8_MMA(1, 0, At, B0); PG8_MMA(1, 1, At, B1); PG8_BAR; PG8_SCHED;
.LBB0_1430:
	v_add_u32_e32 v153, s41, v151
	ds_read_b128 v[154:157], v153
	ds_read_b128 v[158:161], v153 offset:1024
	ds_read_b128 v[162:165], v153 offset:2048
	ds_read_b128 v[166:169], v153 offset:3072
	v_add_u32_e32 v153, s42, v151
	s_add_u32 s20, s12, s18
	ds_read_b128 v[170:173], v153
	ds_read_b128 v[174:177], v153 offset:1024
	ds_read_b128 v[178:181], v153 offset:2048
	ds_read_b128 v[182:185], v153 offset:3072
	s_addc_u32 s21, s13, s19
	s_add_u32 s20, s20, 0x100
	s_addc_u32 s21, s21, 0
	s_add_u32 s51, s46, s18
	s_addc_u32 s52, s47, s19
	s_cmpk_eq_i32 s18, 0x1500
	s_cselect_b32 s23, s17, s21
	s_cselect_b32 s22, s16, s20
	s_cselect_b32 s21, s5, s52
	s_cselect_b32 s20, s4, s51
	v_lshl_add_u64 v[206:207], v[144:145], 0, s[18:19]
	s_add_i32 m0, s31, 0xc000
	ds_read_b128 v[186:189], v152
	ds_read_b128 v[190:193], v152 offset:1024
	ds_read_b128 v[194:197], v152 offset:2048
	ds_read_b128 v[198:201], v152 offset:3072
	ds_read_b128 v[202:205], v152 offset:4096
	ds_read_b128 v[210:213], v152 offset:5120
	ds_read_b128 v[214:217], v152 offset:6144
	ds_read_b128 v[218:221], v152 offset:7168
	global_load_lds_dwordx4 v[206:207], off
	v_lshl_add_u64 v[206:207], v[146:147], 0, s[18:19]
	s_add_i32 m0, s31, 0xe000
	s_nop 0
	global_load_lds_dwordx4 v[206:207], off
	s_waitcnt vmcnt(8)
	s_waitcnt lgkmcnt(0)
	s_barrier
	s_setprio 1
	s_waitcnt lgkmcnt(0)
	v_mfma_f32_16x16x32_bf16 v[124:127], v[154:157], v[186:189], v[124:127]
	v_mfma_f32_16x16x32_bf16 v[120:123], v[162:165], v[186:189], v[120:123]
	v_mfma_f32_16x16x32_bf16 v[108:111], v[154:157], v[194:197], v[108:111]
	v_mfma_f32_16x16x32_bf16 v[104:107], v[162:165], v[194:197], v[104:107]
	v_mfma_f32_16x16x32_bf16 v[92:95], v[154:157], v[202:205], v[92:95]
	v_mfma_f32_16x16x32_bf16 v[88:91], v[162:165], v[202:205], v[88:91]
	v_mfma_f32_16x16x32_bf16 v[76:79], v[154:157], v[214:217], v[76:79]
	v_mfma_f32_16x16x32_bf16 v[72:75], v[162:165], v[214:217], v[72:75]
	v_mfma_f32_16x16x32_bf16 v[124:127], v[158:161], v[190:193], v[124:127]
	v_mfma_f32_16x16x32_bf16 v[120:123], v[166:169], v[190:193], v[120:123]
	v_mfma_f32_16x16x32_bf16 v[108:111], v[158:161], v[198:201], v[108:111]
	v_mfma_f32_16x16x32_bf16 v[104:107], v[166:169], v[198:201], v[104:107]
	v_mfma_f32_16x16x32_bf16 v[92:95], v[158:161], v[210:213], v[92:95]
	v_mfma_f32_16x16x32_bf16 v[88:91], v[166:169], v[210:213], v[88:91]
	v_mfma_f32_16x16x32_bf16 v[76:79], v[158:161], v[218:221], v[76:79]
	v_mfma_f32_16x16x32_bf16 v[72:75], v[166:169], v[218:221], v[72:75]
	s_setprio 0
	s_setprio 1
	v_mfma_f32_16x16x32_bf16 v[116:119], v[170:173], v[186:189], v[116:119]
	v_mfma_f32_16x16x32_bf16 v[112:115], v[178:181], v[186:189], v[112:115]
	v_mfma_f32_16x16x32_bf16 v[100:103], v[170:173], v[194:197], v[100:103]
	v_mfma_f32_16x16x32_bf16 v[96:99], v[178:181], v[194:197], v[96:99]
	v_mfma_f32_16x16x32_bf16 v[84:87], v[170:173], v[202:205], v[84:87]
	v_mfma_f32_16x16x32_bf16 v[80:83], v[178:181], v[202:205], v[80:83]
	v_mfma_f32_16x16x32_bf16 v[68:71], v[170:173], v[214:217], v[68:71]
	v_mfma_f32_16x16x32_bf16 v[64:67], v[178:181], v[214:217], v[64:67]
	v_mfma_f32_16x16x32_bf16 v[116:119], v[174:177], v[190:193], v[116:119]
	v_mfma_f32_16x16x32_bf16 v[112:115], v[182:185], v[190:193], v[112:115]
	v_mfma_f32_16x16x32_bf16 v[100:103], v[174:177], v[198:201], v[100:103]
	v_mfma_f32_16x16x32_bf16 v[96:99], v[182:185], v[198:201], v[96:99]
	v_mfma_f32_16x16x32_bf16 v[84:87], v[174:177], v[210:213], v[84:87]
	v_mfma_f32_16x16x32_bf16 v[80:83], v[182:185], v[210:213], v[80:83]
	v_mfma_f32_16x16x32_bf16 v[68:71], v[174:177], v[218:221], v[68:71]
	s_barrier
	v_mfma_f32_16x16x32_bf16 v[64:67], v[182:185], v[218:221], v[64:67]
	s_setprio 0
	s_add_i32 s51, s41, s30
	v_lshl_add_u64 v[206:207], s[20:21], 0, v[130:131]
	s_mov_b32 m0, s51
	ds_read_b128 v[186:189], v152 offset:16384
	ds_read_b128 v[190:193], v152 offset:17408
	ds_read_b128 v[194:197], v152 offset:18432
	ds_read_b128 v[198:201], v152 offset:19456
	ds_read_b128 v[202:205], v152 offset:20480
	ds_read_b128 v[210:213], v152 offset:21504
	ds_read_b128 v[214:217], v152 offset:22528
	ds_read_b128 v[218:221], v152 offset:23552
	global_load_lds_dwordx4 v[206:207], off
	s_add_i32 m0, s51, 0x2000
	s_add_u32 s52, s20, 0xb0000
	v_lshl_add_u64 v[222:223], s[20:21], 0, v[134:135]
	s_addc_u32 s53, s21, 0
	s_add_i32 s51, s42, s30
	global_load_lds_dwordx4 v[222:223], off
	v_lshl_add_u64 v[224:225], s[52:53], 0, v[130:131]
	s_mov_b32 m0, s51
	v_lshl_add_u64 v[226:227], s[22:23], 0, v[132:133]
	global_load_lds_dwordx4 v[224:225], off
	v_lshl_add_u64 v[224:225], s[52:53], 0, v[134:135]
	s_add_i32 m0, s51, 0x2000
	s_nop 0
	global_load_lds_dwordx4 v[224:225], off
	v_lshl_add_u64 v[224:225], s[22:23], 0, v[128:129]
	s_mov_b32 m0, s31
	s_nop 0
	global_load_lds_dwordx4 v[224:225], off
	s_mov_b32 m0, s33
	s_nop 0
	global_load_lds_dwordx4 v[226:227], off
	s_waitcnt vmcnt(8)
	s_waitcnt lgkmcnt(0)
	s_barrier
; #define PG8_STAGE(bufoff, gbase, voff) do { _Pragma("unroll") for (int _i = 0; _i < 2; ++_i) \
;         __builtin_amdgcn_global_load_lds((const unsigned*)((const char*)(gbase) + (voff)[_i]), (PG8_LAS unsigned*)(lds + (bufoff) + ldsw + _i * 8192), 16, 0, 0); } while (0)
; #define PG8_LDA(dst, b, h) do { _Pragma("unroll") for (int m = 0; m < 4; ++m) _Pragma("unroll") for (int k = 0; k < 2; ++k) dst[m][k] = *(const PG8_LAS bf16x8*)(lds + PG8_SA(b, h) + aoff + m * 2048 + k * 1024); } while (0)
; #define PG8_LDB(dst, b, h) do { _Pragma("unroll") for (int n = 0; n < 2; ++n) _Pragma("unroll") for (int k = 0; k < 2; ++k) dst[n][k] = *(const PG8_LAS bf16x8*)(lds + PG8_SB(b, h) + boff + n * 2048 + k * 1024); } while (0)
; #define PG8_MMA(ai, bj, At, Bt) do { __builtin_amdgcn_s_setprio(1); _Pragma("unroll") for (int m = 0; m < 4; ++m) _Pragma("unroll") for (int n = 0; n < 2; ++n) _Pragma("unroll") for (int k = 0; k < 2; ++k) \
;         acc[ai][bj][m][n] = __builtin_amdgcn_mfma_f32_16x16x32_bf16(Bt[n][k], At[m][k], acc[ai][bj][m][n], 0, 0, 0); __builtin_amdgcn_s_setprio(0); } while (0)
; #define PG8_WAIT_V(n) asm volatile("s_waitcnt vmcnt(" #n ")" ::: "memory")
; #define PG8_WAIT_L(n) asm volatile("s_waitcnt lgkmcnt(" #n ")" ::: "memory")
; #define PG8_BAR __builtin_amdgcn_s_barrier()
; #define PG8_SCHED __builtin_amdgcn_sched_barrier(0)
; template <class Epi, class Sched, bool ALIGN_EPI = false, bool SP2 = false>
; __device__ __forceinline__ void gemm_phase(PG8_LAS unsigned char* lds, const Gemm g, const Sched& S, const Epi& E) {
;     ...
;             PG8_WAIT_V(8); PG8_WAIT_L(0); PG8_BAR; PG8_MMA(1, 0, At, B0); PG8_MMA(1, 1, At, B1); PG8_BAR; PG8_SCHED;
;             PG8_LDB(B0, 1, 0); PG8_LDB(B1, 1, 1); PG8_SCHED; PG8_LDA(At, 1, 0); PG8_STAGE(PG8_SA(0, 1), a2 + hstep, voffA);
;             PG8_WAIT_V(8); PG8_WAIT_L(0); PG8_BAR; PG8_MMA(0, 0, At, B0); PG8_MMA(0, 1, At, B1); PG8_BAR; PG8_SCHED;
;             PG8_LDA(At, 1, 1); PG8_STAGE(PG8_SB(1, 0), b3, voffB); PG8_STAGE(PG8_SB(1, 1), b3 + hstep, voffB); PG8_STAGE(PG8_SA(1, 0), a3, voffA);
	s_setprio 1
	s_waitcnt lgkmcnt(0)
	v_mfma_f32_16x16x32_bf16 v[60:63], v[154:157], v[186:189], v[60:63]
	v_mfma_f32_16x16x32_bf16 v[56:59], v[162:165], v[186:189], v[56:59]
	v_mfma_f32_16x16x32_bf16 v[44:47], v[154:157], v[194:197], v[44:47]
	v_mfma_f32_16x16x32_bf16 v[40:43], v[162:165], v[194:197], v[40:43]
	v_mfma_f32_16x16x32_bf16 v[28:31], v[154:157], v[202:205], v[28:31]
	v_mfma_f32_16x16x32_bf16 v[24:27], v[162:165], v[202:205], v[24:27]
	v_mfma_f32_16x16x32_bf16 v[12:15], v[154:157], v[214:217], v[12:15]
	v_mfma_f32_16x16x32_bf16 v[8:11], v[162:165], v[214:217], v[8:11]
	v_mfma_f32_16x16x32_bf16 v[60:63], v[158:161], v[190:193], v[60:63]
	v_mfma_f32_16x16x32_bf16 v[56:59], v[166:169], v[190:193], v[56:59]
	v_mfma_f32_16x16x32_bf16 v[44:47], v[158:161], v[198:201], v[44:47]
	v_mfma_f32_16x16x32_bf16 v[40:43], v[166:169], v[198:201], v[40:43]
	v_mfma_f32_16x16x32_bf16 v[28:31], v[158:161], v[210:213], v[28:31]
	v_mfma_f32_16x16x32_bf16 v[24:27], v[166:169], v[210:213], v[24:27]
	v_mfma_f32_16x16x32_bf16 v[12:15], v[158:161], v[218:221], v[12:15]
	v_mfma_f32_16x16x32_bf16 v[8:11], v[166:169], v[218:221], v[8:11]
	s_setprio 0
	s_setprio 1
	v_mfma_f32_16x16x32_bf16 v[52:55], v[170:173], v[186:189], v[52:55]
	v_mfma_f32_16x16x32_bf16 v[48:51], v[178:181], v[186:189], v[48:51]
	v_mfma_f32_16x16x32_bf16 v[36:39], v[170:173], v[194:197], v[36:39]
	v_mfma_f32_16x16x32_bf16 v[32:35], v[178:181], v[194:197], v[32:35]
	v_mfma_f32_16x16x32_bf16 v[20:23], v[170:173], v[202:205], v[20:23]
	v_mfma_f32_16x16x32_bf16 v[16:19], v[178:181], v[202:205], v[16:19]
	v_mfma_f32_16x16x32_bf16 v[4:7], v[170:173], v[214:217], v[4:7]
	v_mfma_f32_16x16x32_bf16 v[0:3], v[178:181], v[214:217], v[0:3]
	v_mfma_f32_16x16x32_bf16 v[52:55], v[174:177], v[190:193], v[52:55]
	v_mfma_f32_16x16x32_bf16 v[48:51], v[182:185], v[190:193], v[48:51]
	v_mfma_f32_16x16x32_bf16 v[36:39], v[174:177], v[198:201], v[36:39]
	v_mfma_f32_16x16x32_bf16 v[32:35], v[182:185], v[198:201], v[32:35]
	v_mfma_f32_16x16x32_bf16 v[20:23], v[174:177], v[210:213], v[20:23]
	v_mfma_f32_16x16x32_bf16 v[16:19], v[182:185], v[210:213], v[16:19]
	v_mfma_f32_16x16x32_bf16 v[4:7], v[174:177], v[218:221], v[4:7]
	s_barrier
	v_mfma_f32_16x16x32_bf16 v[0:3], v[182:185], v[218:221], v[0:3]
	s_setprio 0
	s_add_i32 s51, 0, 0x18000
	v_add_u32_e32 v153, s51, v151
	s_add_i32 s52, 0, 0x1c000
	ds_read_b128 v[154:157], v153
	ds_read_b128 v[158:161], v153 offset:1024
	ds_read_b128 v[162:165], v153 offset:2048
	ds_read_b128 v[166:169], v153 offset:3072
	v_add_u32_e32 v153, s52, v151
	ds_read_b128 v[170:173], v153
	ds_read_b128 v[174:177], v153 offset:1024
	ds_read_b128 v[178:181], v153 offset:2048
	ds_read_b128 v[182:185], v153 offset:3072
	s_add_u32 s22, s22, 0xb0000
	s_addc_u32 s23, s23, 0
	s_mov_b32 m0, s34
	v_lshl_add_u64 v[228:229], s[22:23], 0, v[128:129]
	ds_read_b128 v[186:189], v152 offset:32768
	ds_read_b128 v[190:193], v152 offset:33792
	ds_read_b128 v[194:197], v152 offset:34816
	ds_read_b128 v[198:201], v152 offset:35840
	ds_read_b128 v[202:205], v152 offset:36864
	ds_read_b128 v[210:213], v152 offset:37888
	ds_read_b128 v[214:217], v152 offset:38912
	ds_read_b128 v[218:221], v152 offset:39936
	global_load_lds_dwordx4 v[228:229], off
	v_lshl_add_u64 v[228:229], s[22:23], 0, v[132:133]
	s_mov_b32 m0, s35
	s_nop 0
	global_load_lds_dwordx4 v[228:229], off
	s_waitcnt vmcnt(8)
	s_waitcnt lgkmcnt(0)
	s_barrier
	s_setprio 1
	s_waitcnt lgkmcnt(0)
	v_mfma_f32_16x16x32_bf16 v[124:127], v[154:157], v[186:189], v[124:127]
	v_mfma_f32_16x16x32_bf16 v[120:123], v[162:165], v[186:189], v[120:123]
	v_mfma_f32_16x16x32_bf16 v[108:111], v[154:157], v[194:197], v[108:111]
	v_mfma_f32_16x16x32_bf16 v[104:107], v[162:165], v[194:197], v[104:107]
	v_mfma_f32_16x16x32_bf16 v[92:95], v[154:157], v[202:205], v[92:95]
	v_mfma_f32_16x16x32_bf16 v[88:91], v[162:165], v[202:205], v[88:91]
	v_mfma_f32_16x16x32_bf16 v[76:79], v[154:157], v[214:217], v[76:79]
	v_mfma_f32_16x16x32_bf16 v[72:75], v[162:165], v[214:217], v[72:75]
	v_mfma_f32_16x16x32_bf16 v[124:127], v[158:161], v[190:193], v[124:127]
	v_mfma_f32_16x16x32_bf16 v[120:123], v[166:169], v[190:193], v[120:123]
	v_mfma_f32_16x16x32_bf16 v[108:111], v[158:161], v[198:201], v[108:111]
	v_mfma_f32_16x16x32_bf16 v[104:107], v[166:169], v[198:201], v[104:107]
	v_mfma_f32_16x16x32_bf16 v[92:95], v[158:161], v[210:213], v[92:95]
	v_mfma_f32_16x16x32_bf16 v[88:91], v[166:169], v[210:213], v[88:91]
	v_mfma_f32_16x16x32_bf16 v[76:79], v[158:161], v[218:221], v[76:79]
	v_mfma_f32_16x16x32_bf16 v[72:75], v[166:169], v[218:221], v[72:75]
	s_setprio 0
	s_setprio 1
	v_mfma_f32_16x16x32_bf16 v[116:119], v[170:173], v[186:189], v[116:119]
	v_mfma_f32_16x16x32_bf16 v[112:115], v[178:181], v[186:189], v[112:115]
	v_mfma_f32_16x16x32_bf16 v[100:103], v[170:173], v[194:197], v[100:103]
	v_mfma_f32_16x16x32_bf16 v[96:99], v[178:181], v[194:197], v[96:99]
	v_mfma_f32_16x16x32_bf16 v[84:87], v[170:173], v[202:205], v[84:87]
	v_mfma_f32_16x16x32_bf16 v[80:83], v[178:181], v[202:205], v[80:83]
	v_mfma_f32_16x16x32_bf16 v[68:71], v[170:173], v[214:217], v[68:71]
	v_mfma_f32_16x16x32_bf16 v[64:67], v[178:181], v[214:217], v[64:67]
	v_mfma_f32_16x16x32_bf16 v[116:119], v[174:177], v[190:193], v[116:119]
	v_mfma_f32_16x16x32_bf16 v[112:115], v[182:185], v[190:193], v[112:115]
	v_mfma_f32_16x16x32_bf16 v[100:103], v[174:177], v[198:201], v[100:103]
	v_mfma_f32_16x16x32_bf16 v[96:99], v[182:185], v[198:201], v[96:99]
	v_mfma_f32_16x16x32_bf16 v[84:87], v[174:177], v[210:213], v[84:87]
	v_mfma_f32_16x16x32_bf16 v[80:83], v[182:185], v[210:213], v[80:83]
	v_mfma_f32_16x16x32_bf16 v[68:71], v[174:177], v[218:221], v[68:71]
	s_barrier
; #define PG8_STAGE(bufoff, gbase, voff) do { _Pragma("unroll") for (int _i = 0; _i < 2; ++_i) \
;         __builtin_amdgcn_global_load_lds((const unsigned*)((const char*)(gbase) + (voff)[_i]), (PG8_LAS unsigned*)(lds + (bufoff) + ldsw + _i * 8192), 16, 0, 0); } while (0)
; #define PG8_LDA(dst, b, h) do { _Pragma("unroll") for (int m = 0; m < 4; ++m) _Pragma("unroll") for (int k = 0; k < 2; ++k) dst[m][k] = *(const PG8_LAS bf16x8*)(lds + PG8_SA(b, h) + aoff + m * 2048 + k * 1024); } while (0)
; #define PG8_MMA(ai, bj, At, Bt) do { __builtin_amdgcn_s_setprio(1); _Pragma("unroll") for (int m = 0; m < 4; ++m) _Pragma("unroll") for (int n = 0; n < 2; ++n) _Pragma("unroll") for (int k = 0; k < 2; ++k) \
;         acc[ai][bj][m][n] = __builtin_amdgcn_mfma_f32_16x16x32_bf16(Bt[n][k], At[m][k], acc[ai][bj][m][n], 0, 0, 0); __builtin_amdgcn_s_setprio(0); } while (0)
; #define PG8_WAIT_V(n) asm volatile("s_waitcnt vmcnt(" #n ")" ::: "memory")
; #define PG8_WAIT_L(n) asm volatile("s_waitcnt lgkmcnt(" #n ")" ::: "memory")
; #define PG8_BAR __builtin_amdgcn_s_barrier()
; #define PG8_SCHED __builtin_amdgcn_sched_barrier(0)
; template <class Epi, class Sched, bool ALIGN_EPI = false, bool SP2 = false>
; __device__ __forceinline__ void gemm_phase(PG8_LAS unsigned char* lds, const Gemm g, const Sched& S, const Epi& E) {
;     ...
;             PG8_WAIT_V(8); PG8_WAIT_L(0); PG8_BAR; PG8_MMA(0, 0, At, B0); PG8_MMA(0, 1, At, B1); PG8_BAR; PG8_SCHED;
;             PG8_LDA(At, 1, 1); PG8_STAGE(PG8_SB(1, 0), b3, voffB); PG8_STAGE(PG8_SB(1, 1), b3 + hstep, voffB); PG8_STAGE(PG8_SA(1, 0), a3, voffA);
;             PG8_WAIT_V(8); PG8_WAIT_L(0); PG8_BAR; PG8_MMA(1, 0, At, B0); PG8_MMA(1, 1, At, B1); PG8_BAR; PG8_SCHED;
;     ...
; #pragma unroll
;         for (int a = 0; a < 2; ++a)
; #pragma unroll
;             for (int b = 0; b < 2; ++b)
; #pragma unroll
;                 for (int m = 0; m < 4; ++m)
; #pragma unroll
;                     for (int n = 0; n < 2; ++n) acc[a][b][m][n] = (f32x4){0.f, 0.f, 0.f, 0.f};
;         cur = nxt; cA = nA; cB = nB; ++ui;
	v_mfma_f32_16x16x32_bf16 v[64:67], v[182:185], v[218:221], v[64:67]
	s_setprio 0
	s_add_i32 s22, s51, s30
	v_lshl_add_u64 v[206:207], v[206:207], 0, s[14:15]
	s_mov_b32 m0, s22
	ds_read_b128 v[186:189], v152 offset:49152
	ds_read_b128 v[190:193], v152 offset:50176
	ds_read_b128 v[194:197], v152 offset:51200
	ds_read_b128 v[198:201], v152 offset:52224
	ds_read_b128 v[202:205], v152 offset:53248
	ds_read_b128 v[210:213], v152 offset:54272
	ds_read_b128 v[214:217], v152 offset:55296
	ds_read_b128 v[218:221], v152 offset:56320
	global_load_lds_dwordx4 v[206:207], off
	s_add_i32 m0, s22, 0x2000
	s_add_u32 s20, s20, 0xb0080
	v_lshl_add_u64 v[206:207], v[222:223], 0, s[14:15]
	s_addc_u32 s21, s21, 0
	s_add_i32 s22, s52, s30
	global_load_lds_dwordx4 v[206:207], off
	v_lshl_add_u64 v[206:207], s[20:21], 0, v[130:131]
	s_mov_b32 m0, s22
	s_nop 0
	global_load_lds_dwordx4 v[206:207], off
	v_lshl_add_u64 v[206:207], s[20:21], 0, v[134:135]
	s_add_i32 m0, s22, 0x2000
	s_nop 0
	global_load_lds_dwordx4 v[206:207], off
	v_lshl_add_u64 v[206:207], v[224:225], 0, s[14:15]
	s_mov_b32 m0, s37
	s_nop 0
	global_load_lds_dwordx4 v[206:207], off
	v_lshl_add_u64 v[206:207], v[226:227], 0, s[14:15]
	s_mov_b32 m0, s38
	s_nop 0
	global_load_lds_dwordx4 v[206:207], off
	s_waitcnt vmcnt(8)
	s_waitcnt lgkmcnt(0)
	s_barrier
	s_setprio 1
	s_waitcnt lgkmcnt(0)
	v_mfma_f32_16x16x32_bf16 v[60:63], v[154:157], v[186:189], v[60:63]
	v_mfma_f32_16x16x32_bf16 v[56:59], v[162:165], v[186:189], v[56:59]
	v_mfma_f32_16x16x32_bf16 v[44:47], v[154:157], v[194:197], v[44:47]
	v_mfma_f32_16x16x32_bf16 v[40:43], v[162:165], v[194:197], v[40:43]
	v_mfma_f32_16x16x32_bf16 v[28:31], v[154:157], v[202:205], v[28:31]
	v_mfma_f32_16x16x32_bf16 v[24:27], v[162:165], v[202:205], v[24:27]
	v_mfma_f32_16x16x32_bf16 v[12:15], v[154:157], v[214:217], v[12:15]
	v_mfma_f32_16x16x32_bf16 v[8:11], v[162:165], v[214:217], v[8:11]
	v_mfma_f32_16x16x32_bf16 v[60:63], v[158:161], v[190:193], v[60:63]
	v_mfma_f32_16x16x32_bf16 v[56:59], v[166:169], v[190:193], v[56:59]
	v_mfma_f32_16x16x32_bf16 v[44:47], v[158:161], v[198:201], v[44:47]
	v_mfma_f32_16x16x32_bf16 v[40:43], v[166:169], v[198:201], v[40:43]
	v_mfma_f32_16x16x32_bf16 v[28:31], v[158:161], v[210:213], v[28:31]
	v_mfma_f32_16x16x32_bf16 v[24:27], v[166:169], v[210:213], v[24:27]
	v_mfma_f32_16x16x32_bf16 v[12:15], v[158:161], v[218:221], v[12:15]
	v_mfma_f32_16x16x32_bf16 v[8:11], v[166:169], v[218:221], v[8:11]
	s_setprio 0
	s_setprio 1
	v_mfma_f32_16x16x32_bf16 v[52:55], v[170:173], v[186:189], v[52:55]
	v_mfma_f32_16x16x32_bf16 v[48:51], v[178:181], v[186:189], v[48:51]
	v_mfma_f32_16x16x32_bf16 v[36:39], v[170:173], v[194:197], v[36:39]
	v_mfma_f32_16x16x32_bf16 v[32:35], v[178:181], v[194:197], v[32:35]
	v_mfma_f32_16x16x32_bf16 v[20:23], v[170:173], v[202:205], v[20:23]
	v_mfma_f32_16x16x32_bf16 v[16:19], v[178:181], v[202:205], v[16:19]
	v_mfma_f32_16x16x32_bf16 v[4:7], v[170:173], v[214:217], v[4:7]
	v_mfma_f32_16x16x32_bf16 v[0:3], v[178:181], v[214:217], v[0:3]
	v_mfma_f32_16x16x32_bf16 v[52:55], v[174:177], v[190:193], v[52:55]
	v_mfma_f32_16x16x32_bf16 v[48:51], v[182:185], v[190:193], v[48:51]
	v_mfma_f32_16x16x32_bf16 v[36:39], v[174:177], v[198:201], v[36:39]
	v_mfma_f32_16x16x32_bf16 v[32:35], v[182:185], v[198:201], v[32:35]
	v_mfma_f32_16x16x32_bf16 v[20:23], v[174:177], v[210:213], v[20:23]
	v_mfma_f32_16x16x32_bf16 v[16:19], v[182:185], v[210:213], v[16:19]
	v_mfma_f32_16x16x32_bf16 v[4:7], v[174:177], v[218:221], v[4:7]
	s_barrier
	v_mfma_f32_16x16x32_bf16 v[0:3], v[182:185], v[218:221], v[0:3]
	s_setprio 0
	s_add_i32 s50, s50, 2
	s_add_u32 s18, s18, 0x100
	s_addc_u32 s19, s19, 0
	s_cmp_gt_u32 s50, 41
	s_cbranch_scc0 .LBB0_1430
	s_add_u32 s18, s46, 0xffffff00
	s_addc_u32 s19, s47, -1
	s_and_b64 vcc, exec, s[6:7]
	s_cbranch_vccnz .LBB0_1433
	v_mov_b32_e32 v0, 0
	s_mov_b32 s39, s43
	s_mov_b32 s25, s44
	s_mov_b64 s[12:13], s[16:17]
	s_mov_b32 s40, s45
	v_mov_b32_e32 v1, v0
	v_mov_b32_e32 v2, v0
	v_mov_b32_e32 v3, v0
	v_mov_b32_e32 v4, v0
	v_mov_b32_e32 v5, v0
	v_mov_b32_e32 v6, v0
	v_mov_b32_e32 v7, v0
	v_mov_b32_e32 v16, v0
	v_mov_b32_e32 v17, v0
	v_mov_b32_e32 v18, v0
	v_mov_b32_e32 v19, v0
	v_mov_b32_e32 v20, v0
	v_mov_b32_e32 v21, v0
	v_mov_b32_e32 v22, v0
	v_mov_b32_e32 v23, v0
	v_mov_b32_e32 v32, v0
	v_mov_b32_e32 v33, v0
	v_mov_b32_e32 v34, v0
	v_mov_b32_e32 v35, v0
	v_mov_b32_e32 v36, v0
	v_mov_b32_e32 v37, v0
	v_mov_b32_e32 v38, v0
	v_mov_b32_e32 v39, v0
	v_mov_b32_e32 v48, v0
	v_mov_b32_e32 v49, v0
	v_mov_b32_e32 v50, v0
	v_mov_b32_e32 v51, v0
	v_mov_b32_e32 v52, v0
	v_mov_b32_e32 v53, v0
	v_mov_b32_e32 v54, v0
	v_mov_b32_e32 v55, v0
	v_mov_b32_e32 v8, v0
	v_mov_b32_e32 v9, v0
	v_mov_b32_e32 v10, v0
	v_mov_b32_e32 v11, v0
	v_mov_b32_e32 v12, v0
	v_mov_b32_e32 v13, v0
	v_mov_b32_e32 v14, v0
	v_mov_b32_e32 v15, v0
	v_mov_b32_e32 v24, v0
	v_mov_b32_e32 v25, v0
	v_mov_b32_e32 v26, v0
	v_mov_b32_e32 v27, v0
	v_mov_b32_e32 v28, v0
	v_mov_b32_e32 v29, v0
	v_mov_b32_e32 v30, v0
	v_mov_b32_e32 v31, v0
	v_mov_b32_e32 v40, v0
	v_mov_b32_e32 v41, v0
	v_mov_b32_e32 v42, v0
	v_mov_b32_e32 v43, v0
	v_mov_b32_e32 v44, v0
	v_mov_b32_e32 v45, v0
	v_mov_b32_e32 v46, v0
	v_mov_b32_e32 v47, v0
	v_mov_b32_e32 v56, v0
	v_mov_b32_e32 v57, v0
	v_mov_b32_e32 v58, v0
	v_mov_b32_e32 v59, v0
	v_mov_b32_e32 v60, v0
	v_mov_b32_e32 v61, v0
	v_mov_b32_e32 v62, v0
	v_mov_b32_e32 v63, v0
	v_mov_b32_e32 v64, v0
	v_mov_b32_e32 v65, v0
	v_mov_b32_e32 v66, v0
	v_mov_b32_e32 v67, v0
	v_mov_b32_e32 v68, v0
	v_mov_b32_e32 v69, v0
	v_mov_b32_e32 v70, v0
	v_mov_b32_e32 v71, v0
	v_mov_b32_e32 v80, v0
	v_mov_b32_e32 v81, v0
	v_mov_b32_e32 v82, v0
	v_mov_b32_e32 v83, v0
	v_mov_b32_e32 v84, v0
	v_mov_b32_e32 v85, v0
	v_mov_b32_e32 v86, v0
	v_mov_b32_e32 v87, v0
	v_mov_b32_e32 v96, v0
	v_mov_b32_e32 v97, v0
	v_mov_b32_e32 v98, v0
	v_mov_b32_e32 v99, v0
	v_mov_b32_e32 v100, v0
	v_mov_b32_e32 v101, v0
	v_mov_b32_e32 v102, v0
	v_mov_b32_e32 v103, v0
	v_mov_b32_e32 v112, v0
	v_mov_b32_e32 v113, v0
	v_mov_b32_e32 v114, v0
	v_mov_b32_e32 v115, v0
	v_mov_b32_e32 v116, v0
	v_mov_b32_e32 v117, v0
	v_mov_b32_e32 v118, v0
	v_mov_b32_e32 v119, v0
	v_mov_b32_e32 v72, v0
	v_mov_b32_e32 v73, v0
	v_mov_b32_e32 v74, v0
	v_mov_b32_e32 v75, v0
	v_mov_b32_e32 v76, v0
	v_mov_b32_e32 v77, v0
	v_mov_b32_e32 v78, v0
	v_mov_b32_e32 v79, v0
	v_mov_b32_e32 v88, v0
	v_mov_b32_e32 v89, v0
	v_mov_b32_e32 v90, v0
	v_mov_b32_e32 v91, v0
	v_mov_b32_e32 v92, v0
	v_mov_b32_e32 v93, v0
	v_mov_b32_e32 v94, v0
	v_mov_b32_e32 v95, v0
	v_mov_b32_e32 v104, v0
	v_mov_b32_e32 v105, v0
	v_mov_b32_e32 v106, v0
	v_mov_b32_e32 v107, v0
	v_mov_b32_e32 v108, v0
	v_mov_b32_e32 v109, v0
	v_mov_b32_e32 v110, v0
	v_mov_b32_e32 v111, v0
	v_mov_b32_e32 v120, v0
	v_mov_b32_e32 v121, v0
	v_mov_b32_e32 v122, v0
	v_mov_b32_e32 v123, v0
	v_mov_b32_e32 v124, v0
	v_mov_b32_e32 v125, v0
	v_mov_b32_e32 v126, v0
	v_mov_b32_e32 v127, v0
	s_andn2_b64 vcc, exec, s[0:1]
	s_cbranch_vccnz .LBB0_1434
	s_branch .LBB0_1435
